# remove per-unit accumulator zeroing (128 v_mov per wave) in all looped GEMMs: first K-loop iteration peeled with srcC=0 MFMAs
# speedup vs baseline: 1.0118x; 1.0100x over previous
.LBB0_151:
	s_ashr_i32 s27, s26, 31
	s_lshl_b64 s[42:43], s[26:27], 19
	s_add_u32 s42, s3, s42
	s_addc_u32 s43, s23, s43
	s_and_b64 s[44:45], s[4:5], exec
	s_cselect_b32 s27, s43, s49
	s_cselect_b32 s69, s42, s48
	s_ashr_i32 s25, s24, 31
	s_lshl_b64 s[44:45], s[24:25], 19
	s_add_u32 s44, s29, s44
	s_addc_u32 s45, s31, s45
	s_and_b64 s[52:53], s[4:5], exec
	s_cselect_b32 s25, s45, s51
	s_cselect_b32 s70, s44, s50
	s_add_u32 s48, s48, 0x40080
	s_addc_u32 s49, s49, 0
	s_add_u32 s71, s50, 0x100
	s_addc_u32 s72, s51, 0
	s_mov_b32 s73, -2
	ds_read_b128 v[160:163], v155
	ds_read_b128 v[164:167], v155 offset:1024
	ds_read_b128 v[168:171], v155 offset:2048
	ds_read_b128 v[172:175], v155 offset:3072
	ds_read_b128 v[176:179], v156
	ds_read_b128 v[180:183], v156 offset:1024
	ds_read_b128 v[184:187], v156 offset:2048
	ds_read_b128 v[188:191], v156 offset:3072
	s_add_u32 s50, s48, 0xfffc0080
	s_addc_u32 s51, s49, -1
	s_cmp_eq_u32 s73, 12
	s_cselect_b32 s53, s27, s51
	s_cselect_b32 s52, s69, s50
	s_cselect_b32 s51, s25, s72
	s_cselect_b32 s50, s70, s71
	v_lshl_add_u64 v[148:149], s[48:49], 0, v[140:141]
	s_add_i32 m0, s57, 0xc000
	ds_read_b128 v[192:195], v157
	ds_read_b128 v[196:199], v157 offset:1024
	ds_read_b128 v[200:203], v157 offset:2048
	ds_read_b128 v[204:207], v157 offset:3072
	ds_read_b128 v[208:211], v157 offset:4096
	ds_read_b128 v[212:215], v157 offset:5120
	ds_read_b128 v[216:219], v157 offset:6144
	ds_read_b128 v[220:223], v157 offset:7168
	global_load_lds_dwordx4 v[148:149], off
	v_lshl_add_u64 v[148:149], s[48:49], 0, v[142:143]
	s_add_i32 m0, s57, 0xe000
	s_nop 0
	global_load_lds_dwordx4 v[148:149], off
	s_waitcnt vmcnt(8)
	s_waitcnt lgkmcnt(0)
	s_setprio 1
	s_barrier
	v_mfma_f32_16x16x32_bf16 v[118:121], v[160:163], v[192:195], 0
	v_mfma_f32_16x16x32_bf16 v[114:117], v[168:171], v[192:195], 0
	v_mfma_f32_16x16x32_bf16 v[106:109], v[160:163], v[200:203], 0
	v_mfma_f32_16x16x32_bf16 v[98:101], v[168:171], v[200:203], 0
	v_mfma_f32_16x16x32_bf16 v[90:93], v[160:163], v[208:211], 0
	v_mfma_f32_16x16x32_bf16 v[82:85], v[168:171], v[208:211], 0
	v_mfma_f32_16x16x32_bf16 v[74:77], v[160:163], v[216:219], 0
	v_mfma_f32_16x16x32_bf16 v[66:69], v[168:171], v[216:219], 0
	v_mfma_f32_16x16x32_bf16 v[118:121], v[164:167], v[196:199], v[118:121]
	v_mfma_f32_16x16x32_bf16 v[114:117], v[172:175], v[196:199], v[114:117]
	v_mfma_f32_16x16x32_bf16 v[106:109], v[164:167], v[204:207], v[106:109]
	v_mfma_f32_16x16x32_bf16 v[98:101], v[172:175], v[204:207], v[98:101]
	v_mfma_f32_16x16x32_bf16 v[90:93], v[164:167], v[212:215], v[90:93]
	v_mfma_f32_16x16x32_bf16 v[82:85], v[172:175], v[212:215], v[82:85]
	v_mfma_f32_16x16x32_bf16 v[74:77], v[164:167], v[220:223], v[74:77]
	v_mfma_f32_16x16x32_bf16 v[66:69], v[172:175], v[220:223], v[66:69]
	s_setprio 0
	s_setprio 1
	v_mfma_f32_16x16x32_bf16 v[126:129], v[176:179], v[192:195], 0
	v_mfma_f32_16x16x32_bf16 v[122:125], v[184:187], v[192:195], 0
	v_mfma_f32_16x16x32_bf16 v[110:113], v[176:179], v[200:203], 0
	v_mfma_f32_16x16x32_bf16 v[102:105], v[184:187], v[200:203], 0
	v_mfma_f32_16x16x32_bf16 v[94:97], v[176:179], v[208:211], 0
	v_mfma_f32_16x16x32_bf16 v[86:89], v[184:187], v[208:211], 0
	v_mfma_f32_16x16x32_bf16 v[78:81], v[176:179], v[216:219], 0
	v_mfma_f32_16x16x32_bf16 v[70:73], v[184:187], v[216:219], 0
	v_mfma_f32_16x16x32_bf16 v[126:129], v[180:183], v[196:199], v[126:129]
	v_mfma_f32_16x16x32_bf16 v[122:125], v[188:191], v[196:199], v[122:125]
	v_mfma_f32_16x16x32_bf16 v[110:113], v[180:183], v[204:207], v[110:113]
	v_mfma_f32_16x16x32_bf16 v[102:105], v[188:191], v[204:207], v[102:105]
	v_mfma_f32_16x16x32_bf16 v[94:97], v[180:183], v[212:215], v[94:97]
	v_mfma_f32_16x16x32_bf16 v[86:89], v[188:191], v[212:215], v[86:89]
	v_mfma_f32_16x16x32_bf16 v[78:81], v[180:183], v[220:223], v[78:81]
	v_mfma_f32_16x16x32_bf16 v[70:73], v[188:191], v[220:223], v[70:73]
	s_setprio 0
	s_barrier
	s_add_i32 s74, s66, s54
	v_lshl_add_u64 v[148:149], s[50:51], 0, v[134:135]
	s_mov_b32 m0, s74
	ds_read_b128 v[192:195], v157 offset:16384
	ds_read_b128 v[196:199], v157 offset:17408
	ds_read_b128 v[200:203], v157 offset:18432
	ds_read_b128 v[204:207], v157 offset:19456
	ds_read_b128 v[208:211], v157 offset:20480
	ds_read_b128 v[212:215], v157 offset:21504
	ds_read_b128 v[216:219], v157 offset:22528
	ds_read_b128 v[220:223], v157 offset:23552
	global_load_lds_dwordx4 v[148:149], off
	s_add_i32 m0, s74, 0x2000
	s_add_u32 s74, s50, 0x40000
	v_lshl_add_u64 v[224:225], s[50:51], 0, v[130:131]
	s_addc_u32 s75, s51, 0
	s_add_i32 s76, s67, s54
	global_load_lds_dwordx4 v[224:225], off
	v_lshl_add_u64 v[226:227], s[74:75], 0, v[134:135]
	s_mov_b32 m0, s76
	v_lshl_add_u64 v[228:229], s[52:53], 0, v[132:133]
	global_load_lds_dwordx4 v[226:227], off
	v_lshl_add_u64 v[226:227], s[74:75], 0, v[130:131]
	s_add_i32 m0, s76, 0x2000
	s_nop 0
	global_load_lds_dwordx4 v[226:227], off
	v_lshl_add_u64 v[226:227], s[52:53], 0, v[136:137]
	s_mov_b32 m0, s57
	s_nop 0
	global_load_lds_dwordx4 v[226:227], off
	s_mov_b32 m0, s58
	s_nop 0
	global_load_lds_dwordx4 v[228:229], off
	s_waitcnt vmcnt(8)
	s_waitcnt lgkmcnt(0)
	s_setprio 1
	s_barrier
	v_mfma_f32_16x16x32_bf16 v[58:61], v[160:163], v[192:195], 0
	v_mfma_f32_16x16x32_bf16 v[50:53], v[168:171], v[192:195], 0
	v_mfma_f32_16x16x32_bf16 v[42:45], v[160:163], v[200:203], 0
	v_mfma_f32_16x16x32_bf16 v[34:37], v[168:171], v[200:203], 0
	v_mfma_f32_16x16x32_bf16 v[26:29], v[160:163], v[208:211], 0
	v_mfma_f32_16x16x32_bf16 v[18:21], v[168:171], v[208:211], 0
	v_mfma_f32_16x16x32_bf16 v[10:13], v[160:163], v[216:219], 0
	v_mfma_f32_16x16x32_bf16 v[6:9], v[168:171], v[216:219], 0
	v_mfma_f32_16x16x32_bf16 v[58:61], v[164:167], v[196:199], v[58:61]
	v_mfma_f32_16x16x32_bf16 v[50:53], v[172:175], v[196:199], v[50:53]
	v_mfma_f32_16x16x32_bf16 v[42:45], v[164:167], v[204:207], v[42:45]
	v_mfma_f32_16x16x32_bf16 v[34:37], v[172:175], v[204:207], v[34:37]
	v_mfma_f32_16x16x32_bf16 v[26:29], v[164:167], v[212:215], v[26:29]
	v_mfma_f32_16x16x32_bf16 v[18:21], v[172:175], v[212:215], v[18:21]
	v_mfma_f32_16x16x32_bf16 v[10:13], v[164:167], v[220:223], v[10:13]
	v_mfma_f32_16x16x32_bf16 v[6:9], v[172:175], v[220:223], v[6:9]
	s_setprio 0
	s_setprio 1
	v_mfma_f32_16x16x32_bf16 v[62:65], v[176:179], v[192:195], 0
	v_mfma_f32_16x16x32_bf16 v[54:57], v[184:187], v[192:195], 0
	v_mfma_f32_16x16x32_bf16 v[46:49], v[176:179], v[200:203], 0
	v_mfma_f32_16x16x32_bf16 v[38:41], v[184:187], v[200:203], 0
	v_mfma_f32_16x16x32_bf16 v[30:33], v[176:179], v[208:211], 0
	v_mfma_f32_16x16x32_bf16 v[22:25], v[184:187], v[208:211], 0
	v_mfma_f32_16x16x32_bf16 v[14:17], v[176:179], v[216:219], 0
	v_mfma_f32_16x16x32_bf16 v[2:5], v[184:187], v[216:219], 0
	v_mfma_f32_16x16x32_bf16 v[62:65], v[180:183], v[196:199], v[62:65]
	v_mfma_f32_16x16x32_bf16 v[54:57], v[188:191], v[196:199], v[54:57]
	v_mfma_f32_16x16x32_bf16 v[46:49], v[180:183], v[204:207], v[46:49]
	v_mfma_f32_16x16x32_bf16 v[38:41], v[188:191], v[204:207], v[38:41]
	v_mfma_f32_16x16x32_bf16 v[30:33], v[180:183], v[212:215], v[30:33]
	v_mfma_f32_16x16x32_bf16 v[22:25], v[188:191], v[212:215], v[22:25]
	v_mfma_f32_16x16x32_bf16 v[14:17], v[180:183], v[220:223], v[14:17]
	v_mfma_f32_16x16x32_bf16 v[2:5], v[188:191], v[220:223], v[2:5]
	s_setprio 0
	s_barrier
	s_add_i32 s74, 0, 0x18000
	v_add_u32_e32 v159, s74, v151
	s_add_i32 s75, 0, 0x1c000
	ds_read_b128 v[160:163], v159
	ds_read_b128 v[164:167], v159 offset:1024
	ds_read_b128 v[168:171], v159 offset:2048
	ds_read_b128 v[172:175], v159 offset:3072
	v_add_u32_e32 v159, s75, v151
	ds_read_b128 v[176:179], v159
	ds_read_b128 v[180:183], v159 offset:1024
	ds_read_b128 v[184:187], v159 offset:2048
	ds_read_b128 v[188:191], v159 offset:3072
	s_add_u32 s52, s52, 0x40000
	s_addc_u32 s53, s53, 0
	s_mov_b32 m0, s59
	v_lshl_add_u64 v[230:231], s[52:53], 0, v[136:137]
	ds_read_b128 v[192:195], v157 offset:32768
	ds_read_b128 v[196:199], v157 offset:33792
	ds_read_b128 v[200:203], v157 offset:34816
	ds_read_b128 v[204:207], v157 offset:35840
	ds_read_b128 v[208:211], v157 offset:36864
	ds_read_b128 v[212:215], v157 offset:37888
	ds_read_b128 v[216:219], v157 offset:38912
	ds_read_b128 v[220:223], v157 offset:39936
	global_load_lds_dwordx4 v[230:231], off
	v_lshl_add_u64 v[230:231], s[52:53], 0, v[132:133]
	s_mov_b32 m0, s60
	s_nop 0
	global_load_lds_dwordx4 v[230:231], off
	s_waitcnt vmcnt(8)
	s_waitcnt lgkmcnt(0)
	s_setprio 1
	s_barrier
	v_mfma_f32_16x16x32_bf16 v[118:121], v[160:163], v[192:195], v[118:121]
	v_mfma_f32_16x16x32_bf16 v[114:117], v[168:171], v[192:195], v[114:117]
	v_mfma_f32_16x16x32_bf16 v[106:109], v[160:163], v[200:203], v[106:109]
	v_mfma_f32_16x16x32_bf16 v[98:101], v[168:171], v[200:203], v[98:101]
	v_mfma_f32_16x16x32_bf16 v[90:93], v[160:163], v[208:211], v[90:93]
	v_mfma_f32_16x16x32_bf16 v[82:85], v[168:171], v[208:211], v[82:85]
	v_mfma_f32_16x16x32_bf16 v[74:77], v[160:163], v[216:219], v[74:77]
	v_mfma_f32_16x16x32_bf16 v[66:69], v[168:171], v[216:219], v[66:69]
	v_mfma_f32_16x16x32_bf16 v[118:121], v[164:167], v[196:199], v[118:121]
	v_mfma_f32_16x16x32_bf16 v[114:117], v[172:175], v[196:199], v[114:117]
	v_mfma_f32_16x16x32_bf16 v[106:109], v[164:167], v[204:207], v[106:109]
	v_mfma_f32_16x16x32_bf16 v[98:101], v[172:175], v[204:207], v[98:101]
	v_mfma_f32_16x16x32_bf16 v[90:93], v[164:167], v[212:215], v[90:93]
	v_mfma_f32_16x16x32_bf16 v[82:85], v[172:175], v[212:215], v[82:85]
	v_mfma_f32_16x16x32_bf16 v[74:77], v[164:167], v[220:223], v[74:77]
	v_mfma_f32_16x16x32_bf16 v[66:69], v[172:175], v[220:223], v[66:69]
	s_setprio 0
	s_setprio 1
	v_mfma_f32_16x16x32_bf16 v[126:129], v[176:179], v[192:195], v[126:129]
	v_mfma_f32_16x16x32_bf16 v[122:125], v[184:187], v[192:195], v[122:125]
	v_mfma_f32_16x16x32_bf16 v[110:113], v[176:179], v[200:203], v[110:113]
	v_mfma_f32_16x16x32_bf16 v[102:105], v[184:187], v[200:203], v[102:105]
	v_mfma_f32_16x16x32_bf16 v[94:97], v[176:179], v[208:211], v[94:97]
	v_mfma_f32_16x16x32_bf16 v[86:89], v[184:187], v[208:211], v[86:89]
	v_mfma_f32_16x16x32_bf16 v[78:81], v[176:179], v[216:219], v[78:81]
	v_mfma_f32_16x16x32_bf16 v[70:73], v[184:187], v[216:219], v[70:73]
	v_mfma_f32_16x16x32_bf16 v[126:129], v[180:183], v[196:199], v[126:129]
	v_mfma_f32_16x16x32_bf16 v[122:125], v[188:191], v[196:199], v[122:125]
	v_mfma_f32_16x16x32_bf16 v[110:113], v[180:183], v[204:207], v[110:113]
	v_mfma_f32_16x16x32_bf16 v[102:105], v[188:191], v[204:207], v[102:105]
	v_mfma_f32_16x16x32_bf16 v[94:97], v[180:183], v[212:215], v[94:97]
	v_mfma_f32_16x16x32_bf16 v[86:89], v[188:191], v[212:215], v[86:89]
	v_mfma_f32_16x16x32_bf16 v[78:81], v[180:183], v[220:223], v[78:81]
	v_mfma_f32_16x16x32_bf16 v[70:73], v[188:191], v[220:223], v[70:73]
	s_setprio 0
	s_barrier
	s_add_i32 s52, s74, s54
	v_lshl_add_u64 v[148:149], v[148:149], 0, s[14:15]
	s_mov_b32 m0, s52
	ds_read_b128 v[192:195], v157 offset:49152
	ds_read_b128 v[196:199], v157 offset:50176
	ds_read_b128 v[200:203], v157 offset:51200
	ds_read_b128 v[204:207], v157 offset:52224
	ds_read_b128 v[208:211], v157 offset:53248
	ds_read_b128 v[212:215], v157 offset:54272
	ds_read_b128 v[216:219], v157 offset:55296
	ds_read_b128 v[220:223], v157 offset:56320
	global_load_lds_dwordx4 v[148:149], off
	s_add_i32 m0, s52, 0x2000
	s_add_u32 s50, s50, 0x40080
	v_lshl_add_u64 v[148:149], v[224:225], 0, s[14:15]
	s_addc_u32 s51, s51, 0
	s_add_i32 s52, s75, s54
	global_load_lds_dwordx4 v[148:149], off
	v_lshl_add_u64 v[148:149], s[50:51], 0, v[134:135]
	s_mov_b32 m0, s52
	s_nop 0
	global_load_lds_dwordx4 v[148:149], off
	v_lshl_add_u64 v[148:149], s[50:51], 0, v[130:131]
	s_add_i32 m0, s52, 0x2000
	s_nop 0
	global_load_lds_dwordx4 v[148:149], off
	v_lshl_add_u64 v[148:149], v[226:227], 0, s[14:15]
	s_mov_b32 m0, s62
	s_nop 0
	global_load_lds_dwordx4 v[148:149], off
	v_lshl_add_u64 v[148:149], v[228:229], 0, s[14:15]
	s_mov_b32 m0, s63
	s_nop 0
	global_load_lds_dwordx4 v[148:149], off
	s_waitcnt vmcnt(8)
	s_waitcnt lgkmcnt(0)
	s_setprio 1
	s_barrier
	v_mfma_f32_16x16x32_bf16 v[58:61], v[160:163], v[192:195], v[58:61]
	v_mfma_f32_16x16x32_bf16 v[50:53], v[168:171], v[192:195], v[50:53]
	v_mfma_f32_16x16x32_bf16 v[42:45], v[160:163], v[200:203], v[42:45]
	v_mfma_f32_16x16x32_bf16 v[34:37], v[168:171], v[200:203], v[34:37]
	v_mfma_f32_16x16x32_bf16 v[26:29], v[160:163], v[208:211], v[26:29]
	v_mfma_f32_16x16x32_bf16 v[18:21], v[168:171], v[208:211], v[18:21]
	v_mfma_f32_16x16x32_bf16 v[10:13], v[160:163], v[216:219], v[10:13]
	v_mfma_f32_16x16x32_bf16 v[6:9], v[168:171], v[216:219], v[6:9]
	v_mfma_f32_16x16x32_bf16 v[58:61], v[164:167], v[196:199], v[58:61]
	v_mfma_f32_16x16x32_bf16 v[50:53], v[172:175], v[196:199], v[50:53]
	v_mfma_f32_16x16x32_bf16 v[42:45], v[164:167], v[204:207], v[42:45]
	v_mfma_f32_16x16x32_bf16 v[34:37], v[172:175], v[204:207], v[34:37]
	v_mfma_f32_16x16x32_bf16 v[26:29], v[164:167], v[212:215], v[26:29]
	v_mfma_f32_16x16x32_bf16 v[18:21], v[172:175], v[212:215], v[18:21]
	v_mfma_f32_16x16x32_bf16 v[10:13], v[164:167], v[220:223], v[10:13]
	v_mfma_f32_16x16x32_bf16 v[6:9], v[172:175], v[220:223], v[6:9]
	s_setprio 0
	s_setprio 1
	v_mfma_f32_16x16x32_bf16 v[62:65], v[176:179], v[192:195], v[62:65]
	v_mfma_f32_16x16x32_bf16 v[54:57], v[184:187], v[192:195], v[54:57]
	v_mfma_f32_16x16x32_bf16 v[46:49], v[176:179], v[200:203], v[46:49]
	v_mfma_f32_16x16x32_bf16 v[38:41], v[184:187], v[200:203], v[38:41]
	v_mfma_f32_16x16x32_bf16 v[30:33], v[176:179], v[208:211], v[30:33]
	v_mfma_f32_16x16x32_bf16 v[22:25], v[184:187], v[208:211], v[22:25]
	v_mfma_f32_16x16x32_bf16 v[14:17], v[176:179], v[216:219], v[14:17]
	v_mfma_f32_16x16x32_bf16 v[2:5], v[184:187], v[216:219], v[2:5]
	v_mfma_f32_16x16x32_bf16 v[62:65], v[180:183], v[196:199], v[62:65]
	v_mfma_f32_16x16x32_bf16 v[54:57], v[188:191], v[196:199], v[54:57]
	v_mfma_f32_16x16x32_bf16 v[46:49], v[180:183], v[204:207], v[46:49]
	v_mfma_f32_16x16x32_bf16 v[38:41], v[188:191], v[204:207], v[38:41]
	v_mfma_f32_16x16x32_bf16 v[30:33], v[180:183], v[212:215], v[30:33]
	v_mfma_f32_16x16x32_bf16 v[22:25], v[188:191], v[212:215], v[22:25]
	v_mfma_f32_16x16x32_bf16 v[14:17], v[180:183], v[220:223], v[14:17]
	v_mfma_f32_16x16x32_bf16 v[2:5], v[188:191], v[220:223], v[2:5]
	s_setprio 0
	s_barrier
	s_add_i32 s73, s73, 2
	s_add_u32 s48, s48, 0x100
	s_addc_u32 s49, s49, 0
	s_add_u32 s71, s71, 0x100
	s_addc_u32 s72, s72, 0
	s_cmp_gt_u32 s73, 13
	s_cbranch_scc0 .LBB0_152
	s_branch .Lz_post_p1

.Lz_post_p1:
	s_lshl_b32 s25, s46, 8
	v_add_u32_e32 v148, s25, v150
	v_ashrrev_i32_e32 v149, 31, v148
	v_lshl_add_u64 v[160:161], v[148:149], 2, s[8:9]
	global_load_dword v149, v[160:161], off
	global_load_dword v232, v[160:161], off offset:64
	global_load_dword v233, v[160:161], off offset:128
	global_load_dword v234, v[160:161], off offset:192
	global_load_dword v235, v[160:161], off offset:512
	global_load_dword v236, v[160:161], off offset:576
	global_load_dword v237, v[160:161], off offset:640
	global_load_dword v238, v[160:161], off offset:704
	s_and_b64 vcc, exec, s[16:17]
	s_cbranch_vccz .LBB0_155
	s_barrier

.LBB0_250:
	s_add_u32 s69, s46, 0x100
	s_addc_u32 s70, s47, 0
	s_mov_b32 s71, -2
	ds_read_b128 v[122:125], v245
	ds_read_b128 v[126:129], v245 offset:1024
	ds_read_b128 v[130:133], v245 offset:2048
	ds_read_b128 v[134:137], v245 offset:3072
	ds_read_b128 v[138:141], v246
	ds_read_b128 v[142:145], v246 offset:1024
	ds_read_b128 v[146:149], v246 offset:2048
	ds_read_b128 v[158:161], v246 offset:3072
	s_add_u32 s46, s44, 0x100
	s_addc_u32 s47, s45, 0
	s_cmp_eq_u32 s71, 40
	s_cselect_b32 s51, s9, s47
	s_cselect_b32 s50, s8, s46
	s_cselect_b32 s49, s43, s70
	s_cselect_b32 s48, s42, s69
	v_lshl_add_u64 v[210:211], s[44:45], 0, v[206:207]
	s_add_i32 m0, s53, 0xc000
	ds_read_b128 v[162:165], v247
	ds_read_b128 v[166:169], v247 offset:1024
	ds_read_b128 v[170:173], v247 offset:2048
	ds_read_b128 v[174:177], v247 offset:3072
	ds_read_b128 v[178:181], v247 offset:4096
	ds_read_b128 v[182:185], v247 offset:5120
	ds_read_b128 v[186:189], v247 offset:6144
	ds_read_b128 v[190:193], v247 offset:7168
	global_load_lds_dwordx4 v[210:211], off
	v_lshl_add_u64 v[210:211], s[44:45], 0, v[208:209]
	s_add_i32 m0, s53, 0xe000
	s_nop 0
	global_load_lds_dwordx4 v[210:211], off
	s_waitcnt vmcnt(8)
	s_waitcnt lgkmcnt(0)
	s_setprio 1
	s_barrier
	v_mfma_f32_16x16x32_bf16 v[154:157], v[122:125], v[162:165], 0
	v_mfma_f32_16x16x32_bf16 v[150:153], v[130:133], v[162:165], 0
	v_mfma_f32_16x16x32_bf16 v[110:113], v[122:125], v[170:173], 0
	v_mfma_f32_16x16x32_bf16 v[106:109], v[130:133], v[170:173], 0
	v_mfma_f32_16x16x32_bf16 v[94:97], v[122:125], v[178:181], 0
	v_mfma_f32_16x16x32_bf16 v[90:93], v[130:133], v[178:181], 0
	v_mfma_f32_16x16x32_bf16 v[78:81], v[122:125], v[186:189], 0
	v_mfma_f32_16x16x32_bf16 v[74:77], v[130:133], v[186:189], 0
	v_mfma_f32_16x16x32_bf16 v[154:157], v[126:129], v[166:169], v[154:157]
	v_mfma_f32_16x16x32_bf16 v[150:153], v[134:137], v[166:169], v[150:153]
	v_mfma_f32_16x16x32_bf16 v[110:113], v[126:129], v[174:177], v[110:113]
	v_mfma_f32_16x16x32_bf16 v[106:109], v[134:137], v[174:177], v[106:109]
	v_mfma_f32_16x16x32_bf16 v[94:97], v[126:129], v[182:185], v[94:97]
	v_mfma_f32_16x16x32_bf16 v[90:93], v[134:137], v[182:185], v[90:93]
	v_mfma_f32_16x16x32_bf16 v[78:81], v[126:129], v[190:193], v[78:81]
	v_mfma_f32_16x16x32_bf16 v[74:77], v[134:137], v[190:193], v[74:77]
	s_setprio 0
	s_setprio 1
	v_mfma_f32_16x16x32_bf16 v[118:121], v[138:141], v[162:165], 0
	v_mfma_f32_16x16x32_bf16 v[114:117], v[146:149], v[162:165], 0
	v_mfma_f32_16x16x32_bf16 v[102:105], v[138:141], v[170:173], 0
	v_mfma_f32_16x16x32_bf16 v[98:101], v[146:149], v[170:173], 0
	v_mfma_f32_16x16x32_bf16 v[86:89], v[138:141], v[178:181], 0
	v_mfma_f32_16x16x32_bf16 v[82:85], v[146:149], v[178:181], 0
	v_mfma_f32_16x16x32_bf16 v[70:73], v[138:141], v[186:189], 0
	v_mfma_f32_16x16x32_bf16 v[66:69], v[146:149], v[186:189], 0
	v_mfma_f32_16x16x32_bf16 v[118:121], v[142:145], v[166:169], v[118:121]
	v_mfma_f32_16x16x32_bf16 v[114:117], v[158:161], v[166:169], v[114:117]
	v_mfma_f32_16x16x32_bf16 v[102:105], v[142:145], v[174:177], v[102:105]
	v_mfma_f32_16x16x32_bf16 v[98:101], v[158:161], v[174:177], v[98:101]
	v_mfma_f32_16x16x32_bf16 v[86:89], v[142:145], v[182:185], v[86:89]
	v_mfma_f32_16x16x32_bf16 v[82:85], v[158:161], v[182:185], v[82:85]
	v_mfma_f32_16x16x32_bf16 v[70:73], v[142:145], v[190:193], v[70:73]
	v_mfma_f32_16x16x32_bf16 v[66:69], v[158:161], v[190:193], v[66:69]
	s_setprio 0
	s_barrier
	s_add_i32 s44, s63, s52
	v_lshl_add_u64 v[210:211], s[48:49], 0, v[196:197]
	s_mov_b32 m0, s44
	ds_read_b128 v[162:165], v247 offset:16384
	ds_read_b128 v[166:169], v247 offset:17408
	ds_read_b128 v[170:173], v247 offset:18432
	ds_read_b128 v[174:177], v247 offset:19456
	ds_read_b128 v[178:181], v247 offset:20480
	ds_read_b128 v[182:185], v247 offset:21504
	ds_read_b128 v[186:189], v247 offset:22528
	ds_read_b128 v[190:193], v247 offset:23552
	global_load_lds_dwordx4 v[210:211], off
	s_add_i32 m0, s44, 0x2000
	s_add_u32 s44, s48, 0xb0000
	v_lshl_add_u64 v[212:213], s[48:49], 0, v[200:201]
	s_addc_u32 s45, s49, 0
	s_add_i32 s72, s64, s52
	global_load_lds_dwordx4 v[212:213], off
	v_lshl_add_u64 v[214:215], s[44:45], 0, v[196:197]
	s_mov_b32 m0, s72
	v_lshl_add_u64 v[216:217], s[50:51], 0, v[198:199]
	global_load_lds_dwordx4 v[214:215], off
	v_lshl_add_u64 v[214:215], s[44:45], 0, v[200:201]
	s_add_i32 m0, s72, 0x2000
	s_nop 0
	global_load_lds_dwordx4 v[214:215], off
	v_lshl_add_u64 v[214:215], s[50:51], 0, v[194:195]
	s_mov_b32 m0, s53
	s_nop 0
	global_load_lds_dwordx4 v[214:215], off
	s_mov_b32 m0, s54
	s_nop 0
	global_load_lds_dwordx4 v[216:217], off
	s_waitcnt vmcnt(8)
	s_waitcnt lgkmcnt(0)
	s_setprio 1
	s_barrier
	v_mfma_f32_16x16x32_bf16 v[62:65], v[122:125], v[162:165], 0
	v_mfma_f32_16x16x32_bf16 v[58:61], v[130:133], v[162:165], 0
	v_mfma_f32_16x16x32_bf16 v[46:49], v[122:125], v[170:173], 0
	v_mfma_f32_16x16x32_bf16 v[42:45], v[130:133], v[170:173], 0
	v_mfma_f32_16x16x32_bf16 v[30:33], v[122:125], v[178:181], 0
	v_mfma_f32_16x16x32_bf16 v[26:29], v[130:133], v[178:181], 0
	v_mfma_f32_16x16x32_bf16 v[14:17], v[122:125], v[186:189], 0
	v_mfma_f32_16x16x32_bf16 v[10:13], v[130:133], v[186:189], 0
	v_mfma_f32_16x16x32_bf16 v[62:65], v[126:129], v[166:169], v[62:65]
	v_mfma_f32_16x16x32_bf16 v[58:61], v[134:137], v[166:169], v[58:61]
	v_mfma_f32_16x16x32_bf16 v[46:49], v[126:129], v[174:177], v[46:49]
	v_mfma_f32_16x16x32_bf16 v[42:45], v[134:137], v[174:177], v[42:45]
	v_mfma_f32_16x16x32_bf16 v[30:33], v[126:129], v[182:185], v[30:33]
	v_mfma_f32_16x16x32_bf16 v[26:29], v[134:137], v[182:185], v[26:29]
	v_mfma_f32_16x16x32_bf16 v[14:17], v[126:129], v[190:193], v[14:17]
	v_mfma_f32_16x16x32_bf16 v[10:13], v[134:137], v[190:193], v[10:13]
	s_setprio 0
	s_setprio 1
	v_mfma_f32_16x16x32_bf16 v[54:57], v[138:141], v[162:165], 0
	v_mfma_f32_16x16x32_bf16 v[50:53], v[146:149], v[162:165], 0
	v_mfma_f32_16x16x32_bf16 v[38:41], v[138:141], v[170:173], 0
	v_mfma_f32_16x16x32_bf16 v[34:37], v[146:149], v[170:173], 0
	v_mfma_f32_16x16x32_bf16 v[22:25], v[138:141], v[178:181], 0
	v_mfma_f32_16x16x32_bf16 v[18:21], v[146:149], v[178:181], 0
	v_mfma_f32_16x16x32_bf16 v[6:9], v[138:141], v[186:189], 0
	v_mfma_f32_16x16x32_bf16 v[2:5], v[146:149], v[186:189], 0
	v_mfma_f32_16x16x32_bf16 v[54:57], v[142:145], v[166:169], v[54:57]
	v_mfma_f32_16x16x32_bf16 v[50:53], v[158:161], v[166:169], v[50:53]
	v_mfma_f32_16x16x32_bf16 v[38:41], v[142:145], v[174:177], v[38:41]
	v_mfma_f32_16x16x32_bf16 v[34:37], v[158:161], v[174:177], v[34:37]
	v_mfma_f32_16x16x32_bf16 v[22:25], v[142:145], v[182:185], v[22:25]
	v_mfma_f32_16x16x32_bf16 v[18:21], v[158:161], v[182:185], v[18:21]
	v_mfma_f32_16x16x32_bf16 v[6:9], v[142:145], v[190:193], v[6:9]
	v_mfma_f32_16x16x32_bf16 v[2:5], v[158:161], v[190:193], v[2:5]
	s_setprio 0
	s_barrier
	s_add_i32 s72, 0, 0x18000
	s_add_i32 s73, 0, 0x1c000
	v_add_u32_e32 v134, s72, v244
	v_add_u32_e32 v158, s73, v244
	ds_read_b128 v[122:125], v134
	ds_read_b128 v[126:129], v134 offset:1024
	ds_read_b128 v[130:133], v134 offset:2048
	ds_read_b128 v[134:137], v134 offset:3072
	ds_read_b128 v[138:141], v158
	ds_read_b128 v[142:145], v158 offset:1024
	ds_read_b128 v[146:149], v158 offset:2048
	ds_read_b128 v[158:161], v158 offset:3072
	s_add_u32 s44, s50, 0xb0000
	s_addc_u32 s45, s51, 0
	s_mov_b32 m0, s55
	v_lshl_add_u64 v[218:219], s[44:45], 0, v[194:195]
	ds_read_b128 v[162:165], v247 offset:32768
	ds_read_b128 v[166:169], v247 offset:33792
	ds_read_b128 v[170:173], v247 offset:34816
	ds_read_b128 v[174:177], v247 offset:35840
	ds_read_b128 v[178:181], v247 offset:36864
	ds_read_b128 v[182:185], v247 offset:37888
	ds_read_b128 v[186:189], v247 offset:38912
	ds_read_b128 v[190:193], v247 offset:39936
	global_load_lds_dwordx4 v[218:219], off
	v_lshl_add_u64 v[218:219], s[44:45], 0, v[198:199]
	s_mov_b32 m0, s56
	s_nop 0
	global_load_lds_dwordx4 v[218:219], off
	s_waitcnt vmcnt(8)
	s_waitcnt lgkmcnt(0)
	s_setprio 1
	s_barrier
	v_mfma_f32_16x16x32_bf16 v[154:157], v[122:125], v[162:165], v[154:157]
	v_mfma_f32_16x16x32_bf16 v[150:153], v[130:133], v[162:165], v[150:153]
	v_mfma_f32_16x16x32_bf16 v[110:113], v[122:125], v[170:173], v[110:113]
	v_mfma_f32_16x16x32_bf16 v[106:109], v[130:133], v[170:173], v[106:109]
	v_mfma_f32_16x16x32_bf16 v[94:97], v[122:125], v[178:181], v[94:97]
	v_mfma_f32_16x16x32_bf16 v[90:93], v[130:133], v[178:181], v[90:93]
	v_mfma_f32_16x16x32_bf16 v[78:81], v[122:125], v[186:189], v[78:81]
	v_mfma_f32_16x16x32_bf16 v[74:77], v[130:133], v[186:189], v[74:77]
	v_mfma_f32_16x16x32_bf16 v[154:157], v[126:129], v[166:169], v[154:157]
	v_mfma_f32_16x16x32_bf16 v[150:153], v[134:137], v[166:169], v[150:153]
	v_mfma_f32_16x16x32_bf16 v[110:113], v[126:129], v[174:177], v[110:113]
	v_mfma_f32_16x16x32_bf16 v[106:109], v[134:137], v[174:177], v[106:109]
	v_mfma_f32_16x16x32_bf16 v[94:97], v[126:129], v[182:185], v[94:97]
	v_mfma_f32_16x16x32_bf16 v[90:93], v[134:137], v[182:185], v[90:93]
	v_mfma_f32_16x16x32_bf16 v[78:81], v[126:129], v[190:193], v[78:81]
	v_mfma_f32_16x16x32_bf16 v[74:77], v[134:137], v[190:193], v[74:77]
	s_setprio 0
	s_setprio 1
	v_mfma_f32_16x16x32_bf16 v[118:121], v[138:141], v[162:165], v[118:121]
	v_mfma_f32_16x16x32_bf16 v[114:117], v[146:149], v[162:165], v[114:117]
	v_mfma_f32_16x16x32_bf16 v[102:105], v[138:141], v[170:173], v[102:105]
	v_mfma_f32_16x16x32_bf16 v[98:101], v[146:149], v[170:173], v[98:101]
	v_mfma_f32_16x16x32_bf16 v[86:89], v[138:141], v[178:181], v[86:89]
	v_mfma_f32_16x16x32_bf16 v[82:85], v[146:149], v[178:181], v[82:85]
	v_mfma_f32_16x16x32_bf16 v[70:73], v[138:141], v[186:189], v[70:73]
	v_mfma_f32_16x16x32_bf16 v[66:69], v[146:149], v[186:189], v[66:69]
	v_mfma_f32_16x16x32_bf16 v[118:121], v[142:145], v[166:169], v[118:121]
	v_mfma_f32_16x16x32_bf16 v[114:117], v[158:161], v[166:169], v[114:117]
	v_mfma_f32_16x16x32_bf16 v[102:105], v[142:145], v[174:177], v[102:105]
	v_mfma_f32_16x16x32_bf16 v[98:101], v[158:161], v[174:177], v[98:101]
	v_mfma_f32_16x16x32_bf16 v[86:89], v[142:145], v[182:185], v[86:89]
	v_mfma_f32_16x16x32_bf16 v[82:85], v[158:161], v[182:185], v[82:85]
	v_mfma_f32_16x16x32_bf16 v[70:73], v[142:145], v[190:193], v[70:73]
	v_mfma_f32_16x16x32_bf16 v[66:69], v[158:161], v[190:193], v[66:69]
	s_setprio 0
	s_barrier
	s_add_i32 s44, s72, s52
	v_lshl_add_u64 v[210:211], v[210:211], 0, s[24:25]
	s_mov_b32 m0, s44
	ds_read_b128 v[162:165], v247 offset:49152
	ds_read_b128 v[166:169], v247 offset:50176
	ds_read_b128 v[170:173], v247 offset:51200
	ds_read_b128 v[174:177], v247 offset:52224
	ds_read_b128 v[178:181], v247 offset:53248
	ds_read_b128 v[182:185], v247 offset:54272
	ds_read_b128 v[186:189], v247 offset:55296
	ds_read_b128 v[190:193], v247 offset:56320
	global_load_lds_dwordx4 v[210:211], off
	s_add_i32 m0, s44, 0x2000
	s_add_u32 s44, s48, 0xb0080
	v_lshl_add_u64 v[210:211], v[212:213], 0, s[24:25]
	s_addc_u32 s45, s49, 0
	s_add_i32 s48, s73, s52
	global_load_lds_dwordx4 v[210:211], off
	v_lshl_add_u64 v[210:211], s[44:45], 0, v[196:197]
	s_mov_b32 m0, s48
	s_nop 0
	global_load_lds_dwordx4 v[210:211], off
	v_lshl_add_u64 v[210:211], s[44:45], 0, v[200:201]
	s_add_i32 m0, s48, 0x2000
	s_nop 0
	global_load_lds_dwordx4 v[210:211], off
	v_lshl_add_u64 v[210:211], v[214:215], 0, s[24:25]
	s_mov_b32 m0, s58
	s_nop 0
	global_load_lds_dwordx4 v[210:211], off
	v_lshl_add_u64 v[210:211], v[216:217], 0, s[24:25]
	s_mov_b32 m0, s59
	s_nop 0
	global_load_lds_dwordx4 v[210:211], off
	s_waitcnt vmcnt(8)
	s_waitcnt lgkmcnt(0)
	s_setprio 1
	s_barrier
	v_mfma_f32_16x16x32_bf16 v[62:65], v[122:125], v[162:165], v[62:65]
	v_mfma_f32_16x16x32_bf16 v[58:61], v[130:133], v[162:165], v[58:61]
	v_mfma_f32_16x16x32_bf16 v[46:49], v[122:125], v[170:173], v[46:49]
	v_mfma_f32_16x16x32_bf16 v[42:45], v[130:133], v[170:173], v[42:45]
	v_mfma_f32_16x16x32_bf16 v[30:33], v[122:125], v[178:181], v[30:33]
	v_mfma_f32_16x16x32_bf16 v[26:29], v[130:133], v[178:181], v[26:29]
	v_mfma_f32_16x16x32_bf16 v[14:17], v[122:125], v[186:189], v[14:17]
	v_mfma_f32_16x16x32_bf16 v[10:13], v[130:133], v[186:189], v[10:13]
	v_mfma_f32_16x16x32_bf16 v[62:65], v[126:129], v[166:169], v[62:65]
	v_mfma_f32_16x16x32_bf16 v[58:61], v[134:137], v[166:169], v[58:61]
	v_mfma_f32_16x16x32_bf16 v[46:49], v[126:129], v[174:177], v[46:49]
	v_mfma_f32_16x16x32_bf16 v[42:45], v[134:137], v[174:177], v[42:45]
	v_mfma_f32_16x16x32_bf16 v[30:33], v[126:129], v[182:185], v[30:33]
	v_mfma_f32_16x16x32_bf16 v[26:29], v[134:137], v[182:185], v[26:29]
	v_mfma_f32_16x16x32_bf16 v[14:17], v[126:129], v[190:193], v[14:17]
	v_mfma_f32_16x16x32_bf16 v[10:13], v[134:137], v[190:193], v[10:13]
	s_setprio 0
	s_setprio 1
	v_mfma_f32_16x16x32_bf16 v[54:57], v[138:141], v[162:165], v[54:57]
	v_mfma_f32_16x16x32_bf16 v[50:53], v[146:149], v[162:165], v[50:53]
	v_mfma_f32_16x16x32_bf16 v[38:41], v[138:141], v[170:173], v[38:41]
	v_mfma_f32_16x16x32_bf16 v[34:37], v[146:149], v[170:173], v[34:37]
	v_mfma_f32_16x16x32_bf16 v[22:25], v[138:141], v[178:181], v[22:25]
	v_mfma_f32_16x16x32_bf16 v[18:21], v[146:149], v[178:181], v[18:21]
	v_mfma_f32_16x16x32_bf16 v[6:9], v[138:141], v[186:189], v[6:9]
	v_mfma_f32_16x16x32_bf16 v[2:5], v[146:149], v[186:189], v[2:5]
	v_mfma_f32_16x16x32_bf16 v[54:57], v[142:145], v[166:169], v[54:57]
	v_mfma_f32_16x16x32_bf16 v[50:53], v[158:161], v[166:169], v[50:53]
	v_mfma_f32_16x16x32_bf16 v[38:41], v[142:145], v[174:177], v[38:41]
	v_mfma_f32_16x16x32_bf16 v[34:37], v[158:161], v[174:177], v[34:37]
	v_mfma_f32_16x16x32_bf16 v[22:25], v[142:145], v[182:185], v[22:25]
	v_mfma_f32_16x16x32_bf16 v[18:21], v[158:161], v[182:185], v[18:21]
	v_mfma_f32_16x16x32_bf16 v[6:9], v[142:145], v[190:193], v[6:9]
	v_mfma_f32_16x16x32_bf16 v[2:5], v[158:161], v[190:193], v[2:5]
	s_setprio 0
	s_barrier
	s_add_i32 s71, s71, 2
	s_add_u32 s69, s69, 0x100
	s_addc_u32 s70, s70, 0
	s_cmp_gt_u32 s71, 41
	s_mov_b64 s[44:45], s[46:47]
	s_cbranch_scc0 .LBB0_251
	s_branch .Lz_post_p2

.Lz_post_p2:
	s_lshl_b32 s44, s68, 8
	v_lshl_add_u32 v238, s67, 8, v243
	s_ashr_i32 s45, s44, 31
	s_lshl_b64 s[46:47], s[44:45], 1
	v_ashrrev_i32_e32 v239, 31, v238
	v_lshl_add_u64 v[126:127], v[204:205], 0, s[46:47]
	v_lshlrev_b64 v[240:241], 11, v[238:239]
	v_lshl_add_u64 v[122:123], v[126:127], 0, v[240:241]
	global_load_dwordx4 v[190:193], v[122:123], off
	global_load_dwordx4 v[186:189], v[122:123], off offset:256
	v_or_b32_e32 v234, 16, v238
	v_ashrrev_i32_e32 v235, 31, v234
	v_or_b32_e32 v230, 32, v238
	v_lshlrev_b64 v[236:237], 11, v[234:235]
	v_ashrrev_i32_e32 v231, 31, v230
	v_or_b32_e32 v226, 48, v238
	v_lshl_add_u64 v[122:123], v[126:127], 0, v[236:237]
	v_lshlrev_b64 v[232:233], 11, v[230:231]
	v_ashrrev_i32_e32 v227, 31, v226
	v_add_u32_e32 v222, 0x80, v238
	global_load_dwordx4 v[182:185], v[122:123], off
	global_load_dwordx4 v[178:181], v[122:123], off offset:256
	v_lshl_add_u64 v[122:123], v[126:127], 0, v[232:233]
	v_lshlrev_b64 v[228:229], 11, v[226:227]
	v_ashrrev_i32_e32 v223, 31, v222
	v_add_u32_e32 v218, 0x90, v238
	global_load_dwordx4 v[174:177], v[122:123], off
	global_load_dwordx4 v[170:173], v[122:123], off offset:256
	v_lshl_add_u64 v[122:123], v[126:127], 0, v[228:229]
	v_lshlrev_b64 v[224:225], 11, v[222:223]
	v_ashrrev_i32_e32 v219, 31, v218
	v_add_u32_e32 v212, 0xa0, v238
	v_add_u32_e32 v210, 0xb0, v238
	global_load_dwordx4 v[166:169], v[122:123], off
	global_load_dwordx4 v[162:165], v[122:123], off offset:256
	v_lshl_add_u64 v[122:123], v[126:127], 0, v[224:225]
	v_lshlrev_b64 v[220:221], 11, v[218:219]
	v_ashrrev_i32_e32 v213, 31, v212
	v_ashrrev_i32_e32 v211, 31, v210
	global_load_dwordx4 v[158:161], v[122:123], off
	global_load_dwordx4 v[146:149], v[122:123], off offset:256
	v_lshl_add_u64 v[122:123], v[126:127], 0, v[220:221]
	v_lshlrev_b64 v[216:217], 11, v[212:213]
	v_lshlrev_b64 v[214:215], 11, v[210:211]
	global_load_dwordx4 v[142:145], v[122:123], off
	global_load_dwordx4 v[138:141], v[122:123], off offset:256
	v_lshl_add_u64 v[122:123], v[126:127], 0, v[216:217]
	v_lshl_add_u64 v[126:127], v[126:127], 0, v[214:215]
	global_load_dwordx4 v[130:133], v[122:123], off
	s_nop 0
	global_load_dwordx4 v[122:125], v[122:123], off offset:256
	s_nop 0
	global_load_dwordx4 v[134:137], v[126:127], off
	s_nop 0
	global_load_dwordx4 v[126:129], v[126:127], off offset:256
	s_and_b64 vcc, exec, s[26:27]
	s_cbranch_vccz .LBB0_254
	s_barrier

.LBB0_351:
	s_ashr_i32 s43, s42, 31
	s_lshl_b64 s[44:45], s[42:43], 19
	s_add_u32 s44, s3, s44
	s_addc_u32 s45, s23, s45
	s_and_b64 s[46:47], s[4:5], exec
	s_cselect_b32 s7, s45, s49
	s_cselect_b32 s43, s44, s48
	s_ashr_i32 s27, s26, 31
	s_lshl_b64 s[46:47], s[26:27], 19
	s_add_u32 s46, s29, s46
	s_addc_u32 s47, s31, s47
	s_and_b64 s[52:53], s[4:5], exec
	s_cselect_b32 s27, s47, s51
	s_cselect_b32 s70, s46, s50
	s_add_u32 s48, s48, 0x40080
	s_addc_u32 s49, s49, 0
	s_add_u32 s71, s50, 0x100
	s_addc_u32 s72, s51, 0
	s_mov_b32 s73, -2
	ds_read_b128 v[156:159], v152
	ds_read_b128 v[160:163], v152 offset:1024
	ds_read_b128 v[164:167], v152 offset:2048
	ds_read_b128 v[168:171], v152 offset:3072
	ds_read_b128 v[172:175], v153
	ds_read_b128 v[176:179], v153 offset:1024
	ds_read_b128 v[180:183], v153 offset:2048
	ds_read_b128 v[184:187], v153 offset:3072
	s_add_u32 s50, s48, 0xfffc0080
	s_addc_u32 s51, s49, -1
	s_cmp_eq_u32 s73, 12
	s_cselect_b32 s53, s7, s51
	s_cselect_b32 s52, s43, s50
	s_cselect_b32 s51, s27, s72
	s_cselect_b32 s50, s70, s71
	v_lshl_add_u64 v[148:149], s[48:49], 0, v[140:141]
	s_add_i32 m0, s57, 0xc000
	ds_read_b128 v[188:191], v154
	ds_read_b128 v[192:195], v154 offset:1024
	ds_read_b128 v[196:199], v154 offset:2048
	ds_read_b128 v[200:203], v154 offset:3072
	ds_read_b128 v[204:207], v154 offset:4096
	ds_read_b128 v[208:211], v154 offset:5120
	ds_read_b128 v[212:215], v154 offset:6144
	ds_read_b128 v[216:219], v154 offset:7168
	global_load_lds_dwordx4 v[148:149], off
	v_lshl_add_u64 v[148:149], s[48:49], 0, v[142:143]
	s_add_i32 m0, s57, 0xe000
	s_nop 0
	global_load_lds_dwordx4 v[148:149], off
	s_waitcnt vmcnt(8)
	s_waitcnt lgkmcnt(0)
	s_setprio 1
	s_barrier
	v_mfma_f32_16x16x32_bf16 v[126:129], v[156:159], v[188:191], 0
	v_mfma_f32_16x16x32_bf16 v[122:125], v[164:167], v[188:191], 0
	v_mfma_f32_16x16x32_bf16 v[110:113], v[156:159], v[196:199], 0
	v_mfma_f32_16x16x32_bf16 v[106:109], v[164:167], v[196:199], 0
	v_mfma_f32_16x16x32_bf16 v[94:97], v[156:159], v[204:207], 0
	v_mfma_f32_16x16x32_bf16 v[90:93], v[164:167], v[204:207], 0
	v_mfma_f32_16x16x32_bf16 v[78:81], v[156:159], v[212:215], 0
	v_mfma_f32_16x16x32_bf16 v[74:77], v[164:167], v[212:215], 0
	v_mfma_f32_16x16x32_bf16 v[126:129], v[160:163], v[192:195], v[126:129]
	v_mfma_f32_16x16x32_bf16 v[122:125], v[168:171], v[192:195], v[122:125]
	v_mfma_f32_16x16x32_bf16 v[110:113], v[160:163], v[200:203], v[110:113]
	v_mfma_f32_16x16x32_bf16 v[106:109], v[168:171], v[200:203], v[106:109]
	v_mfma_f32_16x16x32_bf16 v[94:97], v[160:163], v[208:211], v[94:97]
	v_mfma_f32_16x16x32_bf16 v[90:93], v[168:171], v[208:211], v[90:93]
	v_mfma_f32_16x16x32_bf16 v[78:81], v[160:163], v[216:219], v[78:81]
	v_mfma_f32_16x16x32_bf16 v[74:77], v[168:171], v[216:219], v[74:77]
	s_setprio 0
	s_setprio 1
	v_mfma_f32_16x16x32_bf16 v[118:121], v[172:175], v[188:191], 0
	v_mfma_f32_16x16x32_bf16 v[114:117], v[180:183], v[188:191], 0
	v_mfma_f32_16x16x32_bf16 v[102:105], v[172:175], v[196:199], 0
	v_mfma_f32_16x16x32_bf16 v[98:101], v[180:183], v[196:199], 0
	v_mfma_f32_16x16x32_bf16 v[86:89], v[172:175], v[204:207], 0
	v_mfma_f32_16x16x32_bf16 v[82:85], v[180:183], v[204:207], 0
	v_mfma_f32_16x16x32_bf16 v[70:73], v[172:175], v[212:215], 0
	v_mfma_f32_16x16x32_bf16 v[66:69], v[180:183], v[212:215], 0
	v_mfma_f32_16x16x32_bf16 v[118:121], v[176:179], v[192:195], v[118:121]
	v_mfma_f32_16x16x32_bf16 v[114:117], v[184:187], v[192:195], v[114:117]
	v_mfma_f32_16x16x32_bf16 v[102:105], v[176:179], v[200:203], v[102:105]
	v_mfma_f32_16x16x32_bf16 v[98:101], v[184:187], v[200:203], v[98:101]
	v_mfma_f32_16x16x32_bf16 v[86:89], v[176:179], v[208:211], v[86:89]
	v_mfma_f32_16x16x32_bf16 v[82:85], v[184:187], v[208:211], v[82:85]
	v_mfma_f32_16x16x32_bf16 v[70:73], v[176:179], v[216:219], v[70:73]
	v_mfma_f32_16x16x32_bf16 v[66:69], v[184:187], v[216:219], v[66:69]
	s_setprio 0
	s_barrier
	s_add_i32 s74, s67, s54
	v_lshl_add_u64 v[148:149], s[50:51], 0, v[134:135]
	s_mov_b32 m0, s74
	ds_read_b128 v[188:191], v154 offset:16384
	ds_read_b128 v[192:195], v154 offset:17408
	ds_read_b128 v[196:199], v154 offset:18432
	ds_read_b128 v[200:203], v154 offset:19456
	ds_read_b128 v[204:207], v154 offset:20480
	ds_read_b128 v[208:211], v154 offset:21504
	ds_read_b128 v[212:215], v154 offset:22528
	ds_read_b128 v[216:219], v154 offset:23552
	global_load_lds_dwordx4 v[148:149], off
	s_add_i32 m0, s74, 0x2000
	s_add_u32 s74, s50, 0x40000
	v_lshl_add_u64 v[220:221], s[50:51], 0, v[130:131]
	s_addc_u32 s75, s51, 0
	s_add_i32 s76, s68, s54
	global_load_lds_dwordx4 v[220:221], off
	v_lshl_add_u64 v[222:223], s[74:75], 0, v[134:135]
	s_mov_b32 m0, s76
	v_lshl_add_u64 v[224:225], s[52:53], 0, v[132:133]
	global_load_lds_dwordx4 v[222:223], off
	v_lshl_add_u64 v[222:223], s[74:75], 0, v[130:131]
	s_add_i32 m0, s76, 0x2000
	s_nop 0
	global_load_lds_dwordx4 v[222:223], off
	v_lshl_add_u64 v[222:223], s[52:53], 0, v[136:137]
	s_mov_b32 m0, s57
	s_nop 0
	global_load_lds_dwordx4 v[222:223], off
	s_mov_b32 m0, s58
	s_nop 0
	global_load_lds_dwordx4 v[224:225], off
	s_waitcnt vmcnt(8)
	s_waitcnt lgkmcnt(0)
	s_setprio 1
	s_barrier
	v_mfma_f32_16x16x32_bf16 v[62:65], v[156:159], v[188:191], 0
	v_mfma_f32_16x16x32_bf16 v[58:61], v[164:167], v[188:191], 0
	v_mfma_f32_16x16x32_bf16 v[46:49], v[156:159], v[196:199], 0
	v_mfma_f32_16x16x32_bf16 v[42:45], v[164:167], v[196:199], 0
	v_mfma_f32_16x16x32_bf16 v[30:33], v[156:159], v[204:207], 0
	v_mfma_f32_16x16x32_bf16 v[26:29], v[164:167], v[204:207], 0
	v_mfma_f32_16x16x32_bf16 v[14:17], v[156:159], v[212:215], 0
	v_mfma_f32_16x16x32_bf16 v[10:13], v[164:167], v[212:215], 0
	v_mfma_f32_16x16x32_bf16 v[62:65], v[160:163], v[192:195], v[62:65]
	v_mfma_f32_16x16x32_bf16 v[58:61], v[168:171], v[192:195], v[58:61]
	v_mfma_f32_16x16x32_bf16 v[46:49], v[160:163], v[200:203], v[46:49]
	v_mfma_f32_16x16x32_bf16 v[42:45], v[168:171], v[200:203], v[42:45]
	v_mfma_f32_16x16x32_bf16 v[30:33], v[160:163], v[208:211], v[30:33]
	v_mfma_f32_16x16x32_bf16 v[26:29], v[168:171], v[208:211], v[26:29]
	v_mfma_f32_16x16x32_bf16 v[14:17], v[160:163], v[216:219], v[14:17]
	v_mfma_f32_16x16x32_bf16 v[10:13], v[168:171], v[216:219], v[10:13]
	s_setprio 0
	s_setprio 1
	v_mfma_f32_16x16x32_bf16 v[54:57], v[172:175], v[188:191], 0
	v_mfma_f32_16x16x32_bf16 v[50:53], v[180:183], v[188:191], 0
	v_mfma_f32_16x16x32_bf16 v[38:41], v[172:175], v[196:199], 0
	v_mfma_f32_16x16x32_bf16 v[34:37], v[180:183], v[196:199], 0
	v_mfma_f32_16x16x32_bf16 v[22:25], v[172:175], v[204:207], 0
	v_mfma_f32_16x16x32_bf16 v[18:21], v[180:183], v[204:207], 0
	v_mfma_f32_16x16x32_bf16 v[6:9], v[172:175], v[212:215], 0
	v_mfma_f32_16x16x32_bf16 v[2:5], v[180:183], v[212:215], 0
	v_mfma_f32_16x16x32_bf16 v[54:57], v[176:179], v[192:195], v[54:57]
	v_mfma_f32_16x16x32_bf16 v[50:53], v[184:187], v[192:195], v[50:53]
	v_mfma_f32_16x16x32_bf16 v[38:41], v[176:179], v[200:203], v[38:41]
	v_mfma_f32_16x16x32_bf16 v[34:37], v[184:187], v[200:203], v[34:37]
	v_mfma_f32_16x16x32_bf16 v[22:25], v[176:179], v[208:211], v[22:25]
	v_mfma_f32_16x16x32_bf16 v[18:21], v[184:187], v[208:211], v[18:21]
	v_mfma_f32_16x16x32_bf16 v[6:9], v[176:179], v[216:219], v[6:9]
	v_mfma_f32_16x16x32_bf16 v[2:5], v[184:187], v[216:219], v[2:5]
	s_setprio 0
	s_barrier
	s_add_i32 s74, 0, 0x18000
	s_add_i32 s75, 0, 0x1c000
	v_add_u32_e32 v168, s74, v151
	v_add_u32_e32 v184, s75, v151
	ds_read_b128 v[156:159], v168
	ds_read_b128 v[160:163], v168 offset:1024
	ds_read_b128 v[164:167], v168 offset:2048
	ds_read_b128 v[168:171], v168 offset:3072
	ds_read_b128 v[172:175], v184
	ds_read_b128 v[176:179], v184 offset:1024
	ds_read_b128 v[180:183], v184 offset:2048
	ds_read_b128 v[184:187], v184 offset:3072
	s_add_u32 s52, s52, 0x40000
	s_addc_u32 s53, s53, 0
	s_mov_b32 m0, s59
	v_lshl_add_u64 v[226:227], s[52:53], 0, v[136:137]
	ds_read_b128 v[188:191], v154 offset:32768
	ds_read_b128 v[192:195], v154 offset:33792
	ds_read_b128 v[196:199], v154 offset:34816
	ds_read_b128 v[200:203], v154 offset:35840
	ds_read_b128 v[204:207], v154 offset:36864
	ds_read_b128 v[208:211], v154 offset:37888
	ds_read_b128 v[212:215], v154 offset:38912
	ds_read_b128 v[216:219], v154 offset:39936
	global_load_lds_dwordx4 v[226:227], off
	v_lshl_add_u64 v[226:227], s[52:53], 0, v[132:133]
	s_mov_b32 m0, s60
	s_nop 0
	global_load_lds_dwordx4 v[226:227], off
	s_waitcnt vmcnt(8)
	s_waitcnt lgkmcnt(0)
	s_setprio 1
	s_barrier
	v_mfma_f32_16x16x32_bf16 v[126:129], v[156:159], v[188:191], v[126:129]
	v_mfma_f32_16x16x32_bf16 v[122:125], v[164:167], v[188:191], v[122:125]
	v_mfma_f32_16x16x32_bf16 v[110:113], v[156:159], v[196:199], v[110:113]
	v_mfma_f32_16x16x32_bf16 v[106:109], v[164:167], v[196:199], v[106:109]
	v_mfma_f32_16x16x32_bf16 v[94:97], v[156:159], v[204:207], v[94:97]
	v_mfma_f32_16x16x32_bf16 v[90:93], v[164:167], v[204:207], v[90:93]
	v_mfma_f32_16x16x32_bf16 v[78:81], v[156:159], v[212:215], v[78:81]
	v_mfma_f32_16x16x32_bf16 v[74:77], v[164:167], v[212:215], v[74:77]
	v_mfma_f32_16x16x32_bf16 v[126:129], v[160:163], v[192:195], v[126:129]
	v_mfma_f32_16x16x32_bf16 v[122:125], v[168:171], v[192:195], v[122:125]
	v_mfma_f32_16x16x32_bf16 v[110:113], v[160:163], v[200:203], v[110:113]
	v_mfma_f32_16x16x32_bf16 v[106:109], v[168:171], v[200:203], v[106:109]
	v_mfma_f32_16x16x32_bf16 v[94:97], v[160:163], v[208:211], v[94:97]
	v_mfma_f32_16x16x32_bf16 v[90:93], v[168:171], v[208:211], v[90:93]
	v_mfma_f32_16x16x32_bf16 v[78:81], v[160:163], v[216:219], v[78:81]
	v_mfma_f32_16x16x32_bf16 v[74:77], v[168:171], v[216:219], v[74:77]
	s_setprio 0
	s_setprio 1
	v_mfma_f32_16x16x32_bf16 v[118:121], v[172:175], v[188:191], v[118:121]
	v_mfma_f32_16x16x32_bf16 v[114:117], v[180:183], v[188:191], v[114:117]
	v_mfma_f32_16x16x32_bf16 v[102:105], v[172:175], v[196:199], v[102:105]
	v_mfma_f32_16x16x32_bf16 v[98:101], v[180:183], v[196:199], v[98:101]
	v_mfma_f32_16x16x32_bf16 v[86:89], v[172:175], v[204:207], v[86:89]
	v_mfma_f32_16x16x32_bf16 v[82:85], v[180:183], v[204:207], v[82:85]
	v_mfma_f32_16x16x32_bf16 v[70:73], v[172:175], v[212:215], v[70:73]
	v_mfma_f32_16x16x32_bf16 v[66:69], v[180:183], v[212:215], v[66:69]
	v_mfma_f32_16x16x32_bf16 v[118:121], v[176:179], v[192:195], v[118:121]
	v_mfma_f32_16x16x32_bf16 v[114:117], v[184:187], v[192:195], v[114:117]
	v_mfma_f32_16x16x32_bf16 v[102:105], v[176:179], v[200:203], v[102:105]
	v_mfma_f32_16x16x32_bf16 v[98:101], v[184:187], v[200:203], v[98:101]
	v_mfma_f32_16x16x32_bf16 v[86:89], v[176:179], v[208:211], v[86:89]
	v_mfma_f32_16x16x32_bf16 v[82:85], v[184:187], v[208:211], v[82:85]
	v_mfma_f32_16x16x32_bf16 v[70:73], v[176:179], v[216:219], v[70:73]
	v_mfma_f32_16x16x32_bf16 v[66:69], v[184:187], v[216:219], v[66:69]
	s_setprio 0
	s_barrier
	s_add_i32 s52, s74, s54
	v_lshl_add_u64 v[148:149], v[148:149], 0, s[16:17]
	s_mov_b32 m0, s52
	ds_read_b128 v[188:191], v154 offset:49152
	ds_read_b128 v[192:195], v154 offset:50176
	ds_read_b128 v[196:199], v154 offset:51200
	ds_read_b128 v[200:203], v154 offset:52224
	ds_read_b128 v[204:207], v154 offset:53248
	ds_read_b128 v[208:211], v154 offset:54272
	ds_read_b128 v[212:215], v154 offset:55296
	ds_read_b128 v[216:219], v154 offset:56320
	global_load_lds_dwordx4 v[148:149], off
	s_add_i32 m0, s52, 0x2000
	s_add_u32 s50, s50, 0x40080
	v_lshl_add_u64 v[148:149], v[220:221], 0, s[16:17]
	s_addc_u32 s51, s51, 0
	s_add_i32 s52, s75, s54
	global_load_lds_dwordx4 v[148:149], off
	v_lshl_add_u64 v[148:149], s[50:51], 0, v[134:135]
	s_mov_b32 m0, s52
	s_nop 0
	global_load_lds_dwordx4 v[148:149], off
	v_lshl_add_u64 v[148:149], s[50:51], 0, v[130:131]
	s_add_i32 m0, s52, 0x2000
	s_nop 0
	global_load_lds_dwordx4 v[148:149], off
	v_lshl_add_u64 v[148:149], v[222:223], 0, s[16:17]
	s_mov_b32 m0, s63
	s_nop 0
	global_load_lds_dwordx4 v[148:149], off
	v_lshl_add_u64 v[148:149], v[224:225], 0, s[16:17]
	s_mov_b32 m0, s64
	s_nop 0
	global_load_lds_dwordx4 v[148:149], off
	s_waitcnt vmcnt(8)
	s_waitcnt lgkmcnt(0)
	s_setprio 1
	s_barrier
	v_mfma_f32_16x16x32_bf16 v[62:65], v[156:159], v[188:191], v[62:65]
	v_mfma_f32_16x16x32_bf16 v[58:61], v[164:167], v[188:191], v[58:61]
	v_mfma_f32_16x16x32_bf16 v[46:49], v[156:159], v[196:199], v[46:49]
	v_mfma_f32_16x16x32_bf16 v[42:45], v[164:167], v[196:199], v[42:45]
	v_mfma_f32_16x16x32_bf16 v[30:33], v[156:159], v[204:207], v[30:33]
	v_mfma_f32_16x16x32_bf16 v[26:29], v[164:167], v[204:207], v[26:29]
	v_mfma_f32_16x16x32_bf16 v[14:17], v[156:159], v[212:215], v[14:17]
	v_mfma_f32_16x16x32_bf16 v[10:13], v[164:167], v[212:215], v[10:13]
	v_mfma_f32_16x16x32_bf16 v[62:65], v[160:163], v[192:195], v[62:65]
	v_mfma_f32_16x16x32_bf16 v[58:61], v[168:171], v[192:195], v[58:61]
	v_mfma_f32_16x16x32_bf16 v[46:49], v[160:163], v[200:203], v[46:49]
	v_mfma_f32_16x16x32_bf16 v[42:45], v[168:171], v[200:203], v[42:45]
	v_mfma_f32_16x16x32_bf16 v[30:33], v[160:163], v[208:211], v[30:33]
	v_mfma_f32_16x16x32_bf16 v[26:29], v[168:171], v[208:211], v[26:29]
	v_mfma_f32_16x16x32_bf16 v[14:17], v[160:163], v[216:219], v[14:17]
	v_mfma_f32_16x16x32_bf16 v[10:13], v[168:171], v[216:219], v[10:13]
	s_setprio 0
	s_setprio 1
	v_mfma_f32_16x16x32_bf16 v[54:57], v[172:175], v[188:191], v[54:57]
	v_mfma_f32_16x16x32_bf16 v[50:53], v[180:183], v[188:191], v[50:53]
	v_mfma_f32_16x16x32_bf16 v[38:41], v[172:175], v[196:199], v[38:41]
	v_mfma_f32_16x16x32_bf16 v[34:37], v[180:183], v[196:199], v[34:37]
	v_mfma_f32_16x16x32_bf16 v[22:25], v[172:175], v[204:207], v[22:25]
	v_mfma_f32_16x16x32_bf16 v[18:21], v[180:183], v[204:207], v[18:21]
	v_mfma_f32_16x16x32_bf16 v[6:9], v[172:175], v[212:215], v[6:9]
	v_mfma_f32_16x16x32_bf16 v[2:5], v[180:183], v[212:215], v[2:5]
	v_mfma_f32_16x16x32_bf16 v[54:57], v[176:179], v[192:195], v[54:57]
	v_mfma_f32_16x16x32_bf16 v[50:53], v[184:187], v[192:195], v[50:53]
	v_mfma_f32_16x16x32_bf16 v[38:41], v[176:179], v[200:203], v[38:41]
	v_mfma_f32_16x16x32_bf16 v[34:37], v[184:187], v[200:203], v[34:37]
	v_mfma_f32_16x16x32_bf16 v[22:25], v[176:179], v[208:211], v[22:25]
	v_mfma_f32_16x16x32_bf16 v[18:21], v[184:187], v[208:211], v[18:21]
	v_mfma_f32_16x16x32_bf16 v[6:9], v[176:179], v[216:219], v[6:9]
	v_mfma_f32_16x16x32_bf16 v[2:5], v[184:187], v[216:219], v[2:5]
	s_setprio 0
	s_barrier
	s_add_i32 s73, s73, 2
	s_add_u32 s48, s48, 0x100
	s_addc_u32 s49, s49, 0
	s_add_u32 s71, s71, 0x100
	s_addc_u32 s72, s72, 0
	s_cmp_gt_u32 s73, 13
	s_cbranch_scc0 .LBB0_352
	s_branch .Lz_post_p3

.Lz_post_p3:
	s_and_b64 vcc, exec, s[24:25]
	s_cbranch_vccz .LBB0_355
	s_barrier

.LBB0_738:
	s_ashr_i32 s43, s42, 31
	s_lshl_b64 s[44:45], s[42:43], 19
	s_add_u32 s44, s3, s44
	s_addc_u32 s45, s23, s45
	s_and_b64 s[46:47], s[6:7], exec
	s_cselect_b32 s43, s45, s53
	s_cselect_b32 s49, s44, s52
	s_ashr_i32 s27, s26, 31
	s_lshl_b64 s[46:47], s[26:27], 19
	s_add_u32 s46, s29, s46
	s_addc_u32 s47, s31, s47
	s_and_b64 s[56:57], s[6:7], exec
	s_cselect_b32 s27, s47, s55
	s_cselect_b32 s51, s46, s54
	s_add_u32 s52, s52, 0x40080
	s_addc_u32 s53, s53, 0
	s_add_u32 s71, s54, 0x100
	s_addc_u32 s72, s55, 0
	s_mov_b32 s73, -2
	s_waitcnt vmcnt(0)
	ds_read_b128 v[122:125], v245
	ds_read_b128 v[126:129], v245 offset:1024
	ds_read_b128 v[130:133], v245 offset:2048
	ds_read_b128 v[134:137], v245 offset:3072
	ds_read_b128 v[138:141], v246
	ds_read_b128 v[142:145], v246 offset:1024
	ds_read_b128 v[146:149], v246 offset:2048
	ds_read_b128 v[158:161], v246 offset:3072
	s_add_u32 s54, s52, 0xfffc0080
	s_addc_u32 s55, s53, -1
	s_cmp_eq_u32 s73, 12
	s_cselect_b32 s57, s43, s55
	s_cselect_b32 s56, s49, s54
	s_cselect_b32 s55, s27, s72
	s_cselect_b32 s54, s51, s71
	v_lshl_add_u64 v[210:211], s[52:53], 0, v[206:207]
	s_add_i32 m0, s59, 0xc000
	ds_read_b128 v[162:165], v247
	ds_read_b128 v[166:169], v247 offset:1024
	ds_read_b128 v[170:173], v247 offset:2048
	ds_read_b128 v[174:177], v247 offset:3072
	ds_read_b128 v[178:181], v247 offset:4096
	ds_read_b128 v[182:185], v247 offset:5120
	ds_read_b128 v[186:189], v247 offset:6144
	ds_read_b128 v[190:193], v247 offset:7168
	global_load_lds_dwordx4 v[210:211], off
	v_lshl_add_u64 v[210:211], s[52:53], 0, v[208:209]
	s_add_i32 m0, s59, 0xe000
	s_nop 0
	global_load_lds_dwordx4 v[210:211], off
	s_waitcnt vmcnt(8)
	s_waitcnt lgkmcnt(0)
	s_setprio 1
	s_barrier
	v_mfma_f32_16x16x32_bf16 v[154:157], v[122:125], v[162:165], 0
	v_mfma_f32_16x16x32_bf16 v[150:153], v[130:133], v[162:165], 0
	v_mfma_f32_16x16x32_bf16 v[110:113], v[122:125], v[170:173], 0
	v_mfma_f32_16x16x32_bf16 v[106:109], v[130:133], v[170:173], 0
	v_mfma_f32_16x16x32_bf16 v[94:97], v[122:125], v[178:181], 0
	v_mfma_f32_16x16x32_bf16 v[90:93], v[130:133], v[178:181], 0
	v_mfma_f32_16x16x32_bf16 v[78:81], v[122:125], v[186:189], 0
	v_mfma_f32_16x16x32_bf16 v[74:77], v[130:133], v[186:189], 0
	v_mfma_f32_16x16x32_bf16 v[154:157], v[126:129], v[166:169], v[154:157]
	v_mfma_f32_16x16x32_bf16 v[150:153], v[134:137], v[166:169], v[150:153]
	v_mfma_f32_16x16x32_bf16 v[110:113], v[126:129], v[174:177], v[110:113]
	v_mfma_f32_16x16x32_bf16 v[106:109], v[134:137], v[174:177], v[106:109]
	v_mfma_f32_16x16x32_bf16 v[94:97], v[126:129], v[182:185], v[94:97]
	v_mfma_f32_16x16x32_bf16 v[90:93], v[134:137], v[182:185], v[90:93]
	v_mfma_f32_16x16x32_bf16 v[78:81], v[126:129], v[190:193], v[78:81]
	v_mfma_f32_16x16x32_bf16 v[74:77], v[134:137], v[190:193], v[74:77]
	s_setprio 0
	s_setprio 1
	v_mfma_f32_16x16x32_bf16 v[118:121], v[138:141], v[162:165], 0
	v_mfma_f32_16x16x32_bf16 v[114:117], v[146:149], v[162:165], 0
	v_mfma_f32_16x16x32_bf16 v[102:105], v[138:141], v[170:173], 0
	v_mfma_f32_16x16x32_bf16 v[98:101], v[146:149], v[170:173], 0
	v_mfma_f32_16x16x32_bf16 v[86:89], v[138:141], v[178:181], 0
	v_mfma_f32_16x16x32_bf16 v[82:85], v[146:149], v[178:181], 0
	v_mfma_f32_16x16x32_bf16 v[70:73], v[138:141], v[186:189], 0
	v_mfma_f32_16x16x32_bf16 v[66:69], v[146:149], v[186:189], 0
	v_mfma_f32_16x16x32_bf16 v[118:121], v[142:145], v[166:169], v[118:121]
	v_mfma_f32_16x16x32_bf16 v[114:117], v[158:161], v[166:169], v[114:117]
	v_mfma_f32_16x16x32_bf16 v[102:105], v[142:145], v[174:177], v[102:105]
	v_mfma_f32_16x16x32_bf16 v[98:101], v[158:161], v[174:177], v[98:101]
	v_mfma_f32_16x16x32_bf16 v[86:89], v[142:145], v[182:185], v[86:89]
	v_mfma_f32_16x16x32_bf16 v[82:85], v[158:161], v[182:185], v[82:85]
	v_mfma_f32_16x16x32_bf16 v[70:73], v[142:145], v[190:193], v[70:73]
	v_mfma_f32_16x16x32_bf16 v[66:69], v[158:161], v[190:193], v[66:69]
	s_setprio 0
	s_barrier
	s_add_i32 s74, s69, s58
	v_lshl_add_u64 v[210:211], s[54:55], 0, v[196:197]
	s_mov_b32 m0, s74
	ds_read_b128 v[162:165], v247 offset:16384
	ds_read_b128 v[166:169], v247 offset:17408
	ds_read_b128 v[170:173], v247 offset:18432
	ds_read_b128 v[174:177], v247 offset:19456
	ds_read_b128 v[178:181], v247 offset:20480
	ds_read_b128 v[182:185], v247 offset:21504
	ds_read_b128 v[186:189], v247 offset:22528
	ds_read_b128 v[190:193], v247 offset:23552
	global_load_lds_dwordx4 v[210:211], off
	s_add_i32 m0, s74, 0x2000
	s_add_u32 s74, s54, 0x40000
	v_lshl_add_u64 v[212:213], s[54:55], 0, v[200:201]
	s_addc_u32 s75, s55, 0
	s_add_i32 s76, s70, s58
	global_load_lds_dwordx4 v[212:213], off
	v_lshl_add_u64 v[214:215], s[74:75], 0, v[196:197]
	s_mov_b32 m0, s76
	v_lshl_add_u64 v[216:217], s[56:57], 0, v[198:199]
	global_load_lds_dwordx4 v[214:215], off
	v_lshl_add_u64 v[214:215], s[74:75], 0, v[200:201]
	s_add_i32 m0, s76, 0x2000
	s_nop 0
	global_load_lds_dwordx4 v[214:215], off
	v_lshl_add_u64 v[214:215], s[56:57], 0, v[194:195]
	s_mov_b32 m0, s59
	s_nop 0
	global_load_lds_dwordx4 v[214:215], off
	s_mov_b32 m0, s60
	s_nop 0
	global_load_lds_dwordx4 v[216:217], off
	s_waitcnt vmcnt(8)
	s_waitcnt lgkmcnt(0)
	s_setprio 1
	s_barrier
	v_mfma_f32_16x16x32_bf16 v[62:65], v[122:125], v[162:165], 0
	v_mfma_f32_16x16x32_bf16 v[58:61], v[130:133], v[162:165], 0
	v_mfma_f32_16x16x32_bf16 v[46:49], v[122:125], v[170:173], 0
	v_mfma_f32_16x16x32_bf16 v[42:45], v[130:133], v[170:173], 0
	v_mfma_f32_16x16x32_bf16 v[30:33], v[122:125], v[178:181], 0
	v_mfma_f32_16x16x32_bf16 v[26:29], v[130:133], v[178:181], 0
	v_mfma_f32_16x16x32_bf16 v[14:17], v[122:125], v[186:189], 0
	v_mfma_f32_16x16x32_bf16 v[10:13], v[130:133], v[186:189], 0
	v_mfma_f32_16x16x32_bf16 v[62:65], v[126:129], v[166:169], v[62:65]
	v_mfma_f32_16x16x32_bf16 v[58:61], v[134:137], v[166:169], v[58:61]
	v_mfma_f32_16x16x32_bf16 v[46:49], v[126:129], v[174:177], v[46:49]
	v_mfma_f32_16x16x32_bf16 v[42:45], v[134:137], v[174:177], v[42:45]
	v_mfma_f32_16x16x32_bf16 v[30:33], v[126:129], v[182:185], v[30:33]
	v_mfma_f32_16x16x32_bf16 v[26:29], v[134:137], v[182:185], v[26:29]
	v_mfma_f32_16x16x32_bf16 v[14:17], v[126:129], v[190:193], v[14:17]
	v_mfma_f32_16x16x32_bf16 v[10:13], v[134:137], v[190:193], v[10:13]
	s_setprio 0
	s_setprio 1
	v_mfma_f32_16x16x32_bf16 v[54:57], v[138:141], v[162:165], 0
	v_mfma_f32_16x16x32_bf16 v[50:53], v[146:149], v[162:165], 0
	v_mfma_f32_16x16x32_bf16 v[38:41], v[138:141], v[170:173], 0
	v_mfma_f32_16x16x32_bf16 v[34:37], v[146:149], v[170:173], 0
	v_mfma_f32_16x16x32_bf16 v[22:25], v[138:141], v[178:181], 0
	v_mfma_f32_16x16x32_bf16 v[18:21], v[146:149], v[178:181], 0
	v_mfma_f32_16x16x32_bf16 v[6:9], v[138:141], v[186:189], 0
	v_mfma_f32_16x16x32_bf16 v[2:5], v[146:149], v[186:189], 0
	v_mfma_f32_16x16x32_bf16 v[54:57], v[142:145], v[166:169], v[54:57]
	v_mfma_f32_16x16x32_bf16 v[50:53], v[158:161], v[166:169], v[50:53]
	v_mfma_f32_16x16x32_bf16 v[38:41], v[142:145], v[174:177], v[38:41]
	v_mfma_f32_16x16x32_bf16 v[34:37], v[158:161], v[174:177], v[34:37]
	v_mfma_f32_16x16x32_bf16 v[22:25], v[142:145], v[182:185], v[22:25]
	v_mfma_f32_16x16x32_bf16 v[18:21], v[158:161], v[182:185], v[18:21]
	v_mfma_f32_16x16x32_bf16 v[6:9], v[142:145], v[190:193], v[6:9]
	v_mfma_f32_16x16x32_bf16 v[2:5], v[158:161], v[190:193], v[2:5]
	s_setprio 0
	s_barrier
	s_add_i32 s74, 0, 0x18000
	s_add_i32 s75, 0, 0x1c000
	v_add_u32_e32 v134, s74, v244
	v_add_u32_e32 v158, s75, v244
	ds_read_b128 v[122:125], v134
	ds_read_b128 v[126:129], v134 offset:1024
	ds_read_b128 v[130:133], v134 offset:2048
	ds_read_b128 v[134:137], v134 offset:3072
	ds_read_b128 v[138:141], v158
	ds_read_b128 v[142:145], v158 offset:1024
	ds_read_b128 v[146:149], v158 offset:2048
	ds_read_b128 v[158:161], v158 offset:3072
	s_add_u32 s56, s56, 0x40000
	s_addc_u32 s57, s57, 0
	s_mov_b32 m0, s61
	v_lshl_add_u64 v[218:219], s[56:57], 0, v[194:195]
	ds_read_b128 v[162:165], v247 offset:32768
	ds_read_b128 v[166:169], v247 offset:33792
	ds_read_b128 v[170:173], v247 offset:34816
	ds_read_b128 v[174:177], v247 offset:35840
	ds_read_b128 v[178:181], v247 offset:36864
	ds_read_b128 v[182:185], v247 offset:37888
	ds_read_b128 v[186:189], v247 offset:38912
	ds_read_b128 v[190:193], v247 offset:39936
	global_load_lds_dwordx4 v[218:219], off
	v_lshl_add_u64 v[218:219], s[56:57], 0, v[198:199]
	s_mov_b32 m0, s62
	s_nop 0
	global_load_lds_dwordx4 v[218:219], off
	s_waitcnt vmcnt(8)
	s_waitcnt lgkmcnt(0)
	s_setprio 1
	s_barrier
	v_mfma_f32_16x16x32_bf16 v[154:157], v[122:125], v[162:165], v[154:157]
	v_mfma_f32_16x16x32_bf16 v[150:153], v[130:133], v[162:165], v[150:153]
	v_mfma_f32_16x16x32_bf16 v[110:113], v[122:125], v[170:173], v[110:113]
	v_mfma_f32_16x16x32_bf16 v[106:109], v[130:133], v[170:173], v[106:109]
	v_mfma_f32_16x16x32_bf16 v[94:97], v[122:125], v[178:181], v[94:97]
	v_mfma_f32_16x16x32_bf16 v[90:93], v[130:133], v[178:181], v[90:93]
	v_mfma_f32_16x16x32_bf16 v[78:81], v[122:125], v[186:189], v[78:81]
	v_mfma_f32_16x16x32_bf16 v[74:77], v[130:133], v[186:189], v[74:77]
	v_mfma_f32_16x16x32_bf16 v[154:157], v[126:129], v[166:169], v[154:157]
	v_mfma_f32_16x16x32_bf16 v[150:153], v[134:137], v[166:169], v[150:153]
	v_mfma_f32_16x16x32_bf16 v[110:113], v[126:129], v[174:177], v[110:113]
	v_mfma_f32_16x16x32_bf16 v[106:109], v[134:137], v[174:177], v[106:109]
	v_mfma_f32_16x16x32_bf16 v[94:97], v[126:129], v[182:185], v[94:97]
	v_mfma_f32_16x16x32_bf16 v[90:93], v[134:137], v[182:185], v[90:93]
	v_mfma_f32_16x16x32_bf16 v[78:81], v[126:129], v[190:193], v[78:81]
	v_mfma_f32_16x16x32_bf16 v[74:77], v[134:137], v[190:193], v[74:77]
	s_setprio 0
	s_setprio 1
	v_mfma_f32_16x16x32_bf16 v[118:121], v[138:141], v[162:165], v[118:121]
	v_mfma_f32_16x16x32_bf16 v[114:117], v[146:149], v[162:165], v[114:117]
	v_mfma_f32_16x16x32_bf16 v[102:105], v[138:141], v[170:173], v[102:105]
	v_mfma_f32_16x16x32_bf16 v[98:101], v[146:149], v[170:173], v[98:101]
	v_mfma_f32_16x16x32_bf16 v[86:89], v[138:141], v[178:181], v[86:89]
	v_mfma_f32_16x16x32_bf16 v[82:85], v[146:149], v[178:181], v[82:85]
	v_mfma_f32_16x16x32_bf16 v[70:73], v[138:141], v[186:189], v[70:73]
	v_mfma_f32_16x16x32_bf16 v[66:69], v[146:149], v[186:189], v[66:69]
	v_mfma_f32_16x16x32_bf16 v[118:121], v[142:145], v[166:169], v[118:121]
	v_mfma_f32_16x16x32_bf16 v[114:117], v[158:161], v[166:169], v[114:117]
	v_mfma_f32_16x16x32_bf16 v[102:105], v[142:145], v[174:177], v[102:105]
	v_mfma_f32_16x16x32_bf16 v[98:101], v[158:161], v[174:177], v[98:101]
	v_mfma_f32_16x16x32_bf16 v[86:89], v[142:145], v[182:185], v[86:89]
	v_mfma_f32_16x16x32_bf16 v[82:85], v[158:161], v[182:185], v[82:85]
	v_mfma_f32_16x16x32_bf16 v[70:73], v[142:145], v[190:193], v[70:73]
	v_mfma_f32_16x16x32_bf16 v[66:69], v[158:161], v[190:193], v[66:69]
	s_setprio 0
	s_barrier
	s_add_i32 s56, s74, s58
	v_lshl_add_u64 v[210:211], v[210:211], 0, s[16:17]
	s_mov_b32 m0, s56
	ds_read_b128 v[162:165], v247 offset:49152
	ds_read_b128 v[166:169], v247 offset:50176
	ds_read_b128 v[170:173], v247 offset:51200
	ds_read_b128 v[174:177], v247 offset:52224
	ds_read_b128 v[178:181], v247 offset:53248
	ds_read_b128 v[182:185], v247 offset:54272
	ds_read_b128 v[186:189], v247 offset:55296
	ds_read_b128 v[190:193], v247 offset:56320
	global_load_lds_dwordx4 v[210:211], off
	s_add_i32 m0, s56, 0x2000
	s_add_u32 s54, s54, 0x40080
	v_lshl_add_u64 v[210:211], v[212:213], 0, s[16:17]
	s_addc_u32 s55, s55, 0
	s_add_i32 s56, s75, s58
	global_load_lds_dwordx4 v[210:211], off
	v_lshl_add_u64 v[210:211], s[54:55], 0, v[196:197]
	s_mov_b32 m0, s56
	s_nop 0
	global_load_lds_dwordx4 v[210:211], off
	v_lshl_add_u64 v[210:211], s[54:55], 0, v[200:201]
	s_add_i32 m0, s56, 0x2000
	s_nop 0
	global_load_lds_dwordx4 v[210:211], off
	v_lshl_add_u64 v[210:211], v[214:215], 0, s[16:17]
	s_mov_b32 m0, s64
	s_nop 0
	global_load_lds_dwordx4 v[210:211], off
	v_lshl_add_u64 v[210:211], v[216:217], 0, s[16:17]
	s_mov_b32 m0, s65
	s_nop 0
	global_load_lds_dwordx4 v[210:211], off
	s_waitcnt vmcnt(8)
	s_waitcnt lgkmcnt(0)
	s_setprio 1
	s_barrier
	v_mfma_f32_16x16x32_bf16 v[62:65], v[122:125], v[162:165], v[62:65]
	v_mfma_f32_16x16x32_bf16 v[58:61], v[130:133], v[162:165], v[58:61]
	v_mfma_f32_16x16x32_bf16 v[46:49], v[122:125], v[170:173], v[46:49]
	v_mfma_f32_16x16x32_bf16 v[42:45], v[130:133], v[170:173], v[42:45]
	v_mfma_f32_16x16x32_bf16 v[30:33], v[122:125], v[178:181], v[30:33]
	v_mfma_f32_16x16x32_bf16 v[26:29], v[130:133], v[178:181], v[26:29]
	v_mfma_f32_16x16x32_bf16 v[14:17], v[122:125], v[186:189], v[14:17]
	v_mfma_f32_16x16x32_bf16 v[10:13], v[130:133], v[186:189], v[10:13]
	v_mfma_f32_16x16x32_bf16 v[62:65], v[126:129], v[166:169], v[62:65]
	v_mfma_f32_16x16x32_bf16 v[58:61], v[134:137], v[166:169], v[58:61]
	v_mfma_f32_16x16x32_bf16 v[46:49], v[126:129], v[174:177], v[46:49]
	v_mfma_f32_16x16x32_bf16 v[42:45], v[134:137], v[174:177], v[42:45]
	v_mfma_f32_16x16x32_bf16 v[30:33], v[126:129], v[182:185], v[30:33]
	v_mfma_f32_16x16x32_bf16 v[26:29], v[134:137], v[182:185], v[26:29]
	v_mfma_f32_16x16x32_bf16 v[14:17], v[126:129], v[190:193], v[14:17]
	v_mfma_f32_16x16x32_bf16 v[10:13], v[134:137], v[190:193], v[10:13]
	s_setprio 0
	s_setprio 1
	v_mfma_f32_16x16x32_bf16 v[54:57], v[138:141], v[162:165], v[54:57]
	v_mfma_f32_16x16x32_bf16 v[50:53], v[146:149], v[162:165], v[50:53]
	v_mfma_f32_16x16x32_bf16 v[38:41], v[138:141], v[170:173], v[38:41]
	v_mfma_f32_16x16x32_bf16 v[34:37], v[146:149], v[170:173], v[34:37]
	v_mfma_f32_16x16x32_bf16 v[22:25], v[138:141], v[178:181], v[22:25]
	v_mfma_f32_16x16x32_bf16 v[18:21], v[146:149], v[178:181], v[18:21]
	v_mfma_f32_16x16x32_bf16 v[6:9], v[138:141], v[186:189], v[6:9]
	v_mfma_f32_16x16x32_bf16 v[2:5], v[146:149], v[186:189], v[2:5]
	v_mfma_f32_16x16x32_bf16 v[54:57], v[142:145], v[166:169], v[54:57]
	v_mfma_f32_16x16x32_bf16 v[50:53], v[158:161], v[166:169], v[50:53]
	v_mfma_f32_16x16x32_bf16 v[38:41], v[142:145], v[174:177], v[38:41]
	v_mfma_f32_16x16x32_bf16 v[34:37], v[158:161], v[174:177], v[34:37]
	v_mfma_f32_16x16x32_bf16 v[22:25], v[142:145], v[182:185], v[22:25]
	v_mfma_f32_16x16x32_bf16 v[18:21], v[158:161], v[182:185], v[18:21]
	v_mfma_f32_16x16x32_bf16 v[6:9], v[142:145], v[190:193], v[6:9]
	v_mfma_f32_16x16x32_bf16 v[2:5], v[158:161], v[190:193], v[2:5]
	s_setprio 0
	s_barrier
	s_add_i32 s73, s73, 2
	s_add_u32 s52, s52, 0x100
	s_addc_u32 s53, s53, 0
	s_add_u32 s71, s71, 0x100
	s_addc_u32 s72, s72, 0
	s_cmp_gt_u32 s73, 13
	s_cbranch_scc0 .LBB0_739
	s_branch .Lz_post_p5

.Lz_post_p5:
	v_lshl_add_u32 v238, s48, 8, v243
	s_lshl_b32 s48, s50, 8
	s_ashr_i32 s49, s48, 31
	s_lshl_b64 s[50:51], s[48:49], 1
	v_ashrrev_i32_e32 v239, 31, v238
	v_lshl_add_u64 v[126:127], v[204:205], 0, s[50:51]
	v_lshlrev_b64 v[240:241], 11, v[238:239]
	v_lshl_add_u64 v[122:123], v[126:127], 0, v[240:241]
	global_load_dwordx4 v[190:193], v[122:123], off
	global_load_dwordx4 v[186:189], v[122:123], off offset:256
	v_or_b32_e32 v234, 16, v238
	v_ashrrev_i32_e32 v235, 31, v234
	v_or_b32_e32 v230, 32, v238
	v_lshlrev_b64 v[236:237], 11, v[234:235]
	v_ashrrev_i32_e32 v231, 31, v230
	v_or_b32_e32 v226, 48, v238
	v_lshl_add_u64 v[122:123], v[126:127], 0, v[236:237]
	v_lshlrev_b64 v[232:233], 11, v[230:231]
	v_ashrrev_i32_e32 v227, 31, v226
	v_add_u32_e32 v222, 0x80, v238
	global_load_dwordx4 v[182:185], v[122:123], off
	global_load_dwordx4 v[178:181], v[122:123], off offset:256
	v_lshl_add_u64 v[122:123], v[126:127], 0, v[232:233]
	v_lshlrev_b64 v[228:229], 11, v[226:227]
	v_ashrrev_i32_e32 v223, 31, v222
	v_add_u32_e32 v218, 0x90, v238
	global_load_dwordx4 v[174:177], v[122:123], off
	global_load_dwordx4 v[170:173], v[122:123], off offset:256
	v_lshl_add_u64 v[122:123], v[126:127], 0, v[228:229]
	v_lshlrev_b64 v[224:225], 11, v[222:223]
	v_ashrrev_i32_e32 v219, 31, v218
	v_add_u32_e32 v212, 0xa0, v238
	v_add_u32_e32 v210, 0xb0, v238
	global_load_dwordx4 v[166:169], v[122:123], off
	global_load_dwordx4 v[162:165], v[122:123], off offset:256
	v_lshl_add_u64 v[122:123], v[126:127], 0, v[224:225]
	v_lshlrev_b64 v[220:221], 11, v[218:219]
	v_ashrrev_i32_e32 v213, 31, v212
	v_ashrrev_i32_e32 v211, 31, v210
	global_load_dwordx4 v[158:161], v[122:123], off
	global_load_dwordx4 v[146:149], v[122:123], off offset:256
	v_lshl_add_u64 v[122:123], v[126:127], 0, v[220:221]
	v_lshlrev_b64 v[216:217], 11, v[212:213]
	v_lshlrev_b64 v[214:215], 11, v[210:211]
	global_load_dwordx4 v[142:145], v[122:123], off
	global_load_dwordx4 v[138:141], v[122:123], off offset:256
	v_lshl_add_u64 v[122:123], v[126:127], 0, v[216:217]
	v_lshl_add_u64 v[126:127], v[126:127], 0, v[214:215]
	global_load_dwordx4 v[130:133], v[122:123], off
	s_nop 0
	global_load_dwordx4 v[122:125], v[122:123], off offset:256
	s_nop 0
	global_load_dwordx4 v[134:137], v[126:127], off
	s_nop 0
	global_load_dwordx4 v[126:129], v[126:127], off offset:256
	s_and_b64 vcc, exec, s[24:25]
	s_cbranch_vccz .LBB0_742
	s_barrier

.LBB0_839:
	s_ashr_i32 s27, s26, 31
	s_lshl_b64 s[42:43], s[26:27], 19
	s_add_u32 s42, s3, s42
	s_addc_u32 s43, s23, s43
	s_and_b64 s[44:45], s[4:5], exec
	s_cselect_b32 s27, s43, s49
	s_cselect_b32 s69, s42, s48
	s_ashr_i32 s25, s24, 31
	s_lshl_b64 s[44:45], s[24:25], 19
	s_add_u32 s44, s29, s44
	s_addc_u32 s45, s31, s45
	s_and_b64 s[52:53], s[4:5], exec
	s_cselect_b32 s25, s45, s51
	s_cselect_b32 s70, s44, s50
	s_add_u32 s48, s48, 0x40080
	s_addc_u32 s49, s49, 0
	s_add_u32 s71, s50, 0x100
	s_addc_u32 s72, s51, 0
	s_mov_b32 s73, -2
	s_waitcnt vmcnt(0)
	ds_read_b128 v[160:163], v155
	ds_read_b128 v[164:167], v155 offset:1024
	ds_read_b128 v[168:171], v155 offset:2048
	ds_read_b128 v[172:175], v155 offset:3072
	ds_read_b128 v[176:179], v156
	ds_read_b128 v[180:183], v156 offset:1024
	ds_read_b128 v[184:187], v156 offset:2048
	ds_read_b128 v[188:191], v156 offset:3072
	s_add_u32 s50, s48, 0xfffc0080
	s_addc_u32 s51, s49, -1
	s_cmp_eq_u32 s73, 12
	s_cselect_b32 s53, s27, s51
	s_cselect_b32 s52, s69, s50
	s_cselect_b32 s51, s25, s72
	s_cselect_b32 s50, s70, s71
	v_lshl_add_u64 v[148:149], s[48:49], 0, v[140:141]
	s_add_i32 m0, s57, 0xc000
	ds_read_b128 v[192:195], v157
	ds_read_b128 v[196:199], v157 offset:1024
	ds_read_b128 v[200:203], v157 offset:2048
	ds_read_b128 v[204:207], v157 offset:3072
	ds_read_b128 v[208:211], v157 offset:4096
	ds_read_b128 v[212:215], v157 offset:5120
	ds_read_b128 v[216:219], v157 offset:6144
	ds_read_b128 v[220:223], v157 offset:7168
	global_load_lds_dwordx4 v[148:149], off
	v_lshl_add_u64 v[148:149], s[48:49], 0, v[142:143]
	s_add_i32 m0, s57, 0xe000
	s_nop 0
	global_load_lds_dwordx4 v[148:149], off
	s_waitcnt vmcnt(8)
	s_waitcnt lgkmcnt(0)
	s_setprio 1
	s_barrier
	v_mfma_f32_16x16x32_bf16 v[118:121], v[160:163], v[192:195], 0
	v_mfma_f32_16x16x32_bf16 v[114:117], v[168:171], v[192:195], 0
	v_mfma_f32_16x16x32_bf16 v[106:109], v[160:163], v[200:203], 0
	v_mfma_f32_16x16x32_bf16 v[98:101], v[168:171], v[200:203], 0
	v_mfma_f32_16x16x32_bf16 v[90:93], v[160:163], v[208:211], 0
	v_mfma_f32_16x16x32_bf16 v[82:85], v[168:171], v[208:211], 0
	v_mfma_f32_16x16x32_bf16 v[74:77], v[160:163], v[216:219], 0
	v_mfma_f32_16x16x32_bf16 v[66:69], v[168:171], v[216:219], 0
	v_mfma_f32_16x16x32_bf16 v[118:121], v[164:167], v[196:199], v[118:121]
	v_mfma_f32_16x16x32_bf16 v[114:117], v[172:175], v[196:199], v[114:117]
	v_mfma_f32_16x16x32_bf16 v[106:109], v[164:167], v[204:207], v[106:109]
	v_mfma_f32_16x16x32_bf16 v[98:101], v[172:175], v[204:207], v[98:101]
	v_mfma_f32_16x16x32_bf16 v[90:93], v[164:167], v[212:215], v[90:93]
	v_mfma_f32_16x16x32_bf16 v[82:85], v[172:175], v[212:215], v[82:85]
	v_mfma_f32_16x16x32_bf16 v[74:77], v[164:167], v[220:223], v[74:77]
	v_mfma_f32_16x16x32_bf16 v[66:69], v[172:175], v[220:223], v[66:69]
	s_setprio 0
	s_setprio 1
	v_mfma_f32_16x16x32_bf16 v[126:129], v[176:179], v[192:195], 0
	v_mfma_f32_16x16x32_bf16 v[122:125], v[184:187], v[192:195], 0
	v_mfma_f32_16x16x32_bf16 v[110:113], v[176:179], v[200:203], 0
	v_mfma_f32_16x16x32_bf16 v[102:105], v[184:187], v[200:203], 0
	v_mfma_f32_16x16x32_bf16 v[94:97], v[176:179], v[208:211], 0
	v_mfma_f32_16x16x32_bf16 v[86:89], v[184:187], v[208:211], 0
	v_mfma_f32_16x16x32_bf16 v[78:81], v[176:179], v[216:219], 0
	v_mfma_f32_16x16x32_bf16 v[70:73], v[184:187], v[216:219], 0
	v_mfma_f32_16x16x32_bf16 v[126:129], v[180:183], v[196:199], v[126:129]
	v_mfma_f32_16x16x32_bf16 v[122:125], v[188:191], v[196:199], v[122:125]
	v_mfma_f32_16x16x32_bf16 v[110:113], v[180:183], v[204:207], v[110:113]
	v_mfma_f32_16x16x32_bf16 v[102:105], v[188:191], v[204:207], v[102:105]
	v_mfma_f32_16x16x32_bf16 v[94:97], v[180:183], v[212:215], v[94:97]
	v_mfma_f32_16x16x32_bf16 v[86:89], v[188:191], v[212:215], v[86:89]
	v_mfma_f32_16x16x32_bf16 v[78:81], v[180:183], v[220:223], v[78:81]
	v_mfma_f32_16x16x32_bf16 v[70:73], v[188:191], v[220:223], v[70:73]
	s_setprio 0
	s_barrier
	s_add_i32 s74, s66, s54
	v_lshl_add_u64 v[148:149], s[50:51], 0, v[134:135]
	s_mov_b32 m0, s74
	ds_read_b128 v[192:195], v157 offset:16384
	ds_read_b128 v[196:199], v157 offset:17408
	ds_read_b128 v[200:203], v157 offset:18432
	ds_read_b128 v[204:207], v157 offset:19456
	ds_read_b128 v[208:211], v157 offset:20480
	ds_read_b128 v[212:215], v157 offset:21504
	ds_read_b128 v[216:219], v157 offset:22528
	ds_read_b128 v[220:223], v157 offset:23552
	global_load_lds_dwordx4 v[148:149], off
	s_add_i32 m0, s74, 0x2000
	s_add_u32 s74, s50, 0x40000
	v_lshl_add_u64 v[224:225], s[50:51], 0, v[130:131]
	s_addc_u32 s75, s51, 0
	s_add_i32 s76, s67, s54
	global_load_lds_dwordx4 v[224:225], off
	v_lshl_add_u64 v[226:227], s[74:75], 0, v[134:135]
	s_mov_b32 m0, s76
	v_lshl_add_u64 v[228:229], s[52:53], 0, v[132:133]
	global_load_lds_dwordx4 v[226:227], off
	v_lshl_add_u64 v[226:227], s[74:75], 0, v[130:131]
	s_add_i32 m0, s76, 0x2000
	s_nop 0
	global_load_lds_dwordx4 v[226:227], off
	v_lshl_add_u64 v[226:227], s[52:53], 0, v[136:137]
	s_mov_b32 m0, s57
	s_nop 0
	global_load_lds_dwordx4 v[226:227], off
	s_mov_b32 m0, s58
	s_nop 0
	global_load_lds_dwordx4 v[228:229], off
	s_waitcnt vmcnt(8)
	s_waitcnt lgkmcnt(0)
	s_setprio 1
	s_barrier
	v_mfma_f32_16x16x32_bf16 v[58:61], v[160:163], v[192:195], 0
	v_mfma_f32_16x16x32_bf16 v[50:53], v[168:171], v[192:195], 0
	v_mfma_f32_16x16x32_bf16 v[42:45], v[160:163], v[200:203], 0
	v_mfma_f32_16x16x32_bf16 v[34:37], v[168:171], v[200:203], 0
	v_mfma_f32_16x16x32_bf16 v[26:29], v[160:163], v[208:211], 0
	v_mfma_f32_16x16x32_bf16 v[18:21], v[168:171], v[208:211], 0
	v_mfma_f32_16x16x32_bf16 v[10:13], v[160:163], v[216:219], 0
	v_mfma_f32_16x16x32_bf16 v[6:9], v[168:171], v[216:219], 0
	v_mfma_f32_16x16x32_bf16 v[58:61], v[164:167], v[196:199], v[58:61]
	v_mfma_f32_16x16x32_bf16 v[50:53], v[172:175], v[196:199], v[50:53]
	v_mfma_f32_16x16x32_bf16 v[42:45], v[164:167], v[204:207], v[42:45]
	v_mfma_f32_16x16x32_bf16 v[34:37], v[172:175], v[204:207], v[34:37]
	v_mfma_f32_16x16x32_bf16 v[26:29], v[164:167], v[212:215], v[26:29]
	v_mfma_f32_16x16x32_bf16 v[18:21], v[172:175], v[212:215], v[18:21]
	v_mfma_f32_16x16x32_bf16 v[10:13], v[164:167], v[220:223], v[10:13]
	v_mfma_f32_16x16x32_bf16 v[6:9], v[172:175], v[220:223], v[6:9]
	s_setprio 0
	s_setprio 1
	v_mfma_f32_16x16x32_bf16 v[62:65], v[176:179], v[192:195], 0
	v_mfma_f32_16x16x32_bf16 v[54:57], v[184:187], v[192:195], 0
	v_mfma_f32_16x16x32_bf16 v[46:49], v[176:179], v[200:203], 0
	v_mfma_f32_16x16x32_bf16 v[38:41], v[184:187], v[200:203], 0
	v_mfma_f32_16x16x32_bf16 v[30:33], v[176:179], v[208:211], 0
	v_mfma_f32_16x16x32_bf16 v[22:25], v[184:187], v[208:211], 0
	v_mfma_f32_16x16x32_bf16 v[14:17], v[176:179], v[216:219], 0
	v_mfma_f32_16x16x32_bf16 v[2:5], v[184:187], v[216:219], 0
	v_mfma_f32_16x16x32_bf16 v[62:65], v[180:183], v[196:199], v[62:65]
	v_mfma_f32_16x16x32_bf16 v[54:57], v[188:191], v[196:199], v[54:57]
	v_mfma_f32_16x16x32_bf16 v[46:49], v[180:183], v[204:207], v[46:49]
	v_mfma_f32_16x16x32_bf16 v[38:41], v[188:191], v[204:207], v[38:41]
	v_mfma_f32_16x16x32_bf16 v[30:33], v[180:183], v[212:215], v[30:33]
	v_mfma_f32_16x16x32_bf16 v[22:25], v[188:191], v[212:215], v[22:25]
	v_mfma_f32_16x16x32_bf16 v[14:17], v[180:183], v[220:223], v[14:17]
	v_mfma_f32_16x16x32_bf16 v[2:5], v[188:191], v[220:223], v[2:5]
	s_setprio 0
	s_barrier
	s_add_i32 s74, 0, 0x18000
	v_add_u32_e32 v159, s74, v151
	s_add_i32 s75, 0, 0x1c000
	ds_read_b128 v[160:163], v159
	ds_read_b128 v[164:167], v159 offset:1024
	ds_read_b128 v[168:171], v159 offset:2048
	ds_read_b128 v[172:175], v159 offset:3072
	v_add_u32_e32 v159, s75, v151
	ds_read_b128 v[176:179], v159
	ds_read_b128 v[180:183], v159 offset:1024
	ds_read_b128 v[184:187], v159 offset:2048
	ds_read_b128 v[188:191], v159 offset:3072
	s_add_u32 s52, s52, 0x40000
	s_addc_u32 s53, s53, 0
	s_mov_b32 m0, s59
	v_lshl_add_u64 v[230:231], s[52:53], 0, v[136:137]
	ds_read_b128 v[192:195], v157 offset:32768
	ds_read_b128 v[196:199], v157 offset:33792
	ds_read_b128 v[200:203], v157 offset:34816
	ds_read_b128 v[204:207], v157 offset:35840
	ds_read_b128 v[208:211], v157 offset:36864
	ds_read_b128 v[212:215], v157 offset:37888
	ds_read_b128 v[216:219], v157 offset:38912
	ds_read_b128 v[220:223], v157 offset:39936
	global_load_lds_dwordx4 v[230:231], off
	v_lshl_add_u64 v[230:231], s[52:53], 0, v[132:133]
	s_mov_b32 m0, s60
	s_nop 0
	global_load_lds_dwordx4 v[230:231], off
	s_waitcnt vmcnt(8)
	s_waitcnt lgkmcnt(0)
	s_setprio 1
	s_barrier
	v_mfma_f32_16x16x32_bf16 v[118:121], v[160:163], v[192:195], v[118:121]
	v_mfma_f32_16x16x32_bf16 v[114:117], v[168:171], v[192:195], v[114:117]
	v_mfma_f32_16x16x32_bf16 v[106:109], v[160:163], v[200:203], v[106:109]
	v_mfma_f32_16x16x32_bf16 v[98:101], v[168:171], v[200:203], v[98:101]
	v_mfma_f32_16x16x32_bf16 v[90:93], v[160:163], v[208:211], v[90:93]
	v_mfma_f32_16x16x32_bf16 v[82:85], v[168:171], v[208:211], v[82:85]
	v_mfma_f32_16x16x32_bf16 v[74:77], v[160:163], v[216:219], v[74:77]
	v_mfma_f32_16x16x32_bf16 v[66:69], v[168:171], v[216:219], v[66:69]
	v_mfma_f32_16x16x32_bf16 v[118:121], v[164:167], v[196:199], v[118:121]
	v_mfma_f32_16x16x32_bf16 v[114:117], v[172:175], v[196:199], v[114:117]
	v_mfma_f32_16x16x32_bf16 v[106:109], v[164:167], v[204:207], v[106:109]
	v_mfma_f32_16x16x32_bf16 v[98:101], v[172:175], v[204:207], v[98:101]
	v_mfma_f32_16x16x32_bf16 v[90:93], v[164:167], v[212:215], v[90:93]
	v_mfma_f32_16x16x32_bf16 v[82:85], v[172:175], v[212:215], v[82:85]
	v_mfma_f32_16x16x32_bf16 v[74:77], v[164:167], v[220:223], v[74:77]
	v_mfma_f32_16x16x32_bf16 v[66:69], v[172:175], v[220:223], v[66:69]
	s_setprio 0
	s_setprio 1
	v_mfma_f32_16x16x32_bf16 v[126:129], v[176:179], v[192:195], v[126:129]
	v_mfma_f32_16x16x32_bf16 v[122:125], v[184:187], v[192:195], v[122:125]
	v_mfma_f32_16x16x32_bf16 v[110:113], v[176:179], v[200:203], v[110:113]
	v_mfma_f32_16x16x32_bf16 v[102:105], v[184:187], v[200:203], v[102:105]
	v_mfma_f32_16x16x32_bf16 v[94:97], v[176:179], v[208:211], v[94:97]
	v_mfma_f32_16x16x32_bf16 v[86:89], v[184:187], v[208:211], v[86:89]
	v_mfma_f32_16x16x32_bf16 v[78:81], v[176:179], v[216:219], v[78:81]
	v_mfma_f32_16x16x32_bf16 v[70:73], v[184:187], v[216:219], v[70:73]
	v_mfma_f32_16x16x32_bf16 v[126:129], v[180:183], v[196:199], v[126:129]
	v_mfma_f32_16x16x32_bf16 v[122:125], v[188:191], v[196:199], v[122:125]
	v_mfma_f32_16x16x32_bf16 v[110:113], v[180:183], v[204:207], v[110:113]
	v_mfma_f32_16x16x32_bf16 v[102:105], v[188:191], v[204:207], v[102:105]
	v_mfma_f32_16x16x32_bf16 v[94:97], v[180:183], v[212:215], v[94:97]
	v_mfma_f32_16x16x32_bf16 v[86:89], v[188:191], v[212:215], v[86:89]
	v_mfma_f32_16x16x32_bf16 v[78:81], v[180:183], v[220:223], v[78:81]
	v_mfma_f32_16x16x32_bf16 v[70:73], v[188:191], v[220:223], v[70:73]
	s_setprio 0
	s_barrier
	s_add_i32 s52, s74, s54
	v_lshl_add_u64 v[148:149], v[148:149], 0, s[14:15]
	s_mov_b32 m0, s52
	ds_read_b128 v[192:195], v157 offset:49152
	ds_read_b128 v[196:199], v157 offset:50176
	ds_read_b128 v[200:203], v157 offset:51200
	ds_read_b128 v[204:207], v157 offset:52224
	ds_read_b128 v[208:211], v157 offset:53248
	ds_read_b128 v[212:215], v157 offset:54272
	ds_read_b128 v[216:219], v157 offset:55296
	ds_read_b128 v[220:223], v157 offset:56320
	global_load_lds_dwordx4 v[148:149], off
	s_add_i32 m0, s52, 0x2000
	s_add_u32 s50, s50, 0x40080
	v_lshl_add_u64 v[148:149], v[224:225], 0, s[14:15]
	s_addc_u32 s51, s51, 0
	s_add_i32 s52, s75, s54
	global_load_lds_dwordx4 v[148:149], off
	v_lshl_add_u64 v[148:149], s[50:51], 0, v[134:135]
	s_mov_b32 m0, s52
	s_nop 0
	global_load_lds_dwordx4 v[148:149], off
	v_lshl_add_u64 v[148:149], s[50:51], 0, v[130:131]
	s_add_i32 m0, s52, 0x2000
	s_nop 0
	global_load_lds_dwordx4 v[148:149], off
	v_lshl_add_u64 v[148:149], v[226:227], 0, s[14:15]
	s_mov_b32 m0, s62
	s_nop 0
	global_load_lds_dwordx4 v[148:149], off
	v_lshl_add_u64 v[148:149], v[228:229], 0, s[14:15]
	s_mov_b32 m0, s63
	s_nop 0
	global_load_lds_dwordx4 v[148:149], off
	s_waitcnt vmcnt(8)
	s_waitcnt lgkmcnt(0)
	s_setprio 1
	s_barrier
	v_mfma_f32_16x16x32_bf16 v[58:61], v[160:163], v[192:195], v[58:61]
	v_mfma_f32_16x16x32_bf16 v[50:53], v[168:171], v[192:195], v[50:53]
	v_mfma_f32_16x16x32_bf16 v[42:45], v[160:163], v[200:203], v[42:45]
	v_mfma_f32_16x16x32_bf16 v[34:37], v[168:171], v[200:203], v[34:37]
	v_mfma_f32_16x16x32_bf16 v[26:29], v[160:163], v[208:211], v[26:29]
	v_mfma_f32_16x16x32_bf16 v[18:21], v[168:171], v[208:211], v[18:21]
	v_mfma_f32_16x16x32_bf16 v[10:13], v[160:163], v[216:219], v[10:13]
	v_mfma_f32_16x16x32_bf16 v[6:9], v[168:171], v[216:219], v[6:9]
	v_mfma_f32_16x16x32_bf16 v[58:61], v[164:167], v[196:199], v[58:61]
	v_mfma_f32_16x16x32_bf16 v[50:53], v[172:175], v[196:199], v[50:53]
	v_mfma_f32_16x16x32_bf16 v[42:45], v[164:167], v[204:207], v[42:45]
	v_mfma_f32_16x16x32_bf16 v[34:37], v[172:175], v[204:207], v[34:37]
	v_mfma_f32_16x16x32_bf16 v[26:29], v[164:167], v[212:215], v[26:29]
	v_mfma_f32_16x16x32_bf16 v[18:21], v[172:175], v[212:215], v[18:21]
	v_mfma_f32_16x16x32_bf16 v[10:13], v[164:167], v[220:223], v[10:13]
	v_mfma_f32_16x16x32_bf16 v[6:9], v[172:175], v[220:223], v[6:9]
	s_setprio 0
	s_setprio 1
	v_mfma_f32_16x16x32_bf16 v[62:65], v[176:179], v[192:195], v[62:65]
	v_mfma_f32_16x16x32_bf16 v[54:57], v[184:187], v[192:195], v[54:57]
	v_mfma_f32_16x16x32_bf16 v[46:49], v[176:179], v[200:203], v[46:49]
	v_mfma_f32_16x16x32_bf16 v[38:41], v[184:187], v[200:203], v[38:41]
	v_mfma_f32_16x16x32_bf16 v[30:33], v[176:179], v[208:211], v[30:33]
	v_mfma_f32_16x16x32_bf16 v[22:25], v[184:187], v[208:211], v[22:25]
	v_mfma_f32_16x16x32_bf16 v[14:17], v[176:179], v[216:219], v[14:17]
	v_mfma_f32_16x16x32_bf16 v[2:5], v[184:187], v[216:219], v[2:5]
	v_mfma_f32_16x16x32_bf16 v[62:65], v[180:183], v[196:199], v[62:65]
	v_mfma_f32_16x16x32_bf16 v[54:57], v[188:191], v[196:199], v[54:57]
	v_mfma_f32_16x16x32_bf16 v[46:49], v[180:183], v[204:207], v[46:49]
	v_mfma_f32_16x16x32_bf16 v[38:41], v[188:191], v[204:207], v[38:41]
	v_mfma_f32_16x16x32_bf16 v[30:33], v[180:183], v[212:215], v[30:33]
	v_mfma_f32_16x16x32_bf16 v[22:25], v[188:191], v[212:215], v[22:25]
	v_mfma_f32_16x16x32_bf16 v[14:17], v[180:183], v[220:223], v[14:17]
	v_mfma_f32_16x16x32_bf16 v[2:5], v[188:191], v[220:223], v[2:5]
	s_setprio 0
	s_barrier
	s_add_i32 s73, s73, 2
	s_add_u32 s48, s48, 0x100
	s_addc_u32 s49, s49, 0
	s_add_u32 s71, s71, 0x100
	s_addc_u32 s72, s72, 0
	s_cmp_gt_u32 s73, 13
	s_cbranch_scc0 .LBB0_840
	s_branch .Lz_post_p6

.Lz_post_p6:
	s_lshl_b32 s25, s46, 8
	v_add_u32_e32 v148, s25, v150
	v_ashrrev_i32_e32 v149, 31, v148
	v_lshl_add_u64 v[160:161], v[148:149], 2, s[10:11]
	global_load_dword v149, v[160:161], off
	global_load_dword v232, v[160:161], off offset:64
	global_load_dword v233, v[160:161], off offset:128
	global_load_dword v234, v[160:161], off offset:192
	global_load_dword v235, v[160:161], off offset:512
	global_load_dword v236, v[160:161], off offset:576
	global_load_dword v237, v[160:161], off offset:640
	global_load_dword v238, v[160:161], off offset:704
	s_and_b64 vcc, exec, s[16:17]
	s_cbranch_vccz .LBB0_843
	s_barrier

.LBB0_938:
	s_add_u32 s69, s46, 0x100
	s_addc_u32 s70, s47, 0
	s_mov_b32 s71, -2
	s_waitcnt vmcnt(0)
	ds_read_b128 v[122:125], v245
	ds_read_b128 v[126:129], v245 offset:1024
	ds_read_b128 v[130:133], v245 offset:2048
	ds_read_b128 v[134:137], v245 offset:3072
	ds_read_b128 v[138:141], v246
	ds_read_b128 v[142:145], v246 offset:1024
	ds_read_b128 v[146:149], v246 offset:2048
	ds_read_b128 v[158:161], v246 offset:3072
	s_add_u32 s46, s44, 0x100
	s_addc_u32 s47, s45, 0
	s_cmp_eq_u32 s71, 40
	s_cselect_b32 s51, s9, s47
	s_cselect_b32 s50, s8, s46
	s_cselect_b32 s49, s43, s70
	s_cselect_b32 s48, s42, s69
	v_lshl_add_u64 v[210:211], s[44:45], 0, v[206:207]
	s_add_i32 m0, s53, 0xc000
	ds_read_b128 v[162:165], v247
	ds_read_b128 v[166:169], v247 offset:1024
	ds_read_b128 v[170:173], v247 offset:2048
	ds_read_b128 v[174:177], v247 offset:3072
	ds_read_b128 v[178:181], v247 offset:4096
	ds_read_b128 v[182:185], v247 offset:5120
	ds_read_b128 v[186:189], v247 offset:6144
	ds_read_b128 v[190:193], v247 offset:7168
	global_load_lds_dwordx4 v[210:211], off
	v_lshl_add_u64 v[210:211], s[44:45], 0, v[208:209]
	s_add_i32 m0, s53, 0xe000
	s_nop 0
	global_load_lds_dwordx4 v[210:211], off
	s_waitcnt vmcnt(8)
	s_waitcnt lgkmcnt(0)
	s_setprio 1
	s_barrier
	v_mfma_f32_16x16x32_bf16 v[154:157], v[122:125], v[162:165], 0
	v_mfma_f32_16x16x32_bf16 v[150:153], v[130:133], v[162:165], 0
	v_mfma_f32_16x16x32_bf16 v[110:113], v[122:125], v[170:173], 0
	v_mfma_f32_16x16x32_bf16 v[106:109], v[130:133], v[170:173], 0
	v_mfma_f32_16x16x32_bf16 v[94:97], v[122:125], v[178:181], 0
	v_mfma_f32_16x16x32_bf16 v[90:93], v[130:133], v[178:181], 0
	v_mfma_f32_16x16x32_bf16 v[78:81], v[122:125], v[186:189], 0
	v_mfma_f32_16x16x32_bf16 v[74:77], v[130:133], v[186:189], 0
	v_mfma_f32_16x16x32_bf16 v[154:157], v[126:129], v[166:169], v[154:157]
	v_mfma_f32_16x16x32_bf16 v[150:153], v[134:137], v[166:169], v[150:153]
	v_mfma_f32_16x16x32_bf16 v[110:113], v[126:129], v[174:177], v[110:113]
	v_mfma_f32_16x16x32_bf16 v[106:109], v[134:137], v[174:177], v[106:109]
	v_mfma_f32_16x16x32_bf16 v[94:97], v[126:129], v[182:185], v[94:97]
	v_mfma_f32_16x16x32_bf16 v[90:93], v[134:137], v[182:185], v[90:93]
	v_mfma_f32_16x16x32_bf16 v[78:81], v[126:129], v[190:193], v[78:81]
	v_mfma_f32_16x16x32_bf16 v[74:77], v[134:137], v[190:193], v[74:77]
	s_setprio 0
	s_setprio 1
	v_mfma_f32_16x16x32_bf16 v[118:121], v[138:141], v[162:165], 0
	v_mfma_f32_16x16x32_bf16 v[114:117], v[146:149], v[162:165], 0
	v_mfma_f32_16x16x32_bf16 v[102:105], v[138:141], v[170:173], 0
	v_mfma_f32_16x16x32_bf16 v[98:101], v[146:149], v[170:173], 0
	v_mfma_f32_16x16x32_bf16 v[86:89], v[138:141], v[178:181], 0
	v_mfma_f32_16x16x32_bf16 v[82:85], v[146:149], v[178:181], 0
	v_mfma_f32_16x16x32_bf16 v[70:73], v[138:141], v[186:189], 0
	v_mfma_f32_16x16x32_bf16 v[66:69], v[146:149], v[186:189], 0
	v_mfma_f32_16x16x32_bf16 v[118:121], v[142:145], v[166:169], v[118:121]
	v_mfma_f32_16x16x32_bf16 v[114:117], v[158:161], v[166:169], v[114:117]
	v_mfma_f32_16x16x32_bf16 v[102:105], v[142:145], v[174:177], v[102:105]
	v_mfma_f32_16x16x32_bf16 v[98:101], v[158:161], v[174:177], v[98:101]
	v_mfma_f32_16x16x32_bf16 v[86:89], v[142:145], v[182:185], v[86:89]
	v_mfma_f32_16x16x32_bf16 v[82:85], v[158:161], v[182:185], v[82:85]
	v_mfma_f32_16x16x32_bf16 v[70:73], v[142:145], v[190:193], v[70:73]
	v_mfma_f32_16x16x32_bf16 v[66:69], v[158:161], v[190:193], v[66:69]
	s_setprio 0
	s_barrier
	s_add_i32 s44, s63, s52
	v_lshl_add_u64 v[210:211], s[48:49], 0, v[196:197]
	s_mov_b32 m0, s44
	ds_read_b128 v[162:165], v247 offset:16384
	ds_read_b128 v[166:169], v247 offset:17408
	ds_read_b128 v[170:173], v247 offset:18432
	ds_read_b128 v[174:177], v247 offset:19456
	ds_read_b128 v[178:181], v247 offset:20480
	ds_read_b128 v[182:185], v247 offset:21504
	ds_read_b128 v[186:189], v247 offset:22528
	ds_read_b128 v[190:193], v247 offset:23552
	global_load_lds_dwordx4 v[210:211], off
	s_add_i32 m0, s44, 0x2000
	s_add_u32 s44, s48, 0xb0000
	v_lshl_add_u64 v[212:213], s[48:49], 0, v[200:201]
	s_addc_u32 s45, s49, 0
	s_add_i32 s72, s64, s52
	global_load_lds_dwordx4 v[212:213], off
	v_lshl_add_u64 v[214:215], s[44:45], 0, v[196:197]
	s_mov_b32 m0, s72
	v_lshl_add_u64 v[216:217], s[50:51], 0, v[198:199]
	global_load_lds_dwordx4 v[214:215], off
	v_lshl_add_u64 v[214:215], s[44:45], 0, v[200:201]
	s_add_i32 m0, s72, 0x2000
	s_nop 0
	global_load_lds_dwordx4 v[214:215], off
	v_lshl_add_u64 v[214:215], s[50:51], 0, v[194:195]
	s_mov_b32 m0, s53
	s_nop 0
	global_load_lds_dwordx4 v[214:215], off
	s_mov_b32 m0, s54
	s_nop 0
	global_load_lds_dwordx4 v[216:217], off
	s_waitcnt vmcnt(8)
	s_waitcnt lgkmcnt(0)
	s_setprio 1
	s_barrier
	v_mfma_f32_16x16x32_bf16 v[62:65], v[122:125], v[162:165], 0
	v_mfma_f32_16x16x32_bf16 v[58:61], v[130:133], v[162:165], 0
	v_mfma_f32_16x16x32_bf16 v[46:49], v[122:125], v[170:173], 0
	v_mfma_f32_16x16x32_bf16 v[42:45], v[130:133], v[170:173], 0
	v_mfma_f32_16x16x32_bf16 v[30:33], v[122:125], v[178:181], 0
	v_mfma_f32_16x16x32_bf16 v[26:29], v[130:133], v[178:181], 0
	v_mfma_f32_16x16x32_bf16 v[14:17], v[122:125], v[186:189], 0
	v_mfma_f32_16x16x32_bf16 v[10:13], v[130:133], v[186:189], 0
	v_mfma_f32_16x16x32_bf16 v[62:65], v[126:129], v[166:169], v[62:65]
	v_mfma_f32_16x16x32_bf16 v[58:61], v[134:137], v[166:169], v[58:61]
	v_mfma_f32_16x16x32_bf16 v[46:49], v[126:129], v[174:177], v[46:49]
	v_mfma_f32_16x16x32_bf16 v[42:45], v[134:137], v[174:177], v[42:45]
	v_mfma_f32_16x16x32_bf16 v[30:33], v[126:129], v[182:185], v[30:33]
	v_mfma_f32_16x16x32_bf16 v[26:29], v[134:137], v[182:185], v[26:29]
	v_mfma_f32_16x16x32_bf16 v[14:17], v[126:129], v[190:193], v[14:17]
	v_mfma_f32_16x16x32_bf16 v[10:13], v[134:137], v[190:193], v[10:13]
	s_setprio 0
	s_setprio 1
	v_mfma_f32_16x16x32_bf16 v[54:57], v[138:141], v[162:165], 0
	v_mfma_f32_16x16x32_bf16 v[50:53], v[146:149], v[162:165], 0
	v_mfma_f32_16x16x32_bf16 v[38:41], v[138:141], v[170:173], 0
	v_mfma_f32_16x16x32_bf16 v[34:37], v[146:149], v[170:173], 0
	v_mfma_f32_16x16x32_bf16 v[22:25], v[138:141], v[178:181], 0
	v_mfma_f32_16x16x32_bf16 v[18:21], v[146:149], v[178:181], 0
	v_mfma_f32_16x16x32_bf16 v[6:9], v[138:141], v[186:189], 0
	v_mfma_f32_16x16x32_bf16 v[2:5], v[146:149], v[186:189], 0
	v_mfma_f32_16x16x32_bf16 v[54:57], v[142:145], v[166:169], v[54:57]
	v_mfma_f32_16x16x32_bf16 v[50:53], v[158:161], v[166:169], v[50:53]
	v_mfma_f32_16x16x32_bf16 v[38:41], v[142:145], v[174:177], v[38:41]
	v_mfma_f32_16x16x32_bf16 v[34:37], v[158:161], v[174:177], v[34:37]
	v_mfma_f32_16x16x32_bf16 v[22:25], v[142:145], v[182:185], v[22:25]
	v_mfma_f32_16x16x32_bf16 v[18:21], v[158:161], v[182:185], v[18:21]
	v_mfma_f32_16x16x32_bf16 v[6:9], v[142:145], v[190:193], v[6:9]
	v_mfma_f32_16x16x32_bf16 v[2:5], v[158:161], v[190:193], v[2:5]
	s_setprio 0
	s_barrier
	s_add_i32 s72, 0, 0x18000
	s_add_i32 s73, 0, 0x1c000
	v_add_u32_e32 v134, s72, v244
	v_add_u32_e32 v158, s73, v244
	ds_read_b128 v[122:125], v134
	ds_read_b128 v[126:129], v134 offset:1024
	ds_read_b128 v[130:133], v134 offset:2048
	ds_read_b128 v[134:137], v134 offset:3072
	ds_read_b128 v[138:141], v158
	ds_read_b128 v[142:145], v158 offset:1024
	ds_read_b128 v[146:149], v158 offset:2048
	ds_read_b128 v[158:161], v158 offset:3072
	s_add_u32 s44, s50, 0xb0000
	s_addc_u32 s45, s51, 0
	s_mov_b32 m0, s55
	v_lshl_add_u64 v[218:219], s[44:45], 0, v[194:195]
	ds_read_b128 v[162:165], v247 offset:32768
	ds_read_b128 v[166:169], v247 offset:33792
	ds_read_b128 v[170:173], v247 offset:34816
	ds_read_b128 v[174:177], v247 offset:35840
	ds_read_b128 v[178:181], v247 offset:36864
	ds_read_b128 v[182:185], v247 offset:37888
	ds_read_b128 v[186:189], v247 offset:38912
	ds_read_b128 v[190:193], v247 offset:39936
	global_load_lds_dwordx4 v[218:219], off
	v_lshl_add_u64 v[218:219], s[44:45], 0, v[198:199]
	s_mov_b32 m0, s56
	s_nop 0
	global_load_lds_dwordx4 v[218:219], off
	s_waitcnt vmcnt(8)
	s_waitcnt lgkmcnt(0)
	s_setprio 1
	s_barrier
	v_mfma_f32_16x16x32_bf16 v[154:157], v[122:125], v[162:165], v[154:157]
	v_mfma_f32_16x16x32_bf16 v[150:153], v[130:133], v[162:165], v[150:153]
	v_mfma_f32_16x16x32_bf16 v[110:113], v[122:125], v[170:173], v[110:113]
	v_mfma_f32_16x16x32_bf16 v[106:109], v[130:133], v[170:173], v[106:109]
	v_mfma_f32_16x16x32_bf16 v[94:97], v[122:125], v[178:181], v[94:97]
	v_mfma_f32_16x16x32_bf16 v[90:93], v[130:133], v[178:181], v[90:93]
	v_mfma_f32_16x16x32_bf16 v[78:81], v[122:125], v[186:189], v[78:81]
	v_mfma_f32_16x16x32_bf16 v[74:77], v[130:133], v[186:189], v[74:77]
	v_mfma_f32_16x16x32_bf16 v[154:157], v[126:129], v[166:169], v[154:157]
	v_mfma_f32_16x16x32_bf16 v[150:153], v[134:137], v[166:169], v[150:153]
	v_mfma_f32_16x16x32_bf16 v[110:113], v[126:129], v[174:177], v[110:113]
	v_mfma_f32_16x16x32_bf16 v[106:109], v[134:137], v[174:177], v[106:109]
	v_mfma_f32_16x16x32_bf16 v[94:97], v[126:129], v[182:185], v[94:97]
	v_mfma_f32_16x16x32_bf16 v[90:93], v[134:137], v[182:185], v[90:93]
	v_mfma_f32_16x16x32_bf16 v[78:81], v[126:129], v[190:193], v[78:81]
	v_mfma_f32_16x16x32_bf16 v[74:77], v[134:137], v[190:193], v[74:77]
	s_setprio 0
	s_setprio 1
	v_mfma_f32_16x16x32_bf16 v[118:121], v[138:141], v[162:165], v[118:121]
	v_mfma_f32_16x16x32_bf16 v[114:117], v[146:149], v[162:165], v[114:117]
	v_mfma_f32_16x16x32_bf16 v[102:105], v[138:141], v[170:173], v[102:105]
	v_mfma_f32_16x16x32_bf16 v[98:101], v[146:149], v[170:173], v[98:101]
	v_mfma_f32_16x16x32_bf16 v[86:89], v[138:141], v[178:181], v[86:89]
	v_mfma_f32_16x16x32_bf16 v[82:85], v[146:149], v[178:181], v[82:85]
	v_mfma_f32_16x16x32_bf16 v[70:73], v[138:141], v[186:189], v[70:73]
	v_mfma_f32_16x16x32_bf16 v[66:69], v[146:149], v[186:189], v[66:69]
	v_mfma_f32_16x16x32_bf16 v[118:121], v[142:145], v[166:169], v[118:121]
	v_mfma_f32_16x16x32_bf16 v[114:117], v[158:161], v[166:169], v[114:117]
	v_mfma_f32_16x16x32_bf16 v[102:105], v[142:145], v[174:177], v[102:105]
	v_mfma_f32_16x16x32_bf16 v[98:101], v[158:161], v[174:177], v[98:101]
	v_mfma_f32_16x16x32_bf16 v[86:89], v[142:145], v[182:185], v[86:89]
	v_mfma_f32_16x16x32_bf16 v[82:85], v[158:161], v[182:185], v[82:85]
	v_mfma_f32_16x16x32_bf16 v[70:73], v[142:145], v[190:193], v[70:73]
	v_mfma_f32_16x16x32_bf16 v[66:69], v[158:161], v[190:193], v[66:69]
	s_setprio 0
	s_barrier
	s_add_i32 s44, s72, s52
	v_lshl_add_u64 v[210:211], v[210:211], 0, s[24:25]
	s_mov_b32 m0, s44
	ds_read_b128 v[162:165], v247 offset:49152
	ds_read_b128 v[166:169], v247 offset:50176
	ds_read_b128 v[170:173], v247 offset:51200
	ds_read_b128 v[174:177], v247 offset:52224
	ds_read_b128 v[178:181], v247 offset:53248
	ds_read_b128 v[182:185], v247 offset:54272
	ds_read_b128 v[186:189], v247 offset:55296
	ds_read_b128 v[190:193], v247 offset:56320
	global_load_lds_dwordx4 v[210:211], off
	s_add_i32 m0, s44, 0x2000
	s_add_u32 s44, s48, 0xb0080
	v_lshl_add_u64 v[210:211], v[212:213], 0, s[24:25]
	s_addc_u32 s45, s49, 0
	s_add_i32 s48, s73, s52
	global_load_lds_dwordx4 v[210:211], off
	v_lshl_add_u64 v[210:211], s[44:45], 0, v[196:197]
	s_mov_b32 m0, s48
	s_nop 0
	global_load_lds_dwordx4 v[210:211], off
	v_lshl_add_u64 v[210:211], s[44:45], 0, v[200:201]
	s_add_i32 m0, s48, 0x2000
	s_nop 0
	global_load_lds_dwordx4 v[210:211], off
	v_lshl_add_u64 v[210:211], v[214:215], 0, s[24:25]
	s_mov_b32 m0, s58
	s_nop 0
	global_load_lds_dwordx4 v[210:211], off
	v_lshl_add_u64 v[210:211], v[216:217], 0, s[24:25]
	s_mov_b32 m0, s59
	s_nop 0
	global_load_lds_dwordx4 v[210:211], off
	s_waitcnt vmcnt(8)
	s_waitcnt lgkmcnt(0)
	s_setprio 1
	s_barrier
	v_mfma_f32_16x16x32_bf16 v[62:65], v[122:125], v[162:165], v[62:65]
	v_mfma_f32_16x16x32_bf16 v[58:61], v[130:133], v[162:165], v[58:61]
	v_mfma_f32_16x16x32_bf16 v[46:49], v[122:125], v[170:173], v[46:49]
	v_mfma_f32_16x16x32_bf16 v[42:45], v[130:133], v[170:173], v[42:45]
	v_mfma_f32_16x16x32_bf16 v[30:33], v[122:125], v[178:181], v[30:33]
	v_mfma_f32_16x16x32_bf16 v[26:29], v[130:133], v[178:181], v[26:29]
	v_mfma_f32_16x16x32_bf16 v[14:17], v[122:125], v[186:189], v[14:17]
	v_mfma_f32_16x16x32_bf16 v[10:13], v[130:133], v[186:189], v[10:13]
	v_mfma_f32_16x16x32_bf16 v[62:65], v[126:129], v[166:169], v[62:65]
	v_mfma_f32_16x16x32_bf16 v[58:61], v[134:137], v[166:169], v[58:61]
	v_mfma_f32_16x16x32_bf16 v[46:49], v[126:129], v[174:177], v[46:49]
	v_mfma_f32_16x16x32_bf16 v[42:45], v[134:137], v[174:177], v[42:45]
	v_mfma_f32_16x16x32_bf16 v[30:33], v[126:129], v[182:185], v[30:33]
	v_mfma_f32_16x16x32_bf16 v[26:29], v[134:137], v[182:185], v[26:29]
	v_mfma_f32_16x16x32_bf16 v[14:17], v[126:129], v[190:193], v[14:17]
	v_mfma_f32_16x16x32_bf16 v[10:13], v[134:137], v[190:193], v[10:13]
	s_setprio 0
	s_setprio 1
	v_mfma_f32_16x16x32_bf16 v[54:57], v[138:141], v[162:165], v[54:57]
	v_mfma_f32_16x16x32_bf16 v[50:53], v[146:149], v[162:165], v[50:53]
	v_mfma_f32_16x16x32_bf16 v[38:41], v[138:141], v[170:173], v[38:41]
	v_mfma_f32_16x16x32_bf16 v[34:37], v[146:149], v[170:173], v[34:37]
	v_mfma_f32_16x16x32_bf16 v[22:25], v[138:141], v[178:181], v[22:25]
	v_mfma_f32_16x16x32_bf16 v[18:21], v[146:149], v[178:181], v[18:21]
	v_mfma_f32_16x16x32_bf16 v[6:9], v[138:141], v[186:189], v[6:9]
	v_mfma_f32_16x16x32_bf16 v[2:5], v[146:149], v[186:189], v[2:5]
	v_mfma_f32_16x16x32_bf16 v[54:57], v[142:145], v[166:169], v[54:57]
	v_mfma_f32_16x16x32_bf16 v[50:53], v[158:161], v[166:169], v[50:53]
	v_mfma_f32_16x16x32_bf16 v[38:41], v[142:145], v[174:177], v[38:41]
	v_mfma_f32_16x16x32_bf16 v[34:37], v[158:161], v[174:177], v[34:37]
	v_mfma_f32_16x16x32_bf16 v[22:25], v[142:145], v[182:185], v[22:25]
	v_mfma_f32_16x16x32_bf16 v[18:21], v[158:161], v[182:185], v[18:21]
	v_mfma_f32_16x16x32_bf16 v[6:9], v[142:145], v[190:193], v[6:9]
	v_mfma_f32_16x16x32_bf16 v[2:5], v[158:161], v[190:193], v[2:5]
	s_setprio 0
	s_barrier
	s_add_i32 s71, s71, 2
	s_add_u32 s69, s69, 0x100
	s_addc_u32 s70, s70, 0
	s_cmp_gt_u32 s71, 41
	s_mov_b64 s[44:45], s[46:47]
	s_cbranch_scc0 .LBB0_939
	s_branch .Lz_post_p7

.LBB0_1049:
	s_ashr_i32 s51, s50, 31
	s_lshl_b64 s[52:53], s[50:51], 19
	s_add_u32 s52, s3, s52
	s_addc_u32 s53, s23, s53
	s_and_b64 s[54:55], s[6:7], exec
	s_cselect_b32 s9, s53, s57
	s_cselect_b32 s11, s52, s56
	s_ashr_i32 s49, s48, 31
	s_lshl_b64 s[54:55], s[48:49], 19
	s_add_u32 s54, s29, s54
	s_addc_u32 s55, s31, s55
	s_and_b64 s[60:61], s[6:7], exec
	s_cselect_b32 s49, s55, s59
	s_cselect_b32 s51, s54, s58
	s_add_u32 s56, s56, 0x40080
	s_addc_u32 s57, s57, 0
	s_add_u32 s79, s58, 0x100
	s_addc_u32 s80, s59, 0
	s_mov_b32 s81, -2
	s_waitcnt lgkmcnt(0)
	s_waitcnt vmcnt(0)
	ds_read_b128 v[162:165], v156
	ds_read_b128 v[166:169], v156 offset:1024
	ds_read_b128 v[170:173], v156 offset:2048
	ds_read_b128 v[174:177], v156 offset:3072
	ds_read_b128 v[178:181], v157
	ds_read_b128 v[182:185], v157 offset:1024
	ds_read_b128 v[186:189], v157 offset:2048
	ds_read_b128 v[190:193], v157 offset:3072
	s_add_u32 s58, s56, 0xfffc0080
	s_addc_u32 s59, s57, -1
	s_cmp_eq_u32 s81, 12
	s_cselect_b32 s61, s9, s59
	s_cselect_b32 s60, s11, s58
	s_cselect_b32 s59, s49, s80
	s_cselect_b32 s58, s51, s79
	v_lshl_add_u64 v[150:151], s[56:57], 0, v[142:143]
	s_add_i32 m0, s63, 0xc000
	ds_read_b128 v[194:197], v158
	ds_read_b128 v[198:201], v158 offset:1024
	ds_read_b128 v[202:205], v158 offset:2048
	ds_read_b128 v[206:209], v158 offset:3072
	ds_read_b128 v[210:213], v158 offset:4096
	ds_read_b128 v[214:217], v158 offset:5120
	ds_read_b128 v[218:221], v158 offset:6144
	ds_read_b128 v[222:225], v158 offset:7168
	global_load_lds_dwordx4 v[150:151], off
	v_lshl_add_u64 v[150:151], s[56:57], 0, v[144:145]
	s_add_i32 m0, s63, 0xe000
	s_nop 0
	global_load_lds_dwordx4 v[150:151], off
	s_waitcnt vmcnt(8)
	s_waitcnt lgkmcnt(0)
	s_setprio 1
	s_barrier
	v_mfma_f32_16x16x32_bf16 v[126:129], v[162:165], v[194:197], 0
	v_mfma_f32_16x16x32_bf16 v[122:125], v[170:173], v[194:197], 0
	v_mfma_f32_16x16x32_bf16 v[110:113], v[162:165], v[202:205], 0
	v_mfma_f32_16x16x32_bf16 v[106:109], v[170:173], v[202:205], 0
	v_mfma_f32_16x16x32_bf16 v[94:97], v[162:165], v[210:213], 0
	v_mfma_f32_16x16x32_bf16 v[90:93], v[170:173], v[210:213], 0
	v_mfma_f32_16x16x32_bf16 v[78:81], v[162:165], v[218:221], 0
	v_mfma_f32_16x16x32_bf16 v[74:77], v[170:173], v[218:221], 0
	v_mfma_f32_16x16x32_bf16 v[126:129], v[166:169], v[198:201], v[126:129]
	v_mfma_f32_16x16x32_bf16 v[122:125], v[174:177], v[198:201], v[122:125]
	v_mfma_f32_16x16x32_bf16 v[110:113], v[166:169], v[206:209], v[110:113]
	v_mfma_f32_16x16x32_bf16 v[106:109], v[174:177], v[206:209], v[106:109]
	v_mfma_f32_16x16x32_bf16 v[94:97], v[166:169], v[214:217], v[94:97]
	v_mfma_f32_16x16x32_bf16 v[90:93], v[174:177], v[214:217], v[90:93]
	v_mfma_f32_16x16x32_bf16 v[78:81], v[166:169], v[222:225], v[78:81]
	v_mfma_f32_16x16x32_bf16 v[74:77], v[174:177], v[222:225], v[74:77]
	s_setprio 0
	s_setprio 1
	v_mfma_f32_16x16x32_bf16 v[118:121], v[178:181], v[194:197], 0
	v_mfma_f32_16x16x32_bf16 v[114:117], v[186:189], v[194:197], 0
	v_mfma_f32_16x16x32_bf16 v[102:105], v[178:181], v[202:205], 0
	v_mfma_f32_16x16x32_bf16 v[98:101], v[186:189], v[202:205], 0
	v_mfma_f32_16x16x32_bf16 v[86:89], v[178:181], v[210:213], 0
	v_mfma_f32_16x16x32_bf16 v[82:85], v[186:189], v[210:213], 0
	v_mfma_f32_16x16x32_bf16 v[70:73], v[178:181], v[218:221], 0
	v_mfma_f32_16x16x32_bf16 v[66:69], v[186:189], v[218:221], 0
	v_mfma_f32_16x16x32_bf16 v[118:121], v[182:185], v[198:201], v[118:121]
	v_mfma_f32_16x16x32_bf16 v[114:117], v[190:193], v[198:201], v[114:117]
	v_mfma_f32_16x16x32_bf16 v[102:105], v[182:185], v[206:209], v[102:105]
	v_mfma_f32_16x16x32_bf16 v[98:101], v[190:193], v[206:209], v[98:101]
	v_mfma_f32_16x16x32_bf16 v[86:89], v[182:185], v[214:217], v[86:89]
	v_mfma_f32_16x16x32_bf16 v[82:85], v[190:193], v[214:217], v[82:85]
	v_mfma_f32_16x16x32_bf16 v[70:73], v[182:185], v[222:225], v[70:73]
	v_mfma_f32_16x16x32_bf16 v[66:69], v[190:193], v[222:225], v[66:69]
	s_setprio 0
	s_barrier
	s_add_i32 s82, s73, s62
	v_lshl_add_u64 v[150:151], s[58:59], 0, v[132:133]
	s_mov_b32 m0, s82
	ds_read_b128 v[194:197], v158 offset:16384
	ds_read_b128 v[198:201], v158 offset:17408
	ds_read_b128 v[202:205], v158 offset:18432
	ds_read_b128 v[206:209], v158 offset:19456
	ds_read_b128 v[210:213], v158 offset:20480
	ds_read_b128 v[214:217], v158 offset:21504
	ds_read_b128 v[218:221], v158 offset:22528
	ds_read_b128 v[222:225], v158 offset:23552
	global_load_lds_dwordx4 v[150:151], off
	s_add_i32 m0, s82, 0x2000
	s_add_u32 s82, s58, 0x40000
	v_lshl_add_u64 v[226:227], s[58:59], 0, v[136:137]
	s_addc_u32 s83, s59, 0
	s_add_i32 s84, s74, s62
	global_load_lds_dwordx4 v[226:227], off
	v_lshl_add_u64 v[228:229], s[82:83], 0, v[132:133]
	s_mov_b32 m0, s84
	v_lshl_add_u64 v[230:231], s[60:61], 0, v[134:135]
	global_load_lds_dwordx4 v[228:229], off
	v_lshl_add_u64 v[228:229], s[82:83], 0, v[136:137]
	s_add_i32 m0, s84, 0x2000
	s_nop 0
	global_load_lds_dwordx4 v[228:229], off
	v_lshl_add_u64 v[228:229], s[60:61], 0, v[130:131]
	s_mov_b32 m0, s63
	s_nop 0
	global_load_lds_dwordx4 v[228:229], off
	s_mov_b32 m0, s64
	s_nop 0
	global_load_lds_dwordx4 v[230:231], off
	s_waitcnt vmcnt(8)
	s_waitcnt lgkmcnt(0)
	s_setprio 1
	s_barrier
	v_mfma_f32_16x16x32_bf16 v[62:65], v[162:165], v[194:197], 0
	v_mfma_f32_16x16x32_bf16 v[58:61], v[170:173], v[194:197], 0
	v_mfma_f32_16x16x32_bf16 v[46:49], v[162:165], v[202:205], 0
	v_mfma_f32_16x16x32_bf16 v[42:45], v[170:173], v[202:205], 0
	v_mfma_f32_16x16x32_bf16 v[30:33], v[162:165], v[210:213], 0
	v_mfma_f32_16x16x32_bf16 v[26:29], v[170:173], v[210:213], 0
	v_mfma_f32_16x16x32_bf16 v[14:17], v[162:165], v[218:221], 0
	v_mfma_f32_16x16x32_bf16 v[10:13], v[170:173], v[218:221], 0
	v_mfma_f32_16x16x32_bf16 v[62:65], v[166:169], v[198:201], v[62:65]
	v_mfma_f32_16x16x32_bf16 v[58:61], v[174:177], v[198:201], v[58:61]
	v_mfma_f32_16x16x32_bf16 v[46:49], v[166:169], v[206:209], v[46:49]
	v_mfma_f32_16x16x32_bf16 v[42:45], v[174:177], v[206:209], v[42:45]
	v_mfma_f32_16x16x32_bf16 v[30:33], v[166:169], v[214:217], v[30:33]
	v_mfma_f32_16x16x32_bf16 v[26:29], v[174:177], v[214:217], v[26:29]
	v_mfma_f32_16x16x32_bf16 v[14:17], v[166:169], v[222:225], v[14:17]
	v_mfma_f32_16x16x32_bf16 v[10:13], v[174:177], v[222:225], v[10:13]
	s_setprio 0
	s_setprio 1
	v_mfma_f32_16x16x32_bf16 v[54:57], v[178:181], v[194:197], 0
	v_mfma_f32_16x16x32_bf16 v[50:53], v[186:189], v[194:197], 0
	v_mfma_f32_16x16x32_bf16 v[38:41], v[178:181], v[202:205], 0
	v_mfma_f32_16x16x32_bf16 v[34:37], v[186:189], v[202:205], 0
	v_mfma_f32_16x16x32_bf16 v[22:25], v[178:181], v[210:213], 0
	v_mfma_f32_16x16x32_bf16 v[18:21], v[186:189], v[210:213], 0
	v_mfma_f32_16x16x32_bf16 v[6:9], v[178:181], v[218:221], 0
	v_mfma_f32_16x16x32_bf16 v[2:5], v[186:189], v[218:221], 0
	v_mfma_f32_16x16x32_bf16 v[54:57], v[182:185], v[198:201], v[54:57]
	v_mfma_f32_16x16x32_bf16 v[50:53], v[190:193], v[198:201], v[50:53]
	v_mfma_f32_16x16x32_bf16 v[38:41], v[182:185], v[206:209], v[38:41]
	v_mfma_f32_16x16x32_bf16 v[34:37], v[190:193], v[206:209], v[34:37]
	v_mfma_f32_16x16x32_bf16 v[22:25], v[182:185], v[214:217], v[22:25]
	v_mfma_f32_16x16x32_bf16 v[18:21], v[190:193], v[214:217], v[18:21]
	v_mfma_f32_16x16x32_bf16 v[6:9], v[182:185], v[222:225], v[6:9]
	v_mfma_f32_16x16x32_bf16 v[2:5], v[190:193], v[222:225], v[2:5]
	s_setprio 0
	s_barrier
	s_add_i32 s82, 0, 0x18000
	v_add_u32_e32 v152, s82, v155
	s_add_i32 s83, 0, 0x1c000
	ds_read_b128 v[162:165], v152
	ds_read_b128 v[166:169], v152 offset:1024
	ds_read_b128 v[170:173], v152 offset:2048
	ds_read_b128 v[174:177], v152 offset:3072
	v_add_u32_e32 v152, s83, v155
	ds_read_b128 v[178:181], v152
	ds_read_b128 v[182:185], v152 offset:1024
	ds_read_b128 v[186:189], v152 offset:2048
	ds_read_b128 v[190:193], v152 offset:3072
	s_add_u32 s60, s60, 0x40000
	s_addc_u32 s61, s61, 0
	s_mov_b32 m0, s65
	v_lshl_add_u64 v[232:233], s[60:61], 0, v[130:131]
	ds_read_b128 v[194:197], v158 offset:32768
	ds_read_b128 v[198:201], v158 offset:33792
	ds_read_b128 v[202:205], v158 offset:34816
	ds_read_b128 v[206:209], v158 offset:35840
	ds_read_b128 v[210:213], v158 offset:36864
	ds_read_b128 v[214:217], v158 offset:37888
	ds_read_b128 v[218:221], v158 offset:38912
	ds_read_b128 v[222:225], v158 offset:39936
	global_load_lds_dwordx4 v[232:233], off
	v_lshl_add_u64 v[232:233], s[60:61], 0, v[134:135]
	s_mov_b32 m0, s66
	s_nop 0
	global_load_lds_dwordx4 v[232:233], off
	s_waitcnt vmcnt(8)
	s_waitcnt lgkmcnt(0)
	s_setprio 1
	s_barrier
	v_mfma_f32_16x16x32_bf16 v[126:129], v[162:165], v[194:197], v[126:129]
	v_mfma_f32_16x16x32_bf16 v[122:125], v[170:173], v[194:197], v[122:125]
	v_mfma_f32_16x16x32_bf16 v[110:113], v[162:165], v[202:205], v[110:113]
	v_mfma_f32_16x16x32_bf16 v[106:109], v[170:173], v[202:205], v[106:109]
	v_mfma_f32_16x16x32_bf16 v[94:97], v[162:165], v[210:213], v[94:97]
	v_mfma_f32_16x16x32_bf16 v[90:93], v[170:173], v[210:213], v[90:93]
	v_mfma_f32_16x16x32_bf16 v[78:81], v[162:165], v[218:221], v[78:81]
	v_mfma_f32_16x16x32_bf16 v[74:77], v[170:173], v[218:221], v[74:77]
	v_mfma_f32_16x16x32_bf16 v[126:129], v[166:169], v[198:201], v[126:129]
	v_mfma_f32_16x16x32_bf16 v[122:125], v[174:177], v[198:201], v[122:125]
	v_mfma_f32_16x16x32_bf16 v[110:113], v[166:169], v[206:209], v[110:113]
	v_mfma_f32_16x16x32_bf16 v[106:109], v[174:177], v[206:209], v[106:109]
	v_mfma_f32_16x16x32_bf16 v[94:97], v[166:169], v[214:217], v[94:97]
	v_mfma_f32_16x16x32_bf16 v[90:93], v[174:177], v[214:217], v[90:93]
	v_mfma_f32_16x16x32_bf16 v[78:81], v[166:169], v[222:225], v[78:81]
	v_mfma_f32_16x16x32_bf16 v[74:77], v[174:177], v[222:225], v[74:77]
	s_setprio 0
	s_setprio 1
	v_mfma_f32_16x16x32_bf16 v[118:121], v[178:181], v[194:197], v[118:121]
	v_mfma_f32_16x16x32_bf16 v[114:117], v[186:189], v[194:197], v[114:117]
	v_mfma_f32_16x16x32_bf16 v[102:105], v[178:181], v[202:205], v[102:105]
	v_mfma_f32_16x16x32_bf16 v[98:101], v[186:189], v[202:205], v[98:101]
	v_mfma_f32_16x16x32_bf16 v[86:89], v[178:181], v[210:213], v[86:89]
	v_mfma_f32_16x16x32_bf16 v[82:85], v[186:189], v[210:213], v[82:85]
	v_mfma_f32_16x16x32_bf16 v[70:73], v[178:181], v[218:221], v[70:73]
	v_mfma_f32_16x16x32_bf16 v[66:69], v[186:189], v[218:221], v[66:69]
	v_mfma_f32_16x16x32_bf16 v[118:121], v[182:185], v[198:201], v[118:121]
	v_mfma_f32_16x16x32_bf16 v[114:117], v[190:193], v[198:201], v[114:117]
	v_mfma_f32_16x16x32_bf16 v[102:105], v[182:185], v[206:209], v[102:105]
	v_mfma_f32_16x16x32_bf16 v[98:101], v[190:193], v[206:209], v[98:101]
	v_mfma_f32_16x16x32_bf16 v[86:89], v[182:185], v[214:217], v[86:89]
	v_mfma_f32_16x16x32_bf16 v[82:85], v[190:193], v[214:217], v[82:85]
	v_mfma_f32_16x16x32_bf16 v[70:73], v[182:185], v[222:225], v[70:73]
	v_mfma_f32_16x16x32_bf16 v[66:69], v[190:193], v[222:225], v[66:69]
	s_setprio 0
	s_barrier
	s_add_i32 s60, s82, s62
	v_lshl_add_u64 v[150:151], v[150:151], 0, s[42:43]
	s_mov_b32 m0, s60
	ds_read_b128 v[194:197], v158 offset:49152
	ds_read_b128 v[198:201], v158 offset:50176
	ds_read_b128 v[202:205], v158 offset:51200
	ds_read_b128 v[206:209], v158 offset:52224
	ds_read_b128 v[210:213], v158 offset:53248
	ds_read_b128 v[214:217], v158 offset:54272
	ds_read_b128 v[218:221], v158 offset:55296
	ds_read_b128 v[222:225], v158 offset:56320
	global_load_lds_dwordx4 v[150:151], off
	s_add_i32 m0, s60, 0x2000
	s_add_u32 s58, s58, 0x40080
	v_lshl_add_u64 v[150:151], v[226:227], 0, s[42:43]
	s_addc_u32 s59, s59, 0
	s_add_i32 s60, s83, s62
	global_load_lds_dwordx4 v[150:151], off
	v_lshl_add_u64 v[150:151], s[58:59], 0, v[132:133]
	s_mov_b32 m0, s60
	s_nop 0
	global_load_lds_dwordx4 v[150:151], off
	v_lshl_add_u64 v[150:151], s[58:59], 0, v[136:137]
	s_add_i32 m0, s60, 0x2000
	s_nop 0
	global_load_lds_dwordx4 v[150:151], off
	v_lshl_add_u64 v[150:151], v[228:229], 0, s[42:43]
	s_mov_b32 m0, s68
	s_nop 0
	global_load_lds_dwordx4 v[150:151], off
	v_lshl_add_u64 v[150:151], v[230:231], 0, s[42:43]
	s_mov_b32 m0, s69
	s_nop 0
	global_load_lds_dwordx4 v[150:151], off
	s_waitcnt vmcnt(8)
	s_waitcnt lgkmcnt(0)
	s_setprio 1
	s_barrier
	v_mfma_f32_16x16x32_bf16 v[62:65], v[162:165], v[194:197], v[62:65]
	v_mfma_f32_16x16x32_bf16 v[58:61], v[170:173], v[194:197], v[58:61]
	v_mfma_f32_16x16x32_bf16 v[46:49], v[162:165], v[202:205], v[46:49]
	v_mfma_f32_16x16x32_bf16 v[42:45], v[170:173], v[202:205], v[42:45]
	v_mfma_f32_16x16x32_bf16 v[30:33], v[162:165], v[210:213], v[30:33]
	v_mfma_f32_16x16x32_bf16 v[26:29], v[170:173], v[210:213], v[26:29]
	v_mfma_f32_16x16x32_bf16 v[14:17], v[162:165], v[218:221], v[14:17]
	v_mfma_f32_16x16x32_bf16 v[10:13], v[170:173], v[218:221], v[10:13]
	v_mfma_f32_16x16x32_bf16 v[62:65], v[166:169], v[198:201], v[62:65]
	v_mfma_f32_16x16x32_bf16 v[58:61], v[174:177], v[198:201], v[58:61]
	v_mfma_f32_16x16x32_bf16 v[46:49], v[166:169], v[206:209], v[46:49]
	v_mfma_f32_16x16x32_bf16 v[42:45], v[174:177], v[206:209], v[42:45]
	v_mfma_f32_16x16x32_bf16 v[30:33], v[166:169], v[214:217], v[30:33]
	v_mfma_f32_16x16x32_bf16 v[26:29], v[174:177], v[214:217], v[26:29]
	v_mfma_f32_16x16x32_bf16 v[14:17], v[166:169], v[222:225], v[14:17]
	v_mfma_f32_16x16x32_bf16 v[10:13], v[174:177], v[222:225], v[10:13]
	s_setprio 0
	s_setprio 1
	v_mfma_f32_16x16x32_bf16 v[54:57], v[178:181], v[194:197], v[54:57]
	v_mfma_f32_16x16x32_bf16 v[50:53], v[186:189], v[194:197], v[50:53]
	v_mfma_f32_16x16x32_bf16 v[38:41], v[178:181], v[202:205], v[38:41]
	v_mfma_f32_16x16x32_bf16 v[34:37], v[186:189], v[202:205], v[34:37]
	v_mfma_f32_16x16x32_bf16 v[22:25], v[178:181], v[210:213], v[22:25]
	v_mfma_f32_16x16x32_bf16 v[18:21], v[186:189], v[210:213], v[18:21]
	v_mfma_f32_16x16x32_bf16 v[6:9], v[178:181], v[218:221], v[6:9]
	v_mfma_f32_16x16x32_bf16 v[2:5], v[186:189], v[218:221], v[2:5]
	v_mfma_f32_16x16x32_bf16 v[54:57], v[182:185], v[198:201], v[54:57]
	v_mfma_f32_16x16x32_bf16 v[50:53], v[190:193], v[198:201], v[50:53]
	v_mfma_f32_16x16x32_bf16 v[38:41], v[182:185], v[206:209], v[38:41]
	v_mfma_f32_16x16x32_bf16 v[34:37], v[190:193], v[206:209], v[34:37]
	v_mfma_f32_16x16x32_bf16 v[22:25], v[182:185], v[214:217], v[22:25]
	v_mfma_f32_16x16x32_bf16 v[18:21], v[190:193], v[214:217], v[18:21]
	v_mfma_f32_16x16x32_bf16 v[6:9], v[182:185], v[222:225], v[6:9]
	v_mfma_f32_16x16x32_bf16 v[2:5], v[190:193], v[222:225], v[2:5]
	s_setprio 0
	s_barrier
	s_add_i32 s81, s81, 2
	s_add_u32 s56, s56, 0x100
	s_addc_u32 s57, s57, 0
	s_add_u32 s79, s79, 0x100
	s_addc_u32 s80, s80, 0
	s_cmp_gt_u32 s81, 13
	s_cbranch_scc0 .LBB0_1050
	s_branch .Lz_post_p8a

.Lz_post_p8a:
	s_and_b64 vcc, exec, s[44:45]
	s_cbranch_vccz .LBB0_1053
	s_barrier

.LBB0_1356:
	s_ashr_i32 s45, s44, 31
	s_lshl_b64 s[46:47], s[44:45], 19
	s_add_u32 s46, s3, s46
	s_addc_u32 s47, s23, s47
	s_and_b64 s[48:49], s[6:7], exec
	s_cselect_b32 s45, s47, s55
	s_cselect_b32 s51, s46, s54
	s_ashr_i32 s43, s42, 31
	s_lshl_b64 s[48:49], s[42:43], 19
	s_add_u32 s48, s29, s48
	s_addc_u32 s49, s31, s49
	s_and_b64 s[58:59], s[6:7], exec
	s_cselect_b32 s43, s49, s57
	s_cselect_b32 s53, s48, s56
	s_add_u32 s54, s54, 0x40080
	s_addc_u32 s55, s55, 0
	s_add_u32 s74, s56, 0x100
	s_addc_u32 s75, s57, 0
	s_mov_b32 s76, -2
	s_waitcnt lgkmcnt(0)
	s_waitcnt vmcnt(0)
	ds_read_b128 v[158:161], v152
	ds_read_b128 v[162:165], v152 offset:1024
	ds_read_b128 v[166:169], v152 offset:2048
	ds_read_b128 v[170:173], v152 offset:3072
	ds_read_b128 v[174:177], v153
	ds_read_b128 v[178:181], v153 offset:1024
	ds_read_b128 v[182:185], v153 offset:2048
	ds_read_b128 v[186:189], v153 offset:3072
	s_add_u32 s56, s54, 0xfffc0080
	s_addc_u32 s57, s55, -1
	s_cmp_eq_u32 s76, 12
	s_cselect_b32 s59, s45, s57
	s_cselect_b32 s58, s51, s56
	s_cselect_b32 s57, s43, s75
	s_cselect_b32 s56, s53, s74
	v_lshl_add_u64 v[148:149], s[54:55], 0, v[140:141]
	s_add_i32 m0, s61, 0xc000
	ds_read_b128 v[190:193], v154
	ds_read_b128 v[194:197], v154 offset:1024
	ds_read_b128 v[198:201], v154 offset:2048
	ds_read_b128 v[202:205], v154 offset:3072
	ds_read_b128 v[206:209], v154 offset:4096
	ds_read_b128 v[210:213], v154 offset:5120
	ds_read_b128 v[214:217], v154 offset:6144
	ds_read_b128 v[218:221], v154 offset:7168
	global_load_lds_dwordx4 v[148:149], off
	v_lshl_add_u64 v[148:149], s[54:55], 0, v[142:143]
	s_add_i32 m0, s61, 0xe000
	s_nop 0
	global_load_lds_dwordx4 v[148:149], off
	s_waitcnt vmcnt(8)
	s_waitcnt lgkmcnt(0)
	s_setprio 1
	s_barrier
	v_mfma_f32_16x16x32_bf16 v[126:129], v[158:161], v[190:193], 0
	v_mfma_f32_16x16x32_bf16 v[122:125], v[166:169], v[190:193], 0
	v_mfma_f32_16x16x32_bf16 v[110:113], v[158:161], v[198:201], 0
	v_mfma_f32_16x16x32_bf16 v[106:109], v[166:169], v[198:201], 0
	v_mfma_f32_16x16x32_bf16 v[94:97], v[158:161], v[206:209], 0
	v_mfma_f32_16x16x32_bf16 v[90:93], v[166:169], v[206:209], 0
	v_mfma_f32_16x16x32_bf16 v[78:81], v[158:161], v[214:217], 0
	v_mfma_f32_16x16x32_bf16 v[74:77], v[166:169], v[214:217], 0
	v_mfma_f32_16x16x32_bf16 v[126:129], v[162:165], v[194:197], v[126:129]
	v_mfma_f32_16x16x32_bf16 v[122:125], v[170:173], v[194:197], v[122:125]
	v_mfma_f32_16x16x32_bf16 v[110:113], v[162:165], v[202:205], v[110:113]
	v_mfma_f32_16x16x32_bf16 v[106:109], v[170:173], v[202:205], v[106:109]
	v_mfma_f32_16x16x32_bf16 v[94:97], v[162:165], v[210:213], v[94:97]
	v_mfma_f32_16x16x32_bf16 v[90:93], v[170:173], v[210:213], v[90:93]
	v_mfma_f32_16x16x32_bf16 v[78:81], v[162:165], v[218:221], v[78:81]
	v_mfma_f32_16x16x32_bf16 v[74:77], v[170:173], v[218:221], v[74:77]
	s_setprio 0
	s_setprio 1
	v_mfma_f32_16x16x32_bf16 v[118:121], v[174:177], v[190:193], 0
	v_mfma_f32_16x16x32_bf16 v[114:117], v[182:185], v[190:193], 0
	v_mfma_f32_16x16x32_bf16 v[102:105], v[174:177], v[198:201], 0
	v_mfma_f32_16x16x32_bf16 v[98:101], v[182:185], v[198:201], 0
	v_mfma_f32_16x16x32_bf16 v[86:89], v[174:177], v[206:209], 0
	v_mfma_f32_16x16x32_bf16 v[82:85], v[182:185], v[206:209], 0
	v_mfma_f32_16x16x32_bf16 v[70:73], v[174:177], v[214:217], 0
	v_mfma_f32_16x16x32_bf16 v[66:69], v[182:185], v[214:217], 0
	v_mfma_f32_16x16x32_bf16 v[118:121], v[178:181], v[194:197], v[118:121]
	v_mfma_f32_16x16x32_bf16 v[114:117], v[186:189], v[194:197], v[114:117]
	v_mfma_f32_16x16x32_bf16 v[102:105], v[178:181], v[202:205], v[102:105]
	v_mfma_f32_16x16x32_bf16 v[98:101], v[186:189], v[202:205], v[98:101]
	v_mfma_f32_16x16x32_bf16 v[86:89], v[178:181], v[210:213], v[86:89]
	v_mfma_f32_16x16x32_bf16 v[82:85], v[186:189], v[210:213], v[82:85]
	v_mfma_f32_16x16x32_bf16 v[70:73], v[178:181], v[218:221], v[70:73]
	v_mfma_f32_16x16x32_bf16 v[66:69], v[186:189], v[218:221], v[66:69]
	s_setprio 0
	s_barrier
	s_add_i32 s77, s71, s60
	v_lshl_add_u64 v[148:149], s[56:57], 0, v[132:133]
	s_mov_b32 m0, s77
	ds_read_b128 v[190:193], v154 offset:16384
	ds_read_b128 v[194:197], v154 offset:17408
	ds_read_b128 v[198:201], v154 offset:18432
	ds_read_b128 v[202:205], v154 offset:19456
	ds_read_b128 v[206:209], v154 offset:20480
	ds_read_b128 v[210:213], v154 offset:21504
	ds_read_b128 v[214:217], v154 offset:22528
	ds_read_b128 v[218:221], v154 offset:23552
	global_load_lds_dwordx4 v[148:149], off
	s_add_i32 m0, s77, 0x2000
	s_add_u32 s78, s56, 0x40000
	v_lshl_add_u64 v[222:223], s[56:57], 0, v[136:137]
	s_addc_u32 s79, s57, 0
	s_add_i32 s77, s72, s60
	global_load_lds_dwordx4 v[222:223], off
	v_lshl_add_u64 v[224:225], s[78:79], 0, v[132:133]
	s_mov_b32 m0, s77
	v_lshl_add_u64 v[226:227], s[58:59], 0, v[134:135]
	global_load_lds_dwordx4 v[224:225], off
	v_lshl_add_u64 v[224:225], s[78:79], 0, v[136:137]
	s_add_i32 m0, s77, 0x2000
	s_nop 0
	global_load_lds_dwordx4 v[224:225], off
	v_lshl_add_u64 v[224:225], s[58:59], 0, v[130:131]
	s_mov_b32 m0, s61
	s_nop 0
	global_load_lds_dwordx4 v[224:225], off
	s_mov_b32 m0, s62
	s_nop 0
	global_load_lds_dwordx4 v[226:227], off
	s_waitcnt vmcnt(8)
	s_waitcnt lgkmcnt(0)
	s_setprio 1
	s_barrier
	v_mfma_f32_16x16x32_bf16 v[62:65], v[158:161], v[190:193], 0
	v_mfma_f32_16x16x32_bf16 v[58:61], v[166:169], v[190:193], 0
	v_mfma_f32_16x16x32_bf16 v[46:49], v[158:161], v[198:201], 0
	v_mfma_f32_16x16x32_bf16 v[42:45], v[166:169], v[198:201], 0
	v_mfma_f32_16x16x32_bf16 v[30:33], v[158:161], v[206:209], 0
	v_mfma_f32_16x16x32_bf16 v[26:29], v[166:169], v[206:209], 0
	v_mfma_f32_16x16x32_bf16 v[14:17], v[158:161], v[214:217], 0
	v_mfma_f32_16x16x32_bf16 v[10:13], v[166:169], v[214:217], 0
	v_mfma_f32_16x16x32_bf16 v[62:65], v[162:165], v[194:197], v[62:65]
	v_mfma_f32_16x16x32_bf16 v[58:61], v[170:173], v[194:197], v[58:61]
	v_mfma_f32_16x16x32_bf16 v[46:49], v[162:165], v[202:205], v[46:49]
	v_mfma_f32_16x16x32_bf16 v[42:45], v[170:173], v[202:205], v[42:45]
	v_mfma_f32_16x16x32_bf16 v[30:33], v[162:165], v[210:213], v[30:33]
	v_mfma_f32_16x16x32_bf16 v[26:29], v[170:173], v[210:213], v[26:29]
	v_mfma_f32_16x16x32_bf16 v[14:17], v[162:165], v[218:221], v[14:17]
	v_mfma_f32_16x16x32_bf16 v[10:13], v[170:173], v[218:221], v[10:13]
	s_setprio 0
	s_setprio 1
	v_mfma_f32_16x16x32_bf16 v[54:57], v[174:177], v[190:193], 0
	v_mfma_f32_16x16x32_bf16 v[50:53], v[182:185], v[190:193], 0
	v_mfma_f32_16x16x32_bf16 v[38:41], v[174:177], v[198:201], 0
	v_mfma_f32_16x16x32_bf16 v[34:37], v[182:185], v[198:201], 0
	v_mfma_f32_16x16x32_bf16 v[22:25], v[174:177], v[206:209], 0
	v_mfma_f32_16x16x32_bf16 v[18:21], v[182:185], v[206:209], 0
	v_mfma_f32_16x16x32_bf16 v[6:9], v[174:177], v[214:217], 0
	v_mfma_f32_16x16x32_bf16 v[2:5], v[182:185], v[214:217], 0
	v_mfma_f32_16x16x32_bf16 v[54:57], v[178:181], v[194:197], v[54:57]
	v_mfma_f32_16x16x32_bf16 v[50:53], v[186:189], v[194:197], v[50:53]
	v_mfma_f32_16x16x32_bf16 v[38:41], v[178:181], v[202:205], v[38:41]
	v_mfma_f32_16x16x32_bf16 v[34:37], v[186:189], v[202:205], v[34:37]
	v_mfma_f32_16x16x32_bf16 v[22:25], v[178:181], v[210:213], v[22:25]
	v_mfma_f32_16x16x32_bf16 v[18:21], v[186:189], v[210:213], v[18:21]
	v_mfma_f32_16x16x32_bf16 v[6:9], v[178:181], v[218:221], v[6:9]
	v_mfma_f32_16x16x32_bf16 v[2:5], v[186:189], v[218:221], v[2:5]
	s_setprio 0
	s_barrier
	s_add_i32 s77, 0, 0x18000
	v_add_u32_e32 v157, s77, v151
	s_add_i32 s78, 0, 0x1c000
	ds_read_b128 v[158:161], v157
	ds_read_b128 v[162:165], v157 offset:1024
	ds_read_b128 v[166:169], v157 offset:2048
	ds_read_b128 v[170:173], v157 offset:3072
	v_add_u32_e32 v157, s78, v151
	ds_read_b128 v[174:177], v157
	ds_read_b128 v[178:181], v157 offset:1024
	ds_read_b128 v[182:185], v157 offset:2048
	ds_read_b128 v[186:189], v157 offset:3072
	s_add_u32 s58, s58, 0x40000
	s_addc_u32 s59, s59, 0
	s_mov_b32 m0, s63
	v_lshl_add_u64 v[228:229], s[58:59], 0, v[130:131]
	ds_read_b128 v[190:193], v154 offset:32768
	ds_read_b128 v[194:197], v154 offset:33792
	ds_read_b128 v[198:201], v154 offset:34816
	ds_read_b128 v[202:205], v154 offset:35840
	ds_read_b128 v[206:209], v154 offset:36864
	ds_read_b128 v[210:213], v154 offset:37888
	ds_read_b128 v[214:217], v154 offset:38912
	ds_read_b128 v[218:221], v154 offset:39936
	global_load_lds_dwordx4 v[228:229], off
	v_lshl_add_u64 v[228:229], s[58:59], 0, v[134:135]
	s_mov_b32 m0, s64
	s_nop 0
	global_load_lds_dwordx4 v[228:229], off
	s_waitcnt vmcnt(8)
	s_waitcnt lgkmcnt(0)
	s_setprio 1
	s_barrier
	v_mfma_f32_16x16x32_bf16 v[126:129], v[158:161], v[190:193], v[126:129]
	v_mfma_f32_16x16x32_bf16 v[122:125], v[166:169], v[190:193], v[122:125]
	v_mfma_f32_16x16x32_bf16 v[110:113], v[158:161], v[198:201], v[110:113]
	v_mfma_f32_16x16x32_bf16 v[106:109], v[166:169], v[198:201], v[106:109]
	v_mfma_f32_16x16x32_bf16 v[94:97], v[158:161], v[206:209], v[94:97]
	v_mfma_f32_16x16x32_bf16 v[90:93], v[166:169], v[206:209], v[90:93]
	v_mfma_f32_16x16x32_bf16 v[78:81], v[158:161], v[214:217], v[78:81]
	v_mfma_f32_16x16x32_bf16 v[74:77], v[166:169], v[214:217], v[74:77]
	v_mfma_f32_16x16x32_bf16 v[126:129], v[162:165], v[194:197], v[126:129]
	v_mfma_f32_16x16x32_bf16 v[122:125], v[170:173], v[194:197], v[122:125]
	v_mfma_f32_16x16x32_bf16 v[110:113], v[162:165], v[202:205], v[110:113]
	v_mfma_f32_16x16x32_bf16 v[106:109], v[170:173], v[202:205], v[106:109]
	v_mfma_f32_16x16x32_bf16 v[94:97], v[162:165], v[210:213], v[94:97]
	v_mfma_f32_16x16x32_bf16 v[90:93], v[170:173], v[210:213], v[90:93]
	v_mfma_f32_16x16x32_bf16 v[78:81], v[162:165], v[218:221], v[78:81]
	v_mfma_f32_16x16x32_bf16 v[74:77], v[170:173], v[218:221], v[74:77]
	s_setprio 0
	s_setprio 1
	v_mfma_f32_16x16x32_bf16 v[118:121], v[174:177], v[190:193], v[118:121]
	v_mfma_f32_16x16x32_bf16 v[114:117], v[182:185], v[190:193], v[114:117]
	v_mfma_f32_16x16x32_bf16 v[102:105], v[174:177], v[198:201], v[102:105]
	v_mfma_f32_16x16x32_bf16 v[98:101], v[182:185], v[198:201], v[98:101]
	v_mfma_f32_16x16x32_bf16 v[86:89], v[174:177], v[206:209], v[86:89]
	v_mfma_f32_16x16x32_bf16 v[82:85], v[182:185], v[206:209], v[82:85]
	v_mfma_f32_16x16x32_bf16 v[70:73], v[174:177], v[214:217], v[70:73]
	v_mfma_f32_16x16x32_bf16 v[66:69], v[182:185], v[214:217], v[66:69]
	v_mfma_f32_16x16x32_bf16 v[118:121], v[178:181], v[194:197], v[118:121]
	v_mfma_f32_16x16x32_bf16 v[114:117], v[186:189], v[194:197], v[114:117]
	v_mfma_f32_16x16x32_bf16 v[102:105], v[178:181], v[202:205], v[102:105]
	v_mfma_f32_16x16x32_bf16 v[98:101], v[186:189], v[202:205], v[98:101]
	v_mfma_f32_16x16x32_bf16 v[86:89], v[178:181], v[210:213], v[86:89]
	v_mfma_f32_16x16x32_bf16 v[82:85], v[186:189], v[210:213], v[82:85]
	v_mfma_f32_16x16x32_bf16 v[70:73], v[178:181], v[218:221], v[70:73]
	v_mfma_f32_16x16x32_bf16 v[66:69], v[186:189], v[218:221], v[66:69]
	s_setprio 0
	s_barrier
	s_add_i32 s58, s77, s60
	v_lshl_add_u64 v[148:149], v[148:149], 0, s[24:25]
	s_mov_b32 m0, s58
	ds_read_b128 v[190:193], v154 offset:49152
	ds_read_b128 v[194:197], v154 offset:50176
	ds_read_b128 v[198:201], v154 offset:51200
	ds_read_b128 v[202:205], v154 offset:52224
	ds_read_b128 v[206:209], v154 offset:53248
	ds_read_b128 v[210:213], v154 offset:54272
	ds_read_b128 v[214:217], v154 offset:55296
	ds_read_b128 v[218:221], v154 offset:56320
	global_load_lds_dwordx4 v[148:149], off
	s_add_i32 m0, s58, 0x2000
	s_add_u32 s56, s56, 0x40080
	v_lshl_add_u64 v[148:149], v[222:223], 0, s[24:25]
	s_addc_u32 s57, s57, 0
	s_add_i32 s58, s78, s60
	global_load_lds_dwordx4 v[148:149], off
	v_lshl_add_u64 v[148:149], s[56:57], 0, v[132:133]
	s_mov_b32 m0, s58
	s_nop 0
	global_load_lds_dwordx4 v[148:149], off
	v_lshl_add_u64 v[148:149], s[56:57], 0, v[136:137]
	s_add_i32 m0, s58, 0x2000
	s_nop 0
	global_load_lds_dwordx4 v[148:149], off
	v_lshl_add_u64 v[148:149], v[224:225], 0, s[24:25]
	s_mov_b32 m0, s66
	s_nop 0
	global_load_lds_dwordx4 v[148:149], off
	v_lshl_add_u64 v[148:149], v[226:227], 0, s[24:25]
	s_mov_b32 m0, s67
	s_nop 0
	global_load_lds_dwordx4 v[148:149], off
	s_waitcnt vmcnt(8)
	s_waitcnt lgkmcnt(0)
	s_setprio 1
	s_barrier
	v_mfma_f32_16x16x32_bf16 v[62:65], v[158:161], v[190:193], v[62:65]
	v_mfma_f32_16x16x32_bf16 v[58:61], v[166:169], v[190:193], v[58:61]
	v_mfma_f32_16x16x32_bf16 v[46:49], v[158:161], v[198:201], v[46:49]
	v_mfma_f32_16x16x32_bf16 v[42:45], v[166:169], v[198:201], v[42:45]
	v_mfma_f32_16x16x32_bf16 v[30:33], v[158:161], v[206:209], v[30:33]
	v_mfma_f32_16x16x32_bf16 v[26:29], v[166:169], v[206:209], v[26:29]
	v_mfma_f32_16x16x32_bf16 v[14:17], v[158:161], v[214:217], v[14:17]
	v_mfma_f32_16x16x32_bf16 v[10:13], v[166:169], v[214:217], v[10:13]
	v_mfma_f32_16x16x32_bf16 v[62:65], v[162:165], v[194:197], v[62:65]
	v_mfma_f32_16x16x32_bf16 v[58:61], v[170:173], v[194:197], v[58:61]
	v_mfma_f32_16x16x32_bf16 v[46:49], v[162:165], v[202:205], v[46:49]
	v_mfma_f32_16x16x32_bf16 v[42:45], v[170:173], v[202:205], v[42:45]
	v_mfma_f32_16x16x32_bf16 v[30:33], v[162:165], v[210:213], v[30:33]
	v_mfma_f32_16x16x32_bf16 v[26:29], v[170:173], v[210:213], v[26:29]
	v_mfma_f32_16x16x32_bf16 v[14:17], v[162:165], v[218:221], v[14:17]
	v_mfma_f32_16x16x32_bf16 v[10:13], v[170:173], v[218:221], v[10:13]
	s_setprio 0
	s_setprio 1
	v_mfma_f32_16x16x32_bf16 v[54:57], v[174:177], v[190:193], v[54:57]
	v_mfma_f32_16x16x32_bf16 v[50:53], v[182:185], v[190:193], v[50:53]
	v_mfma_f32_16x16x32_bf16 v[38:41], v[174:177], v[198:201], v[38:41]
	v_mfma_f32_16x16x32_bf16 v[34:37], v[182:185], v[198:201], v[34:37]
	v_mfma_f32_16x16x32_bf16 v[22:25], v[174:177], v[206:209], v[22:25]
	v_mfma_f32_16x16x32_bf16 v[18:21], v[182:185], v[206:209], v[18:21]
	v_mfma_f32_16x16x32_bf16 v[6:9], v[174:177], v[214:217], v[6:9]
	v_mfma_f32_16x16x32_bf16 v[2:5], v[182:185], v[214:217], v[2:5]
	v_mfma_f32_16x16x32_bf16 v[54:57], v[178:181], v[194:197], v[54:57]
	v_mfma_f32_16x16x32_bf16 v[50:53], v[186:189], v[194:197], v[50:53]
	v_mfma_f32_16x16x32_bf16 v[38:41], v[178:181], v[202:205], v[38:41]
	v_mfma_f32_16x16x32_bf16 v[34:37], v[186:189], v[202:205], v[34:37]
	v_mfma_f32_16x16x32_bf16 v[22:25], v[178:181], v[210:213], v[22:25]
	v_mfma_f32_16x16x32_bf16 v[18:21], v[186:189], v[210:213], v[18:21]
	v_mfma_f32_16x16x32_bf16 v[6:9], v[178:181], v[218:221], v[6:9]
	v_mfma_f32_16x16x32_bf16 v[2:5], v[186:189], v[218:221], v[2:5]
	s_setprio 0
	s_barrier
	s_add_i32 s76, s76, 2
	s_add_u32 s54, s54, 0x100
	s_addc_u32 s55, s55, 0
	s_add_u32 s74, s74, 0x100
	s_addc_u32 s75, s75, 0
	s_cmp_gt_u32 s76, 13
	s_cbranch_scc0 .LBB0_1357
	s_branch .Lz_post_p10

.Lz_post_p10:
	s_and_b64 vcc, exec, s[26:27]
	s_cbranch_vccz .LBB0_1360
	s_barrier

.LBB0_1485:
	s_add_u32 s10, s52, 0x100
	s_addc_u32 s79, s53, 0
	s_mov_b32 s80, -2
	s_waitcnt vmcnt(0)
	ds_read_b128 v[152:155], v157
	ds_read_b128 v[162:165], v157 offset:1024
	ds_read_b128 v[166:169], v157 offset:2048
	ds_read_b128 v[170:173], v157 offset:3072
	ds_read_b128 v[174:177], v158
	ds_read_b128 v[178:181], v158 offset:1024
	ds_read_b128 v[182:185], v158 offset:2048
	ds_read_b128 v[186:189], v158 offset:3072
	s_add_u32 s6, s50, 0x100
	s_addc_u32 s7, s51, 0
	s_cmp_eq_u32 s80, 8
	s_cselect_b32 s55, s47, s7
	s_cselect_b32 s54, s46, s6
	s_cselect_b32 s53, s49, s79
	s_cselect_b32 s52, s48, s10
	v_lshl_add_u64 v[222:223], s[50:51], 0, v[144:145]
	s_add_i32 m0, s57, 0xc000
	ds_read_b128 v[190:193], v159
	ds_read_b128 v[194:197], v159 offset:1024
	ds_read_b128 v[198:201], v159 offset:2048
	ds_read_b128 v[202:205], v159 offset:3072
	ds_read_b128 v[206:209], v159 offset:4096
	ds_read_b128 v[210:213], v159 offset:5120
	ds_read_b128 v[214:217], v159 offset:6144
	ds_read_b128 v[218:221], v159 offset:7168
	global_load_lds_dwordx4 v[222:223], off
	v_lshl_add_u64 v[222:223], s[50:51], 0, v[146:147]
	s_add_i32 m0, s57, 0xe000
	s_nop 0
	global_load_lds_dwordx4 v[222:223], off
	s_waitcnt vmcnt(8)
	s_waitcnt lgkmcnt(0)
	s_setprio 1
	s_barrier
	v_mfma_f32_16x16x32_bf16 v[126:129], v[152:155], v[190:193], 0
	v_mfma_f32_16x16x32_bf16 v[122:125], v[166:169], v[190:193], 0
	v_mfma_f32_16x16x32_bf16 v[110:113], v[152:155], v[198:201], 0
	v_mfma_f32_16x16x32_bf16 v[106:109], v[166:169], v[198:201], 0
	v_mfma_f32_16x16x32_bf16 v[94:97], v[152:155], v[206:209], 0
	v_mfma_f32_16x16x32_bf16 v[90:93], v[166:169], v[206:209], 0
	v_mfma_f32_16x16x32_bf16 v[78:81], v[152:155], v[214:217], 0
	v_mfma_f32_16x16x32_bf16 v[74:77], v[166:169], v[214:217], 0
	v_mfma_f32_16x16x32_bf16 v[126:129], v[162:165], v[194:197], v[126:129]
	v_mfma_f32_16x16x32_bf16 v[122:125], v[170:173], v[194:197], v[122:125]
	v_mfma_f32_16x16x32_bf16 v[110:113], v[162:165], v[202:205], v[110:113]
	v_mfma_f32_16x16x32_bf16 v[106:109], v[170:173], v[202:205], v[106:109]
	v_mfma_f32_16x16x32_bf16 v[94:97], v[162:165], v[210:213], v[94:97]
	v_mfma_f32_16x16x32_bf16 v[90:93], v[170:173], v[210:213], v[90:93]
	v_mfma_f32_16x16x32_bf16 v[78:81], v[162:165], v[218:221], v[78:81]
	v_mfma_f32_16x16x32_bf16 v[74:77], v[170:173], v[218:221], v[74:77]
	s_setprio 0
	s_setprio 1
	v_mfma_f32_16x16x32_bf16 v[118:121], v[174:177], v[190:193], 0
	v_mfma_f32_16x16x32_bf16 v[114:117], v[182:185], v[190:193], 0
	v_mfma_f32_16x16x32_bf16 v[102:105], v[174:177], v[198:201], 0
	v_mfma_f32_16x16x32_bf16 v[98:101], v[182:185], v[198:201], 0
	v_mfma_f32_16x16x32_bf16 v[86:89], v[174:177], v[206:209], 0
	v_mfma_f32_16x16x32_bf16 v[82:85], v[182:185], v[206:209], 0
	v_mfma_f32_16x16x32_bf16 v[70:73], v[174:177], v[214:217], 0
	v_mfma_f32_16x16x32_bf16 v[66:69], v[182:185], v[214:217], 0
	v_mfma_f32_16x16x32_bf16 v[118:121], v[178:181], v[194:197], v[118:121]
	v_mfma_f32_16x16x32_bf16 v[114:117], v[186:189], v[194:197], v[114:117]
	v_mfma_f32_16x16x32_bf16 v[102:105], v[178:181], v[202:205], v[102:105]
	v_mfma_f32_16x16x32_bf16 v[98:101], v[186:189], v[202:205], v[98:101]
	v_mfma_f32_16x16x32_bf16 v[86:89], v[178:181], v[210:213], v[86:89]
	v_mfma_f32_16x16x32_bf16 v[82:85], v[186:189], v[210:213], v[82:85]
	v_mfma_f32_16x16x32_bf16 v[70:73], v[178:181], v[218:221], v[70:73]
	v_mfma_f32_16x16x32_bf16 v[66:69], v[186:189], v[218:221], v[66:69]
	s_setprio 0
	s_barrier
	s_add_i32 s50, s68, s56
	v_lshl_add_u64 v[222:223], s[52:53], 0, v[132:133]
	s_mov_b32 m0, s50
	ds_read_b128 v[190:193], v159 offset:16384
	ds_read_b128 v[194:197], v159 offset:17408
	ds_read_b128 v[198:201], v159 offset:18432
	ds_read_b128 v[202:205], v159 offset:19456
	ds_read_b128 v[206:209], v159 offset:20480
	ds_read_b128 v[210:213], v159 offset:21504
	ds_read_b128 v[214:217], v159 offset:22528
	ds_read_b128 v[218:221], v159 offset:23552
	global_load_lds_dwordx4 v[222:223], off
	s_add_i32 m0, s50, 0x2000
	s_add_u32 s50, s52, 0x30000
	v_lshl_add_u64 v[224:225], s[52:53], 0, v[136:137]
	s_addc_u32 s51, s53, 0
	s_add_i32 s81, s69, s56
	global_load_lds_dwordx4 v[224:225], off
	v_lshl_add_u64 v[226:227], s[50:51], 0, v[132:133]
	s_mov_b32 m0, s81
	v_lshl_add_u64 v[228:229], s[54:55], 0, v[134:135]
	global_load_lds_dwordx4 v[226:227], off
	v_lshl_add_u64 v[226:227], s[50:51], 0, v[136:137]
	s_add_i32 m0, s81, 0x2000
	s_nop 0
	global_load_lds_dwordx4 v[226:227], off
	v_lshl_add_u64 v[226:227], s[54:55], 0, v[130:131]
	s_mov_b32 m0, s57
	s_nop 0
	global_load_lds_dwordx4 v[226:227], off
	s_mov_b32 m0, s58
	s_nop 0
	global_load_lds_dwordx4 v[228:229], off
	s_waitcnt vmcnt(8)
	s_waitcnt lgkmcnt(0)
	s_setprio 1
	s_barrier
	v_mfma_f32_16x16x32_bf16 v[62:65], v[152:155], v[190:193], 0
	v_mfma_f32_16x16x32_bf16 v[58:61], v[166:169], v[190:193], 0
	v_mfma_f32_16x16x32_bf16 v[46:49], v[152:155], v[198:201], 0
	v_mfma_f32_16x16x32_bf16 v[42:45], v[166:169], v[198:201], 0
	v_mfma_f32_16x16x32_bf16 v[30:33], v[152:155], v[206:209], 0
	v_mfma_f32_16x16x32_bf16 v[26:29], v[166:169], v[206:209], 0
	v_mfma_f32_16x16x32_bf16 v[14:17], v[152:155], v[214:217], 0
	v_mfma_f32_16x16x32_bf16 v[10:13], v[166:169], v[214:217], 0
	v_mfma_f32_16x16x32_bf16 v[62:65], v[162:165], v[194:197], v[62:65]
	v_mfma_f32_16x16x32_bf16 v[58:61], v[170:173], v[194:197], v[58:61]
	v_mfma_f32_16x16x32_bf16 v[46:49], v[162:165], v[202:205], v[46:49]
	v_mfma_f32_16x16x32_bf16 v[42:45], v[170:173], v[202:205], v[42:45]
	v_mfma_f32_16x16x32_bf16 v[30:33], v[162:165], v[210:213], v[30:33]
	v_mfma_f32_16x16x32_bf16 v[26:29], v[170:173], v[210:213], v[26:29]
	v_mfma_f32_16x16x32_bf16 v[14:17], v[162:165], v[218:221], v[14:17]
	v_mfma_f32_16x16x32_bf16 v[10:13], v[170:173], v[218:221], v[10:13]
	s_setprio 0
	s_setprio 1
	v_mfma_f32_16x16x32_bf16 v[54:57], v[174:177], v[190:193], 0
	v_mfma_f32_16x16x32_bf16 v[50:53], v[182:185], v[190:193], 0
	v_mfma_f32_16x16x32_bf16 v[38:41], v[174:177], v[198:201], 0
	v_mfma_f32_16x16x32_bf16 v[34:37], v[182:185], v[198:201], 0
	v_mfma_f32_16x16x32_bf16 v[22:25], v[174:177], v[206:209], 0
	v_mfma_f32_16x16x32_bf16 v[18:21], v[182:185], v[206:209], 0
	v_mfma_f32_16x16x32_bf16 v[6:9], v[174:177], v[214:217], 0
	v_mfma_f32_16x16x32_bf16 v[2:5], v[182:185], v[214:217], 0
	v_mfma_f32_16x16x32_bf16 v[54:57], v[178:181], v[194:197], v[54:57]
	v_mfma_f32_16x16x32_bf16 v[50:53], v[186:189], v[194:197], v[50:53]
	v_mfma_f32_16x16x32_bf16 v[38:41], v[178:181], v[202:205], v[38:41]
	v_mfma_f32_16x16x32_bf16 v[34:37], v[186:189], v[202:205], v[34:37]
	v_mfma_f32_16x16x32_bf16 v[22:25], v[178:181], v[210:213], v[22:25]
	v_mfma_f32_16x16x32_bf16 v[18:21], v[186:189], v[210:213], v[18:21]
	v_mfma_f32_16x16x32_bf16 v[6:9], v[178:181], v[218:221], v[6:9]
	v_mfma_f32_16x16x32_bf16 v[2:5], v[186:189], v[218:221], v[2:5]
	s_setprio 0
	s_barrier
	s_add_i32 s81, 0, 0x18000
	v_add_u32_e32 v138, s81, v143
	s_add_i32 s82, 0, 0x1c000
	ds_read_b128 v[152:155], v138
	ds_read_b128 v[162:165], v138 offset:1024
	ds_read_b128 v[166:169], v138 offset:2048
	ds_read_b128 v[170:173], v138 offset:3072
	v_add_u32_e32 v138, s82, v143
	ds_read_b128 v[174:177], v138
	ds_read_b128 v[178:181], v138 offset:1024
	ds_read_b128 v[182:185], v138 offset:2048
	ds_read_b128 v[186:189], v138 offset:3072
	s_add_u32 s50, s54, 0x30000
	s_addc_u32 s51, s55, 0
	s_mov_b32 m0, s59
	v_lshl_add_u64 v[230:231], s[50:51], 0, v[130:131]
	ds_read_b128 v[190:193], v159 offset:32768
	ds_read_b128 v[194:197], v159 offset:33792
	ds_read_b128 v[198:201], v159 offset:34816
	ds_read_b128 v[202:205], v159 offset:35840
	ds_read_b128 v[206:209], v159 offset:36864
	ds_read_b128 v[210:213], v159 offset:37888
	ds_read_b128 v[214:217], v159 offset:38912
	ds_read_b128 v[218:221], v159 offset:39936
	global_load_lds_dwordx4 v[230:231], off
	v_lshl_add_u64 v[230:231], s[50:51], 0, v[134:135]
	s_mov_b32 m0, s60
	s_nop 0
	global_load_lds_dwordx4 v[230:231], off
	s_waitcnt vmcnt(8)
	s_waitcnt lgkmcnt(0)
	s_setprio 1
	s_barrier
	v_mfma_f32_16x16x32_bf16 v[126:129], v[152:155], v[190:193], v[126:129]
	v_mfma_f32_16x16x32_bf16 v[122:125], v[166:169], v[190:193], v[122:125]
	v_mfma_f32_16x16x32_bf16 v[110:113], v[152:155], v[198:201], v[110:113]
	v_mfma_f32_16x16x32_bf16 v[106:109], v[166:169], v[198:201], v[106:109]
	v_mfma_f32_16x16x32_bf16 v[94:97], v[152:155], v[206:209], v[94:97]
	v_mfma_f32_16x16x32_bf16 v[90:93], v[166:169], v[206:209], v[90:93]
	v_mfma_f32_16x16x32_bf16 v[78:81], v[152:155], v[214:217], v[78:81]
	v_mfma_f32_16x16x32_bf16 v[74:77], v[166:169], v[214:217], v[74:77]
	v_mfma_f32_16x16x32_bf16 v[126:129], v[162:165], v[194:197], v[126:129]
	v_mfma_f32_16x16x32_bf16 v[122:125], v[170:173], v[194:197], v[122:125]
	v_mfma_f32_16x16x32_bf16 v[110:113], v[162:165], v[202:205], v[110:113]
	v_mfma_f32_16x16x32_bf16 v[106:109], v[170:173], v[202:205], v[106:109]
	v_mfma_f32_16x16x32_bf16 v[94:97], v[162:165], v[210:213], v[94:97]
	v_mfma_f32_16x16x32_bf16 v[90:93], v[170:173], v[210:213], v[90:93]
	v_mfma_f32_16x16x32_bf16 v[78:81], v[162:165], v[218:221], v[78:81]
	v_mfma_f32_16x16x32_bf16 v[74:77], v[170:173], v[218:221], v[74:77]
	s_setprio 0
	s_setprio 1
	v_mfma_f32_16x16x32_bf16 v[118:121], v[174:177], v[190:193], v[118:121]
	v_mfma_f32_16x16x32_bf16 v[114:117], v[182:185], v[190:193], v[114:117]
	v_mfma_f32_16x16x32_bf16 v[102:105], v[174:177], v[198:201], v[102:105]
	v_mfma_f32_16x16x32_bf16 v[98:101], v[182:185], v[198:201], v[98:101]
	v_mfma_f32_16x16x32_bf16 v[86:89], v[174:177], v[206:209], v[86:89]
	v_mfma_f32_16x16x32_bf16 v[82:85], v[182:185], v[206:209], v[82:85]
	v_mfma_f32_16x16x32_bf16 v[70:73], v[174:177], v[214:217], v[70:73]
	v_mfma_f32_16x16x32_bf16 v[66:69], v[182:185], v[214:217], v[66:69]
	v_mfma_f32_16x16x32_bf16 v[118:121], v[178:181], v[194:197], v[118:121]
	v_mfma_f32_16x16x32_bf16 v[114:117], v[186:189], v[194:197], v[114:117]
	v_mfma_f32_16x16x32_bf16 v[102:105], v[178:181], v[202:205], v[102:105]
	v_mfma_f32_16x16x32_bf16 v[98:101], v[186:189], v[202:205], v[98:101]
	v_mfma_f32_16x16x32_bf16 v[86:89], v[178:181], v[210:213], v[86:89]
	v_mfma_f32_16x16x32_bf16 v[82:85], v[186:189], v[210:213], v[82:85]
	v_mfma_f32_16x16x32_bf16 v[70:73], v[178:181], v[218:221], v[70:73]
	v_mfma_f32_16x16x32_bf16 v[66:69], v[186:189], v[218:221], v[66:69]
	s_setprio 0
	s_barrier
	s_add_i32 s50, s81, s56
	v_lshl_add_u64 v[222:223], v[222:223], 0, s[42:43]
	s_mov_b32 m0, s50
	ds_read_b128 v[190:193], v159 offset:49152
	ds_read_b128 v[194:197], v159 offset:50176
	ds_read_b128 v[198:201], v159 offset:51200
	ds_read_b128 v[202:205], v159 offset:52224
	ds_read_b128 v[206:209], v159 offset:53248
	ds_read_b128 v[210:213], v159 offset:54272
	ds_read_b128 v[214:217], v159 offset:55296
	ds_read_b128 v[218:221], v159 offset:56320
	global_load_lds_dwordx4 v[222:223], off
	s_add_i32 m0, s50, 0x2000
	s_add_u32 s50, s52, 0x30080
	v_lshl_add_u64 v[222:223], v[224:225], 0, s[42:43]
	s_addc_u32 s51, s53, 0
	s_add_i32 s52, s82, s56
	global_load_lds_dwordx4 v[222:223], off
	v_lshl_add_u64 v[222:223], s[50:51], 0, v[132:133]
	s_mov_b32 m0, s52
	s_nop 0
	global_load_lds_dwordx4 v[222:223], off
	v_lshl_add_u64 v[222:223], s[50:51], 0, v[136:137]
	s_add_i32 m0, s52, 0x2000
	s_nop 0
	global_load_lds_dwordx4 v[222:223], off
	v_lshl_add_u64 v[222:223], v[226:227], 0, s[42:43]
	s_mov_b32 m0, s61
	s_nop 0
	global_load_lds_dwordx4 v[222:223], off
	v_lshl_add_u64 v[222:223], v[228:229], 0, s[42:43]
	s_mov_b32 m0, s62
	s_nop 0
	global_load_lds_dwordx4 v[222:223], off
	s_waitcnt vmcnt(8)
	s_waitcnt lgkmcnt(0)
	s_setprio 1
	s_barrier
	v_mfma_f32_16x16x32_bf16 v[62:65], v[152:155], v[190:193], v[62:65]
	v_mfma_f32_16x16x32_bf16 v[58:61], v[166:169], v[190:193], v[58:61]
	v_mfma_f32_16x16x32_bf16 v[46:49], v[152:155], v[198:201], v[46:49]
	v_mfma_f32_16x16x32_bf16 v[42:45], v[166:169], v[198:201], v[42:45]
	v_mfma_f32_16x16x32_bf16 v[30:33], v[152:155], v[206:209], v[30:33]
	v_mfma_f32_16x16x32_bf16 v[26:29], v[166:169], v[206:209], v[26:29]
	v_mfma_f32_16x16x32_bf16 v[14:17], v[152:155], v[214:217], v[14:17]
	v_mfma_f32_16x16x32_bf16 v[10:13], v[166:169], v[214:217], v[10:13]
	v_mfma_f32_16x16x32_bf16 v[62:65], v[162:165], v[194:197], v[62:65]
	v_mfma_f32_16x16x32_bf16 v[58:61], v[170:173], v[194:197], v[58:61]
	v_mfma_f32_16x16x32_bf16 v[46:49], v[162:165], v[202:205], v[46:49]
	v_mfma_f32_16x16x32_bf16 v[42:45], v[170:173], v[202:205], v[42:45]
	v_mfma_f32_16x16x32_bf16 v[30:33], v[162:165], v[210:213], v[30:33]
	v_mfma_f32_16x16x32_bf16 v[26:29], v[170:173], v[210:213], v[26:29]
	v_mfma_f32_16x16x32_bf16 v[14:17], v[162:165], v[218:221], v[14:17]
	v_mfma_f32_16x16x32_bf16 v[10:13], v[170:173], v[218:221], v[10:13]
	s_setprio 0
	s_setprio 1
	v_mfma_f32_16x16x32_bf16 v[54:57], v[174:177], v[190:193], v[54:57]
	v_mfma_f32_16x16x32_bf16 v[50:53], v[182:185], v[190:193], v[50:53]
	v_mfma_f32_16x16x32_bf16 v[38:41], v[174:177], v[198:201], v[38:41]
	v_mfma_f32_16x16x32_bf16 v[34:37], v[182:185], v[198:201], v[34:37]
	v_mfma_f32_16x16x32_bf16 v[22:25], v[174:177], v[206:209], v[22:25]
	v_mfma_f32_16x16x32_bf16 v[18:21], v[182:185], v[206:209], v[18:21]
	v_mfma_f32_16x16x32_bf16 v[6:9], v[174:177], v[214:217], v[6:9]
	v_mfma_f32_16x16x32_bf16 v[2:5], v[182:185], v[214:217], v[2:5]
	v_mfma_f32_16x16x32_bf16 v[54:57], v[178:181], v[194:197], v[54:57]
	v_mfma_f32_16x16x32_bf16 v[50:53], v[186:189], v[194:197], v[50:53]
	v_mfma_f32_16x16x32_bf16 v[38:41], v[178:181], v[202:205], v[38:41]
	v_mfma_f32_16x16x32_bf16 v[34:37], v[186:189], v[202:205], v[34:37]
	v_mfma_f32_16x16x32_bf16 v[22:25], v[178:181], v[210:213], v[22:25]
	v_mfma_f32_16x16x32_bf16 v[18:21], v[186:189], v[210:213], v[18:21]
	v_mfma_f32_16x16x32_bf16 v[6:9], v[178:181], v[218:221], v[6:9]
	v_mfma_f32_16x16x32_bf16 v[2:5], v[186:189], v[218:221], v[2:5]
	s_setprio 0
	s_barrier
	s_add_i32 s80, s80, 2
	s_add_u32 s10, s10, 0x100
	s_addc_u32 s79, s79, 0
	s_cmp_gt_u32 s80, 9
	s_mov_b64 s[50:51], s[6:7]
	s_cbranch_scc0 .LBB0_1486
	s_branch .Lz_post_p11

.LBB0_1908:
	s_add_u32 s69, s46, 0x100
	s_addc_u32 s70, s47, 0
	s_mov_b32 s71, -2
	s_waitcnt lgkmcnt(0)
	s_waitcnt vmcnt(0)
	ds_read_b128 v[114:117], v225
	ds_read_b128 v[126:129], v225 offset:1024
	ds_read_b128 v[138:141], v225 offset:2048
	ds_read_b128 v[142:145], v225 offset:3072
	ds_read_b128 v[146:149], v226
	ds_read_b128 v[150:153], v226 offset:1024
	ds_read_b128 v[154:157], v226 offset:2048
	ds_read_b128 v[158:161], v226 offset:3072
	s_add_u32 s46, s44, 0x100
	s_addc_u32 s47, s45, 0
	s_cmp_eq_u32 s71, 40
	s_cselect_b32 s51, s9, s47
	s_cselect_b32 s50, s8, s46
	s_cselect_b32 s49, s43, s70
	s_cselect_b32 s48, s42, s69
	v_lshl_add_u64 v[214:215], s[44:45], 0, v[198:199]
	s_add_i32 m0, s53, 0xc000
	ds_read_b128 v[162:165], v227
	ds_read_b128 v[166:169], v227 offset:1024
	ds_read_b128 v[170:173], v227 offset:2048
	ds_read_b128 v[174:177], v227 offset:3072
	ds_read_b128 v[178:181], v227 offset:4096
	ds_read_b128 v[182:185], v227 offset:5120
	ds_read_b128 v[206:209], v227 offset:6144
	ds_read_b128 v[210:213], v227 offset:7168
	global_load_lds_dwordx4 v[214:215], off
	v_lshl_add_u64 v[214:215], s[44:45], 0, v[200:201]
	s_add_i32 m0, s53, 0xe000
	s_nop 0
	global_load_lds_dwordx4 v[214:215], off
	s_waitcnt vmcnt(8)
	s_waitcnt lgkmcnt(0)
	s_setprio 1
	s_barrier
	v_mfma_f32_16x16x32_bf16 v[134:137], v[114:117], v[162:165], 0
	v_mfma_f32_16x16x32_bf16 v[130:133], v[138:141], v[162:165], 0
	v_mfma_f32_16x16x32_bf16 v[110:113], v[114:117], v[170:173], 0
	v_mfma_f32_16x16x32_bf16 v[106:109], v[138:141], v[170:173], 0
	v_mfma_f32_16x16x32_bf16 v[94:97], v[114:117], v[178:181], 0
	v_mfma_f32_16x16x32_bf16 v[90:93], v[138:141], v[178:181], 0
	v_mfma_f32_16x16x32_bf16 v[78:81], v[114:117], v[206:209], 0
	v_mfma_f32_16x16x32_bf16 v[74:77], v[138:141], v[206:209], 0
	v_mfma_f32_16x16x32_bf16 v[134:137], v[126:129], v[166:169], v[134:137]
	v_mfma_f32_16x16x32_bf16 v[130:133], v[142:145], v[166:169], v[130:133]
	v_mfma_f32_16x16x32_bf16 v[110:113], v[126:129], v[174:177], v[110:113]
	v_mfma_f32_16x16x32_bf16 v[106:109], v[142:145], v[174:177], v[106:109]
	v_mfma_f32_16x16x32_bf16 v[94:97], v[126:129], v[182:185], v[94:97]
	v_mfma_f32_16x16x32_bf16 v[90:93], v[142:145], v[182:185], v[90:93]
	v_mfma_f32_16x16x32_bf16 v[78:81], v[126:129], v[210:213], v[78:81]
	v_mfma_f32_16x16x32_bf16 v[74:77], v[142:145], v[210:213], v[74:77]
	s_setprio 0
	s_setprio 1
	v_mfma_f32_16x16x32_bf16 v[122:125], v[146:149], v[162:165], 0
	v_mfma_f32_16x16x32_bf16 v[118:121], v[154:157], v[162:165], 0
	v_mfma_f32_16x16x32_bf16 v[102:105], v[146:149], v[170:173], 0
	v_mfma_f32_16x16x32_bf16 v[98:101], v[154:157], v[170:173], 0
	v_mfma_f32_16x16x32_bf16 v[86:89], v[146:149], v[178:181], 0
	v_mfma_f32_16x16x32_bf16 v[82:85], v[154:157], v[178:181], 0
	v_mfma_f32_16x16x32_bf16 v[70:73], v[146:149], v[206:209], 0
	v_mfma_f32_16x16x32_bf16 v[66:69], v[154:157], v[206:209], 0
	v_mfma_f32_16x16x32_bf16 v[122:125], v[150:153], v[166:169], v[122:125]
	v_mfma_f32_16x16x32_bf16 v[118:121], v[158:161], v[166:169], v[118:121]
	v_mfma_f32_16x16x32_bf16 v[102:105], v[150:153], v[174:177], v[102:105]
	v_mfma_f32_16x16x32_bf16 v[98:101], v[158:161], v[174:177], v[98:101]
	v_mfma_f32_16x16x32_bf16 v[86:89], v[150:153], v[182:185], v[86:89]
	v_mfma_f32_16x16x32_bf16 v[82:85], v[158:161], v[182:185], v[82:85]
	v_mfma_f32_16x16x32_bf16 v[70:73], v[150:153], v[210:213], v[70:73]
	v_mfma_f32_16x16x32_bf16 v[66:69], v[158:161], v[210:213], v[66:69]
	s_setprio 0
	s_barrier
	s_add_i32 s44, s63, s52
	v_lshl_add_u64 v[214:215], s[48:49], 0, v[188:189]
	s_mov_b32 m0, s44
	ds_read_b128 v[162:165], v227 offset:16384
	ds_read_b128 v[166:169], v227 offset:17408
	ds_read_b128 v[170:173], v227 offset:18432
	ds_read_b128 v[174:177], v227 offset:19456
	ds_read_b128 v[178:181], v227 offset:20480
	ds_read_b128 v[182:185], v227 offset:21504
	ds_read_b128 v[206:209], v227 offset:22528
	ds_read_b128 v[210:213], v227 offset:23552
	global_load_lds_dwordx4 v[214:215], off
	s_add_i32 m0, s44, 0x2000
	s_add_u32 s44, s48, 0xb0000
	v_lshl_add_u64 v[216:217], s[48:49], 0, v[192:193]
	s_addc_u32 s45, s49, 0
	s_add_i32 s72, s64, s52
	global_load_lds_dwordx4 v[216:217], off
	v_lshl_add_u64 v[218:219], s[44:45], 0, v[188:189]
	s_mov_b32 m0, s72
	v_lshl_add_u64 v[220:221], s[50:51], 0, v[190:191]
	global_load_lds_dwordx4 v[218:219], off
	v_lshl_add_u64 v[218:219], s[44:45], 0, v[192:193]
	s_add_i32 m0, s72, 0x2000
	s_nop 0
	global_load_lds_dwordx4 v[218:219], off
	v_lshl_add_u64 v[218:219], s[50:51], 0, v[186:187]
	s_mov_b32 m0, s53
	s_nop 0
	global_load_lds_dwordx4 v[218:219], off
	s_mov_b32 m0, s54
	s_nop 0
	global_load_lds_dwordx4 v[220:221], off
	s_waitcnt vmcnt(8)
	s_waitcnt lgkmcnt(0)
	s_setprio 1
	s_barrier
	v_mfma_f32_16x16x32_bf16 v[62:65], v[114:117], v[162:165], 0
	v_mfma_f32_16x16x32_bf16 v[58:61], v[138:141], v[162:165], 0
	v_mfma_f32_16x16x32_bf16 v[46:49], v[114:117], v[170:173], 0
	v_mfma_f32_16x16x32_bf16 v[42:45], v[138:141], v[170:173], 0
	v_mfma_f32_16x16x32_bf16 v[30:33], v[114:117], v[178:181], 0
	v_mfma_f32_16x16x32_bf16 v[26:29], v[138:141], v[178:181], 0
	v_mfma_f32_16x16x32_bf16 v[14:17], v[114:117], v[206:209], 0
	v_mfma_f32_16x16x32_bf16 v[10:13], v[138:141], v[206:209], 0
	v_mfma_f32_16x16x32_bf16 v[62:65], v[126:129], v[166:169], v[62:65]
	v_mfma_f32_16x16x32_bf16 v[58:61], v[142:145], v[166:169], v[58:61]
	v_mfma_f32_16x16x32_bf16 v[46:49], v[126:129], v[174:177], v[46:49]
	v_mfma_f32_16x16x32_bf16 v[42:45], v[142:145], v[174:177], v[42:45]
	v_mfma_f32_16x16x32_bf16 v[30:33], v[126:129], v[182:185], v[30:33]
	v_mfma_f32_16x16x32_bf16 v[26:29], v[142:145], v[182:185], v[26:29]
	v_mfma_f32_16x16x32_bf16 v[14:17], v[126:129], v[210:213], v[14:17]
	v_mfma_f32_16x16x32_bf16 v[10:13], v[142:145], v[210:213], v[10:13]
	s_setprio 0
	s_setprio 1
	v_mfma_f32_16x16x32_bf16 v[54:57], v[146:149], v[162:165], 0
	v_mfma_f32_16x16x32_bf16 v[50:53], v[154:157], v[162:165], 0
	v_mfma_f32_16x16x32_bf16 v[38:41], v[146:149], v[170:173], 0
	v_mfma_f32_16x16x32_bf16 v[34:37], v[154:157], v[170:173], 0
	v_mfma_f32_16x16x32_bf16 v[22:25], v[146:149], v[178:181], 0
	v_mfma_f32_16x16x32_bf16 v[18:21], v[154:157], v[178:181], 0
	v_mfma_f32_16x16x32_bf16 v[6:9], v[146:149], v[206:209], 0
	v_mfma_f32_16x16x32_bf16 v[2:5], v[154:157], v[206:209], 0
	v_mfma_f32_16x16x32_bf16 v[54:57], v[150:153], v[166:169], v[54:57]
	v_mfma_f32_16x16x32_bf16 v[50:53], v[158:161], v[166:169], v[50:53]
	v_mfma_f32_16x16x32_bf16 v[38:41], v[150:153], v[174:177], v[38:41]
	v_mfma_f32_16x16x32_bf16 v[34:37], v[158:161], v[174:177], v[34:37]
	v_mfma_f32_16x16x32_bf16 v[22:25], v[150:153], v[182:185], v[22:25]
	v_mfma_f32_16x16x32_bf16 v[18:21], v[158:161], v[182:185], v[18:21]
	v_mfma_f32_16x16x32_bf16 v[6:9], v[150:153], v[210:213], v[6:9]
	v_mfma_f32_16x16x32_bf16 v[2:5], v[158:161], v[210:213], v[2:5]
	s_setprio 0
	s_barrier
	s_add_i32 s72, 0, 0x18000
	s_add_i32 s73, 0, 0x1c000
	v_add_u32_e32 v142, s72, v224
	v_add_u32_e32 v158, s73, v224
	ds_read_b128 v[114:117], v142
	ds_read_b128 v[126:129], v142 offset:1024
	ds_read_b128 v[138:141], v142 offset:2048
	ds_read_b128 v[142:145], v142 offset:3072
	ds_read_b128 v[146:149], v158
	ds_read_b128 v[150:153], v158 offset:1024
	ds_read_b128 v[154:157], v158 offset:2048
	ds_read_b128 v[158:161], v158 offset:3072
	s_add_u32 s44, s50, 0xb0000
	s_addc_u32 s45, s51, 0
	s_mov_b32 m0, s55
	v_lshl_add_u64 v[222:223], s[44:45], 0, v[186:187]
	ds_read_b128 v[162:165], v227 offset:32768
	ds_read_b128 v[166:169], v227 offset:33792
	ds_read_b128 v[170:173], v227 offset:34816
	ds_read_b128 v[174:177], v227 offset:35840
	ds_read_b128 v[178:181], v227 offset:36864
	ds_read_b128 v[182:185], v227 offset:37888
	ds_read_b128 v[206:209], v227 offset:38912
	ds_read_b128 v[210:213], v227 offset:39936
	global_load_lds_dwordx4 v[222:223], off
	v_lshl_add_u64 v[222:223], s[44:45], 0, v[190:191]
	s_mov_b32 m0, s56
	s_nop 0
	global_load_lds_dwordx4 v[222:223], off
	s_waitcnt vmcnt(8)
	s_waitcnt lgkmcnt(0)
	s_setprio 1
	s_barrier
	v_mfma_f32_16x16x32_bf16 v[134:137], v[114:117], v[162:165], v[134:137]
	v_mfma_f32_16x16x32_bf16 v[130:133], v[138:141], v[162:165], v[130:133]
	v_mfma_f32_16x16x32_bf16 v[110:113], v[114:117], v[170:173], v[110:113]
	v_mfma_f32_16x16x32_bf16 v[106:109], v[138:141], v[170:173], v[106:109]
	v_mfma_f32_16x16x32_bf16 v[94:97], v[114:117], v[178:181], v[94:97]
	v_mfma_f32_16x16x32_bf16 v[90:93], v[138:141], v[178:181], v[90:93]
	v_mfma_f32_16x16x32_bf16 v[78:81], v[114:117], v[206:209], v[78:81]
	v_mfma_f32_16x16x32_bf16 v[74:77], v[138:141], v[206:209], v[74:77]
	v_mfma_f32_16x16x32_bf16 v[134:137], v[126:129], v[166:169], v[134:137]
	v_mfma_f32_16x16x32_bf16 v[130:133], v[142:145], v[166:169], v[130:133]
	v_mfma_f32_16x16x32_bf16 v[110:113], v[126:129], v[174:177], v[110:113]
	v_mfma_f32_16x16x32_bf16 v[106:109], v[142:145], v[174:177], v[106:109]
	v_mfma_f32_16x16x32_bf16 v[94:97], v[126:129], v[182:185], v[94:97]
	v_mfma_f32_16x16x32_bf16 v[90:93], v[142:145], v[182:185], v[90:93]
	v_mfma_f32_16x16x32_bf16 v[78:81], v[126:129], v[210:213], v[78:81]
	v_mfma_f32_16x16x32_bf16 v[74:77], v[142:145], v[210:213], v[74:77]
	s_setprio 0
	s_setprio 1
	v_mfma_f32_16x16x32_bf16 v[122:125], v[146:149], v[162:165], v[122:125]
	v_mfma_f32_16x16x32_bf16 v[118:121], v[154:157], v[162:165], v[118:121]
	v_mfma_f32_16x16x32_bf16 v[102:105], v[146:149], v[170:173], v[102:105]
	v_mfma_f32_16x16x32_bf16 v[98:101], v[154:157], v[170:173], v[98:101]
	v_mfma_f32_16x16x32_bf16 v[86:89], v[146:149], v[178:181], v[86:89]
	v_mfma_f32_16x16x32_bf16 v[82:85], v[154:157], v[178:181], v[82:85]
	v_mfma_f32_16x16x32_bf16 v[70:73], v[146:149], v[206:209], v[70:73]
	v_mfma_f32_16x16x32_bf16 v[66:69], v[154:157], v[206:209], v[66:69]
	v_mfma_f32_16x16x32_bf16 v[122:125], v[150:153], v[166:169], v[122:125]
	v_mfma_f32_16x16x32_bf16 v[118:121], v[158:161], v[166:169], v[118:121]
	v_mfma_f32_16x16x32_bf16 v[102:105], v[150:153], v[174:177], v[102:105]
	v_mfma_f32_16x16x32_bf16 v[98:101], v[158:161], v[174:177], v[98:101]
	v_mfma_f32_16x16x32_bf16 v[86:89], v[150:153], v[182:185], v[86:89]
	v_mfma_f32_16x16x32_bf16 v[82:85], v[158:161], v[182:185], v[82:85]
	v_mfma_f32_16x16x32_bf16 v[70:73], v[150:153], v[210:213], v[70:73]
	v_mfma_f32_16x16x32_bf16 v[66:69], v[158:161], v[210:213], v[66:69]
	s_setprio 0
	s_barrier
	s_add_i32 s44, s72, s52
	v_lshl_add_u64 v[214:215], v[214:215], 0, s[24:25]
	s_mov_b32 m0, s44
	ds_read_b128 v[162:165], v227 offset:49152
	ds_read_b128 v[166:169], v227 offset:50176
	ds_read_b128 v[170:173], v227 offset:51200
	ds_read_b128 v[174:177], v227 offset:52224
	ds_read_b128 v[178:181], v227 offset:53248
	ds_read_b128 v[182:185], v227 offset:54272
	ds_read_b128 v[206:209], v227 offset:55296
	ds_read_b128 v[210:213], v227 offset:56320
	global_load_lds_dwordx4 v[214:215], off
	s_add_i32 m0, s44, 0x2000
	s_add_u32 s44, s48, 0xb0080
	v_lshl_add_u64 v[214:215], v[216:217], 0, s[24:25]
	s_addc_u32 s45, s49, 0
	s_add_i32 s48, s73, s52
	global_load_lds_dwordx4 v[214:215], off
	v_lshl_add_u64 v[214:215], s[44:45], 0, v[188:189]
	s_mov_b32 m0, s48
	s_nop 0
	global_load_lds_dwordx4 v[214:215], off
	v_lshl_add_u64 v[214:215], s[44:45], 0, v[192:193]
	s_add_i32 m0, s48, 0x2000
	s_nop 0
	global_load_lds_dwordx4 v[214:215], off
	v_lshl_add_u64 v[214:215], v[218:219], 0, s[24:25]
	s_mov_b32 m0, s58
	s_nop 0
	global_load_lds_dwordx4 v[214:215], off
	v_lshl_add_u64 v[214:215], v[220:221], 0, s[24:25]
	s_mov_b32 m0, s59
	s_nop 0
	global_load_lds_dwordx4 v[214:215], off
	s_waitcnt vmcnt(8)
	s_waitcnt lgkmcnt(0)
	s_setprio 1
	s_barrier
	v_mfma_f32_16x16x32_bf16 v[62:65], v[114:117], v[162:165], v[62:65]
	v_mfma_f32_16x16x32_bf16 v[58:61], v[138:141], v[162:165], v[58:61]
	v_mfma_f32_16x16x32_bf16 v[46:49], v[114:117], v[170:173], v[46:49]
	v_mfma_f32_16x16x32_bf16 v[42:45], v[138:141], v[170:173], v[42:45]
	v_mfma_f32_16x16x32_bf16 v[30:33], v[114:117], v[178:181], v[30:33]
	v_mfma_f32_16x16x32_bf16 v[26:29], v[138:141], v[178:181], v[26:29]
	v_mfma_f32_16x16x32_bf16 v[14:17], v[114:117], v[206:209], v[14:17]
	v_mfma_f32_16x16x32_bf16 v[10:13], v[138:141], v[206:209], v[10:13]
	v_mfma_f32_16x16x32_bf16 v[62:65], v[126:129], v[166:169], v[62:65]
	v_mfma_f32_16x16x32_bf16 v[58:61], v[142:145], v[166:169], v[58:61]
	v_mfma_f32_16x16x32_bf16 v[46:49], v[126:129], v[174:177], v[46:49]
	v_mfma_f32_16x16x32_bf16 v[42:45], v[142:145], v[174:177], v[42:45]
	v_mfma_f32_16x16x32_bf16 v[30:33], v[126:129], v[182:185], v[30:33]
	v_mfma_f32_16x16x32_bf16 v[26:29], v[142:145], v[182:185], v[26:29]
	v_mfma_f32_16x16x32_bf16 v[14:17], v[126:129], v[210:213], v[14:17]
	v_mfma_f32_16x16x32_bf16 v[10:13], v[142:145], v[210:213], v[10:13]
	s_setprio 0
	s_setprio 1
	v_mfma_f32_16x16x32_bf16 v[54:57], v[146:149], v[162:165], v[54:57]
	v_mfma_f32_16x16x32_bf16 v[50:53], v[154:157], v[162:165], v[50:53]
	v_mfma_f32_16x16x32_bf16 v[38:41], v[146:149], v[170:173], v[38:41]
	v_mfma_f32_16x16x32_bf16 v[34:37], v[154:157], v[170:173], v[34:37]
	v_mfma_f32_16x16x32_bf16 v[22:25], v[146:149], v[178:181], v[22:25]
	v_mfma_f32_16x16x32_bf16 v[18:21], v[154:157], v[178:181], v[18:21]
	v_mfma_f32_16x16x32_bf16 v[6:9], v[146:149], v[206:209], v[6:9]
	v_mfma_f32_16x16x32_bf16 v[2:5], v[154:157], v[206:209], v[2:5]
	v_mfma_f32_16x16x32_bf16 v[54:57], v[150:153], v[166:169], v[54:57]
	v_mfma_f32_16x16x32_bf16 v[50:53], v[158:161], v[166:169], v[50:53]
	v_mfma_f32_16x16x32_bf16 v[38:41], v[150:153], v[174:177], v[38:41]
	v_mfma_f32_16x16x32_bf16 v[34:37], v[158:161], v[174:177], v[34:37]
	v_mfma_f32_16x16x32_bf16 v[22:25], v[150:153], v[182:185], v[22:25]
	v_mfma_f32_16x16x32_bf16 v[18:21], v[158:161], v[182:185], v[18:21]
	v_mfma_f32_16x16x32_bf16 v[6:9], v[150:153], v[210:213], v[6:9]
	v_mfma_f32_16x16x32_bf16 v[2:5], v[158:161], v[210:213], v[2:5]
	s_setprio 0
	s_barrier
	s_add_i32 s71, s71, 2
	s_add_u32 s69, s69, 0x100
	s_addc_u32 s70, s70, 0
	s_cmp_gt_u32 s71, 41
	s_mov_b64 s[44:45], s[46:47]
	s_cbranch_scc0 .LBB0_1909
	s_branch .Lz_post_p15

.Lz_post_p15:
	v_lshl_add_u32 v222, s67, 8, v195
	s_lshl_b32 s44, s68, 8
	s_ashr_i32 s45, s44, 31
	v_ashrrev_i32_e32 v223, 31, v222
	v_lshl_add_u64 v[114:115], s[44:45], 1, v[196:197]
	v_lshlrev_b64 v[116:117], 11, v[222:223]
	v_lshl_add_u64 v[116:117], v[114:115], 0, v[116:117]
	global_load_dwordx4 v[230:233], v[116:117], off
	global_load_dwordx4 v[234:237], v[116:117], off offset:256
	v_or_b32_e32 v220, 16, v222
	v_or_b32_e32 v218, 32, v222
	v_or_b32_e32 v216, 48, v222
	v_add_u32_e32 v214, 0x80, v222
	v_add_u32_e32 v212, 0x90, v222
	v_add_u32_e32 v210, 0xa0, v222
	v_add_u32_e32 v206, 0xb0, v222
	v_ashrrev_i32_e32 v221, 31, v220
	v_ashrrev_i32_e32 v219, 31, v218
	v_ashrrev_i32_e32 v217, 31, v216
	v_ashrrev_i32_e32 v215, 31, v214
	v_ashrrev_i32_e32 v213, 31, v212
	v_ashrrev_i32_e32 v211, 31, v210
	v_ashrrev_i32_e32 v207, 31, v206
	v_lshlrev_b64 v[116:117], 11, v[220:221]
	v_lshlrev_b64 v[126:127], 11, v[218:219]
	v_lshlrev_b64 v[128:129], 11, v[216:217]
	v_lshlrev_b64 v[138:139], 11, v[214:215]
	v_lshlrev_b64 v[140:141], 11, v[212:213]
	v_lshlrev_b64 v[142:143], 11, v[210:211]
	v_lshlrev_b64 v[144:145], 11, v[206:207]
	v_lshl_add_u64 v[116:117], v[114:115], 0, v[116:117]
	v_lshl_add_u64 v[126:127], v[114:115], 0, v[126:127]
	v_lshl_add_u64 v[128:129], v[114:115], 0, v[128:129]
	v_lshl_add_u64 v[138:139], v[114:115], 0, v[138:139]
	v_lshl_add_u64 v[140:141], v[114:115], 0, v[140:141]
	v_lshl_add_u64 v[208:209], v[114:115], 0, v[142:143]
	v_lshl_add_u64 v[114:115], v[114:115], 0, v[144:145]
	global_load_dwordx4 v[182:185], v[116:117], off
	global_load_dwordx4 v[178:181], v[116:117], off offset:256
	global_load_dwordx4 v[174:177], v[126:127], off
	global_load_dwordx4 v[170:173], v[126:127], off offset:256
	global_load_dwordx4 v[166:169], v[128:129], off
	global_load_dwordx4 v[162:165], v[128:129], off offset:256
	global_load_dwordx4 v[158:161], v[138:139], off
	global_load_dwordx4 v[154:157], v[138:139], off offset:256
	global_load_dwordx4 v[150:153], v[140:141], off
	global_load_dwordx4 v[146:149], v[140:141], off offset:256
	global_load_dwordx4 v[142:145], v[208:209], off
	s_nop 0
	global_load_dwordx4 v[138:141], v[208:209], off offset:256
	global_load_dwordx4 v[126:129], v[114:115], off
	s_nop 0
	global_load_dwordx4 v[114:117], v[114:115], off offset:256
	s_and_b64 vcc, exec, s[26:27]
	s_cbranch_vccz .LBB0_1912
	s_barrier
